# GEMM K-loop heads aligned to 64 B and every MFMA of the K-loops placed on an 8-byte boundary (s_nop pads at the start of the load segments)
# speedup vs baseline: 1.0020x; 1.0020x over previous
; #define PG8_STAGE(bufoff, gbase, voff) do { if constexpr (!pg8_noload<Epi>::value) { _Pragma("unroll") for (int _i = 0; _i < 2; ++_i) \
;         __builtin_amdgcn_global_load_lds((const unsigned*)((const char*)(gbase) + (size_t)_i * pstep + (voff)[0]), (PG8_LAS unsigned*)(lds + (bufoff) + ldsw + _i * 8192), 16, 0, 0); } } while (0)
; #define PG8_LDA(dst, b, h) do { _Pragma("unroll") for (int m = 0; m < 4; ++m) _Pragma("unroll") for (int k = 0; k < 2; ++k) dst[m][k] = *(const PG8_LAS bf16x8*)(lds + PG8_SA(b, h) + aoff + m * 2048 + k * 1024); } while (0)
; #define PG8_LDB(dst, b, h) do { _Pragma("unroll") for (int n = 0; n < 2; ++n) _Pragma("unroll") for (int k = 0; k < 2; ++k) dst[n][k] = *(const PG8_LAS bf16x8*)(lds + PG8_SB(b, h) + boff + n * 2048 + k * 1024); } while (0)
; #define PG8_WAIT_V(n) asm volatile("s_waitcnt vmcnt(" #n ")" ::: "memory")
; #define PG8_WAIT_L(n) asm volatile("s_waitcnt lgkmcnt(" #n ")" ::: "memory")
; #define PG8_BAR __builtin_amdgcn_s_barrier()
; #define PG8_SCHED __builtin_amdgcn_sched_barrier(0)
; template <class Epi, class Sched, bool ALIGN_EPI = false, bool SP2 = false, bool ABLK = false>
; __device__ __forceinline__ void gemm_phase(PG8_LAS unsigned char* lds, const Gemm g, const Sched& S, const Epi& E) {
;     ...
;         for (int t = 0; t < nt; t += 2) {
;             const bool last = (t == nt - 2);
;             const char* a1 = cA + (size_t)(t + 1) * kstep;
;             const char* a2 = last ? nA : cA + (size_t)(t + 2) * kstep; const char* b2 = last ? nB : cB + (size_t)(t + 2) * kstepB;
;             const char* a3 = a2 + kstep; const char* b3 = b2 + kstepB;
;             if (last && has_next) S.a_ready(nxt);
;             if constexpr (SP2) {
;             PG8_LDB(B0, 0, 0); PG8_LDB(B1, 0, 1); PG8_SCHED; PG8_LDA(At, 0, 0); PG8_STAGE(PG8_SA(1, 1), a1 + hstep, voffA);
;             PG8_WAIT_V(8); PG8_WAIT_L(0); PG8_BAR; PG8_MMA(0, 0, At, B0); PG8_MMA(0, 1, At, B1); PG8_BAR; PG8_SCHED;
;     ...
; #pragma unroll
;         for (int a = 0; a < 2; ++a)
; #pragma unroll
;             for (int b = 0; b < 2; ++b)
; #pragma unroll
;                 for (int m = 0; m < 4; ++m)
; #pragma unroll
;                     for (int n = 0; n < 2; ++n) acc[a][b][m][n] = (f32x4){0.f, 0.f, 0.f, 0.f};
;         cur = nxt; cA = nA; cB = nB; ++ui; nt = cur.nt;
.LBB0_113:
	s_ashr_i32 s3, s2, 31
	s_lshl_b64 s[68:69], s[2:3], 20
	s_add_u32 s88, s13, s68
	s_addc_u32 s89, s25, s69
	s_and_b64 s[68:69], s[10:11], exec
	s_cselect_b32 s3, s89, s71
	s_cselect_b32 s7, s88, s70
	s_ashr_i32 s21, s20, 31
	s_lshl_b64 s[68:69], s[20:21], 20
	s_add_u32 s68, s27, s68
	s_addc_u32 s69, s33, s69
	s_and_b64 s[72:73], s[10:11], exec
	s_cselect_b32 s21, s69, s17
	s_cselect_b32 s72, s68, s16
	s_add_u32 vcc_lo, s70, 0x80800
	s_addc_u32 vcc_hi, s71, 0
	s_add_u32 s16, s16, 0x1000
	v_mov_b32_e32 v2, 0
	s_addc_u32 s17, s17, 0
	s_mov_b32 s70, -2
	v_mov_b32_e32 v3, v2
	s_waitcnt lgkmcnt(0)
	v_mov_b32_e32 v4, v2
	v_mov_b32_e32 v5, v2
	v_mov_b32_e32 v6, v2
	v_mov_b32_e32 v7, v2
	v_mov_b32_e32 v8, v2
	v_mov_b32_e32 v9, v2
	v_mov_b32_e32 v18, v2
	v_mov_b32_e32 v19, v2
	v_mov_b32_e32 v20, v2
	v_mov_b32_e32 v21, v2
	v_mov_b32_e32 v22, v2
	v_mov_b32_e32 v23, v2
	v_mov_b32_e32 v24, v2
	v_mov_b32_e32 v25, v2
	v_mov_b32_e32 v34, v2
	v_mov_b32_e32 v35, v2
	v_mov_b32_e32 v36, v2
	v_mov_b32_e32 v37, v2
	v_mov_b32_e32 v38, v2
	v_mov_b32_e32 v39, v2
	v_mov_b32_e32 v40, v2
	v_mov_b32_e32 v41, v2
	v_mov_b32_e32 v50, v2
	v_mov_b32_e32 v51, v2
	v_mov_b32_e32 v52, v2
	v_mov_b32_e32 v53, v2
	v_mov_b32_e32 v54, v2
	v_mov_b32_e32 v55, v2
	v_mov_b32_e32 v56, v2
	v_mov_b32_e32 v57, v2
	v_mov_b32_e32 v10, v2
	v_mov_b32_e32 v11, v2
	v_mov_b32_e32 v12, v2
	v_mov_b32_e32 v13, v2
	v_mov_b32_e32 v14, v2
	v_mov_b32_e32 v15, v2
	v_mov_b32_e32 v16, v2
	v_mov_b32_e32 v17, v2
	v_mov_b32_e32 v26, v2
	v_mov_b32_e32 v27, v2
	v_mov_b32_e32 v28, v2
	v_mov_b32_e32 v29, v2
	v_mov_b32_e32 v30, v2
	v_mov_b32_e32 v31, v2
	v_mov_b32_e32 v32, v2
	v_mov_b32_e32 v33, v2
	v_mov_b32_e32 v42, v2
	v_mov_b32_e32 v43, v2
	v_mov_b32_e32 v44, v2
	v_mov_b32_e32 v45, v2
	v_mov_b32_e32 v46, v2
	v_mov_b32_e32 v47, v2
	v_mov_b32_e32 v48, v2
	v_mov_b32_e32 v49, v2
	v_mov_b32_e32 v58, v2
	v_mov_b32_e32 v59, v2
	v_mov_b32_e32 v60, v2
	v_mov_b32_e32 v61, v2
	v_mov_b32_e32 v62, v2
	v_mov_b32_e32 v63, v2
	v_mov_b32_e32 v64, v2
	v_mov_b32_e32 v65, v2
	v_mov_b32_e32 v66, v2
	v_mov_b32_e32 v67, v2
	v_mov_b32_e32 v68, v2
	v_mov_b32_e32 v69, v2
	v_mov_b32_e32 v70, v2
	v_mov_b32_e32 v71, v2
	v_mov_b32_e32 v72, v2
	v_mov_b32_e32 v73, v2
	v_mov_b32_e32 v82, v2
	v_mov_b32_e32 v83, v2
	v_mov_b32_e32 v84, v2
	v_mov_b32_e32 v85, v2
	v_mov_b32_e32 v86, v2
	v_mov_b32_e32 v87, v2
	v_mov_b32_e32 v88, v2
	v_mov_b32_e32 v89, v2
	v_mov_b32_e32 v98, v2
	v_mov_b32_e32 v99, v2
	v_mov_b32_e32 v100, v2
	v_mov_b32_e32 v101, v2
	v_mov_b32_e32 v102, v2
	v_mov_b32_e32 v103, v2
	v_mov_b32_e32 v104, v2
	v_mov_b32_e32 v105, v2
	v_mov_b32_e32 v114, v2
	v_mov_b32_e32 v115, v2
	v_mov_b32_e32 v116, v2
	v_mov_b32_e32 v117, v2
	v_mov_b32_e32 v118, v2
	v_mov_b32_e32 v119, v2
	v_mov_b32_e32 v120, v2
	v_mov_b32_e32 v121, v2
	v_mov_b32_e32 v74, v2
	v_mov_b32_e32 v75, v2
	v_mov_b32_e32 v76, v2
	v_mov_b32_e32 v77, v2
	v_mov_b32_e32 v78, v2
	v_mov_b32_e32 v79, v2
	v_mov_b32_e32 v80, v2
	v_mov_b32_e32 v81, v2
	v_mov_b32_e32 v90, v2
	v_mov_b32_e32 v91, v2
	v_mov_b32_e32 v92, v2
	v_mov_b32_e32 v93, v2
	v_mov_b32_e32 v94, v2
	v_mov_b32_e32 v95, v2
	v_mov_b32_e32 v96, v2
	v_mov_b32_e32 v97, v2
	v_mov_b32_e32 v106, v2
	v_mov_b32_e32 v107, v2
	v_mov_b32_e32 v108, v2
	v_mov_b32_e32 v109, v2
	v_mov_b32_e32 v110, v2
	v_mov_b32_e32 v111, v2
	v_mov_b32_e32 v112, v2
	v_mov_b32_e32 v113, v2
	v_mov_b32_e32 v122, v2
	v_mov_b32_e32 v123, v2
	v_mov_b32_e32 v124, v2
	v_mov_b32_e32 v125, v2
	v_mov_b32_e32 v126, v2
	v_mov_b32_e32 v127, v2
	v_mov_b32_e32 v128, v2
	v_mov_b32_e32 v129, v2
	.p2align	6
.LBB0_114:
	ds_read_b128 v[144:147], v168
	ds_read_b128 v[184:187], v168 offset:1024
	ds_read_b128 v[188:191], v168 offset:2048
	ds_read_b128 v[192:195], v168 offset:3072
	ds_read_b128 v[196:199], v169
	ds_read_b128 v[200:203], v169 offset:1024
	ds_read_b128 v[204:207], v169 offset:2048
	ds_read_b128 v[208:211], v169 offset:3072
	s_add_u32 s71, vcc_lo, 0xfff80800
	s_addc_u32 s73, vcc_hi, -1
	s_cmp_eq_u32 s70, 28
	s_cselect_b32 s75, s3, s73
	s_cselect_b32 s74, s7, s71
	s_cselect_b32 s77, s21, s17
	s_cselect_b32 s76, s72, s16
	v_lshl_add_u64 v[244:245], vcc, 0, v[136:137]
	s_add_i32 m0, s53, 0xc000
	ds_read_b128 v[212:215], v170
	ds_read_b128 v[216:219], v170 offset:1024
	ds_read_b128 v[220:223], v170 offset:2048
	ds_read_b128 v[224:227], v170 offset:3072
	ds_read_b128 v[228:231], v170 offset:4096
	ds_read_b128 v[232:235], v170 offset:5120
	ds_read_b128 v[236:239], v170 offset:6144
	ds_read_b128 v[240:243], v170 offset:7168
	global_load_lds_dwordx4 v[244:245], off
	v_lshl_add_u64 v[244:245], v[244:245], 0, s[0:1]
	s_add_i32 m0, s53, 0xe000
	s_nop 0
	global_load_lds_dwordx4 v[244:245], off
	s_waitcnt vmcnt(8)
	s_waitcnt lgkmcnt(0)
	s_barrier
; #define PG8_STAGE(bufoff, gbase, voff) do { if constexpr (!pg8_noload<Epi>::value) { _Pragma("unroll") for (int _i = 0; _i < 2; ++_i) \
;         __builtin_amdgcn_global_load_lds((const unsigned*)((const char*)(gbase) + (size_t)_i * pstep + (voff)[0]), (PG8_LAS unsigned*)(lds + (bufoff) + ldsw + _i * 8192), 16, 0, 0); } } while (0)
; #define PG8_LDA(dst, b, h) do { _Pragma("unroll") for (int m = 0; m < 4; ++m) _Pragma("unroll") for (int k = 0; k < 2; ++k) dst[m][k] = *(const PG8_LAS bf16x8*)(lds + PG8_SA(b, h) + aoff + m * 2048 + k * 1024); } while (0)
; #define PG8_MMA(ai, bj, At, Bt) do { __builtin_amdgcn_s_setprio(1); _Pragma("unroll") for (int m = 0; m < 4; ++m) _Pragma("unroll") for (int n = 0; n < 2; ++n) _Pragma("unroll") for (int k = 0; k < 2; ++k) \
;         acc[ai][bj][m][n] = __builtin_amdgcn_mfma_f32_16x16x32_bf16(Bt[n][k], At[m][k], acc[ai][bj][m][n], 0, 0, 0); __builtin_amdgcn_s_setprio(0); } while (0)
; #define PG8_WAIT_V(n) asm volatile("s_waitcnt vmcnt(" #n ")" ::: "memory")
; #define PG8_WAIT_L(n) asm volatile("s_waitcnt lgkmcnt(" #n ")" ::: "memory")
; #define PG8_BAR __builtin_amdgcn_s_barrier()
; #define PG8_SCHED __builtin_amdgcn_sched_barrier(0)
; template <class Epi, class Sched, bool ALIGN_EPI = false, bool SP2 = false, bool ABLK = false>
; __device__ __forceinline__ void gemm_phase(PG8_LAS unsigned char* lds, const Gemm g, const Sched& S, const Epi& E) {
;     ...
;             PG8_WAIT_V(8); PG8_WAIT_L(0); PG8_BAR; PG8_MMA(0, 0, At, B0); PG8_MMA(0, 1, At, B1); PG8_BAR; PG8_SCHED;
;             PG8_LDA(At, 0, 1); PG8_STAGE(PG8_SB(0, 0), b2, voffB); PG8_STAGE(PG8_SB(0, 1), b2 + hstep, voffB); PG8_STAGE(PG8_SA(0, 0), a2, voffA);
;             PG8_WAIT_V(8); PG8_WAIT_L(0); PG8_BAR; PG8_MMA(1, 0, At, B0); PG8_MMA(1, 1, At, B1); PG8_BAR; PG8_SCHED;
	s_setprio 1
	s_waitcnt lgkmcnt(0)
	v_mfma_f32_16x16x32_bf16 v[126:129], v[144:147], v[212:215], v[126:129]
	v_mfma_f32_16x16x32_bf16 v[126:129], v[184:187], v[216:219], v[126:129]
	v_mfma_f32_16x16x32_bf16 v[110:113], v[184:187], v[224:227], v[110:113]
	v_mfma_f32_16x16x32_bf16 v[110:113], v[144:147], v[220:223], v[110:113]
	v_mfma_f32_16x16x32_bf16 v[94:97], v[144:147], v[228:231], v[94:97]
	v_mfma_f32_16x16x32_bf16 v[94:97], v[184:187], v[232:235], v[94:97]
	v_mfma_f32_16x16x32_bf16 v[78:81], v[184:187], v[240:243], v[78:81]
	v_mfma_f32_16x16x32_bf16 v[78:81], v[144:147], v[236:239], v[78:81]
	v_mfma_f32_16x16x32_bf16 v[74:77], v[188:191], v[236:239], v[74:77]
	v_mfma_f32_16x16x32_bf16 v[74:77], v[192:195], v[240:243], v[74:77]
	v_mfma_f32_16x16x32_bf16 v[90:93], v[192:195], v[232:235], v[90:93]
	v_mfma_f32_16x16x32_bf16 v[90:93], v[188:191], v[228:231], v[90:93]
	v_mfma_f32_16x16x32_bf16 v[106:109], v[188:191], v[220:223], v[106:109]
	v_mfma_f32_16x16x32_bf16 v[106:109], v[192:195], v[224:227], v[106:109]
	v_mfma_f32_16x16x32_bf16 v[122:125], v[192:195], v[216:219], v[122:125]
	v_mfma_f32_16x16x32_bf16 v[122:125], v[188:191], v[212:215], v[122:125]
	v_mfma_f32_16x16x32_bf16 v[118:121], v[196:199], v[212:215], v[118:121]
	v_mfma_f32_16x16x32_bf16 v[118:121], v[200:203], v[216:219], v[118:121]
	v_mfma_f32_16x16x32_bf16 v[102:105], v[200:203], v[224:227], v[102:105]
	v_mfma_f32_16x16x32_bf16 v[102:105], v[196:199], v[220:223], v[102:105]
	v_mfma_f32_16x16x32_bf16 v[86:89], v[196:199], v[228:231], v[86:89]
	v_mfma_f32_16x16x32_bf16 v[86:89], v[200:203], v[232:235], v[86:89]
	v_mfma_f32_16x16x32_bf16 v[70:73], v[200:203], v[240:243], v[70:73]
	v_mfma_f32_16x16x32_bf16 v[70:73], v[196:199], v[236:239], v[70:73]
	v_mfma_f32_16x16x32_bf16 v[66:69], v[204:207], v[236:239], v[66:69]
	v_mfma_f32_16x16x32_bf16 v[66:69], v[208:211], v[240:243], v[66:69]
	v_mfma_f32_16x16x32_bf16 v[82:85], v[208:211], v[232:235], v[82:85]
	v_mfma_f32_16x16x32_bf16 v[82:85], v[204:207], v[228:231], v[82:85]
	s_barrier
	s_setprio 2
	v_mfma_f32_16x16x32_bf16 v[98:101], v[204:207], v[220:223], v[98:101]
	v_mfma_f32_16x16x32_bf16 v[98:101], v[208:211], v[224:227], v[98:101]
	v_mfma_f32_16x16x32_bf16 v[114:117], v[208:211], v[216:219], v[114:117]
	v_mfma_f32_16x16x32_bf16 v[114:117], v[204:207], v[212:215], v[114:117]
	s_setprio 0
	s_nop 0
	s_add_i32 s71, s64, s52
	v_lshl_add_u64 v[244:245], s[76:77], 0, v[130:131]
	s_mov_b32 m0, s71
	ds_read_b128 v[212:215], v170 offset:16384
	ds_read_b128 v[216:219], v170 offset:17408
	ds_read_b128 v[220:223], v170 offset:18432
	ds_read_b128 v[224:227], v170 offset:19456
	ds_read_b128 v[228:231], v170 offset:20480
	ds_read_b128 v[232:235], v170 offset:21504
	ds_read_b128 v[236:239], v170 offset:22528
	ds_read_b128 v[240:243], v170 offset:23552
	global_load_lds_dwordx4 v[244:245], off
	v_lshl_add_u64 v[246:247], v[244:245], 0, s[0:1]
	s_add_i32 m0, s71, 0x2000
	s_add_i32 s71, s65, s52
	global_load_lds_dwordx4 v[246:247], off
	v_lshl_add_u64 v[246:247], v[244:245], 0, s[14:15]
	s_mov_b32 m0, s71
	s_nop 0
	global_load_lds_dwordx4 v[246:247], off
	v_lshl_add_u64 v[246:247], v[244:245], 0, s[18:19]
	s_add_i32 m0, s71, 0x2000
	s_nop 0
	global_load_lds_dwordx4 v[246:247], off
	v_lshl_add_u64 v[246:247], s[74:75], 0, v[130:131]
	s_mov_b32 m0, s53
	v_lshl_add_u64 v[248:249], v[246:247], 0, s[0:1]
	global_load_lds_dwordx4 v[246:247], off
	s_mov_b32 m0, s54
	s_nop 0
	global_load_lds_dwordx4 v[248:249], off
	s_waitcnt vmcnt(8)
	s_waitcnt lgkmcnt(0)
	s_barrier
	s_setprio 1
	s_waitcnt lgkmcnt(0)
	v_mfma_f32_16x16x32_bf16 v[62:65], v[144:147], v[212:215], v[62:65]
	v_mfma_f32_16x16x32_bf16 v[62:65], v[184:187], v[216:219], v[62:65]
	v_mfma_f32_16x16x32_bf16 v[46:49], v[184:187], v[224:227], v[46:49]
	v_mfma_f32_16x16x32_bf16 v[46:49], v[144:147], v[220:223], v[46:49]
	v_mfma_f32_16x16x32_bf16 v[30:33], v[144:147], v[228:231], v[30:33]
	v_mfma_f32_16x16x32_bf16 v[30:33], v[184:187], v[232:235], v[30:33]
	v_mfma_f32_16x16x32_bf16 v[14:17], v[184:187], v[240:243], v[14:17]
	v_mfma_f32_16x16x32_bf16 v[14:17], v[144:147], v[236:239], v[14:17]
	v_mfma_f32_16x16x32_bf16 v[10:13], v[188:191], v[236:239], v[10:13]
	v_mfma_f32_16x16x32_bf16 v[10:13], v[192:195], v[240:243], v[10:13]
	v_mfma_f32_16x16x32_bf16 v[26:29], v[192:195], v[232:235], v[26:29]
	v_mfma_f32_16x16x32_bf16 v[26:29], v[188:191], v[228:231], v[26:29]
	v_mfma_f32_16x16x32_bf16 v[42:45], v[188:191], v[220:223], v[42:45]
	v_mfma_f32_16x16x32_bf16 v[42:45], v[192:195], v[224:227], v[42:45]
	v_mfma_f32_16x16x32_bf16 v[58:61], v[192:195], v[216:219], v[58:61]
	v_mfma_f32_16x16x32_bf16 v[58:61], v[188:191], v[212:215], v[58:61]
	v_mfma_f32_16x16x32_bf16 v[54:57], v[196:199], v[212:215], v[54:57]
	v_mfma_f32_16x16x32_bf16 v[54:57], v[200:203], v[216:219], v[54:57]
	v_mfma_f32_16x16x32_bf16 v[38:41], v[200:203], v[224:227], v[38:41]
	v_mfma_f32_16x16x32_bf16 v[38:41], v[196:199], v[220:223], v[38:41]
	v_mfma_f32_16x16x32_bf16 v[22:25], v[196:199], v[228:231], v[22:25]
	v_mfma_f32_16x16x32_bf16 v[22:25], v[200:203], v[232:235], v[22:25]
	v_mfma_f32_16x16x32_bf16 v[6:9], v[200:203], v[240:243], v[6:9]
	v_mfma_f32_16x16x32_bf16 v[6:9], v[196:199], v[236:239], v[6:9]
	v_mfma_f32_16x16x32_bf16 v[2:5], v[204:207], v[236:239], v[2:5]
	v_mfma_f32_16x16x32_bf16 v[2:5], v[208:211], v[240:243], v[2:5]
	v_mfma_f32_16x16x32_bf16 v[18:21], v[208:211], v[232:235], v[18:21]
	v_mfma_f32_16x16x32_bf16 v[18:21], v[204:207], v[228:231], v[18:21]
	s_barrier
; #define PG8_STAGE(bufoff, gbase, voff) do { if constexpr (!pg8_noload<Epi>::value) { _Pragma("unroll") for (int _i = 0; _i < 2; ++_i) \
;         __builtin_amdgcn_global_load_lds((const unsigned*)((const char*)(gbase) + (size_t)_i * pstep + (voff)[0]), (PG8_LAS unsigned*)(lds + (bufoff) + ldsw + _i * 8192), 16, 0, 0); } } while (0)
; #define PG8_LDA(dst, b, h) do { _Pragma("unroll") for (int m = 0; m < 4; ++m) _Pragma("unroll") for (int k = 0; k < 2; ++k) dst[m][k] = *(const PG8_LAS bf16x8*)(lds + PG8_SA(b, h) + aoff + m * 2048 + k * 1024); } while (0)
; #define PG8_LDB(dst, b, h) do { _Pragma("unroll") for (int n = 0; n < 2; ++n) _Pragma("unroll") for (int k = 0; k < 2; ++k) dst[n][k] = *(const PG8_LAS bf16x8*)(lds + PG8_SB(b, h) + boff + n * 2048 + k * 1024); } while (0)
; #define PG8_MMA(ai, bj, At, Bt) do { __builtin_amdgcn_s_setprio(1); _Pragma("unroll") for (int m = 0; m < 4; ++m) _Pragma("unroll") for (int n = 0; n < 2; ++n) _Pragma("unroll") for (int k = 0; k < 2; ++k) \
;         acc[ai][bj][m][n] = __builtin_amdgcn_mfma_f32_16x16x32_bf16(Bt[n][k], At[m][k], acc[ai][bj][m][n], 0, 0, 0); __builtin_amdgcn_s_setprio(0); } while (0)
; #define PG8_WAIT_V(n) asm volatile("s_waitcnt vmcnt(" #n ")" ::: "memory")
; #define PG8_WAIT_L(n) asm volatile("s_waitcnt lgkmcnt(" #n ")" ::: "memory")
; #define PG8_BAR __builtin_amdgcn_s_barrier()
; #define PG8_SCHED __builtin_amdgcn_sched_barrier(0)
; template <class Epi, class Sched, bool ALIGN_EPI = false, bool SP2 = false, bool ABLK = false>
; __device__ __forceinline__ void gemm_phase(PG8_LAS unsigned char* lds, const Gemm g, const Sched& S, const Epi& E) {
;     ...
;             PG8_WAIT_V(8); PG8_WAIT_L(0); PG8_BAR; PG8_MMA(1, 0, At, B0); PG8_MMA(1, 1, At, B1); PG8_BAR; PG8_SCHED;
;             PG8_LDB(B0, 1, 0); PG8_LDB(B1, 1, 1); PG8_SCHED; PG8_LDA(At, 1, 0); PG8_STAGE(PG8_SA(0, 1), a2 + hstep, voffA);
;             PG8_WAIT_V(8); PG8_WAIT_L(0); PG8_BAR; PG8_MMA(0, 0, At, B0); PG8_MMA(0, 1, At, B1); PG8_BAR; PG8_SCHED;
	s_setprio 2
	v_mfma_f32_16x16x32_bf16 v[34:37], v[204:207], v[220:223], v[34:37]
	v_mfma_f32_16x16x32_bf16 v[34:37], v[208:211], v[224:227], v[34:37]
	v_mfma_f32_16x16x32_bf16 v[50:53], v[208:211], v[216:219], v[50:53]
	v_mfma_f32_16x16x32_bf16 v[50:53], v[204:207], v[212:215], v[50:53]
	s_setprio 0
	s_nop 0
	s_add_i32 s71, 0, 0x18000
	v_add_u32_e32 v133, s71, v149
	s_add_i32 s73, 0, 0x1c000
	ds_read_b128 v[144:147], v133
	ds_read_b128 v[184:187], v133 offset:1024
	ds_read_b128 v[188:191], v133 offset:2048
	ds_read_b128 v[192:195], v133 offset:3072
	v_add_u32_e32 v133, s73, v149
	ds_read_b128 v[196:199], v133
	ds_read_b128 v[200:203], v133 offset:1024
	ds_read_b128 v[204:207], v133 offset:2048
	ds_read_b128 v[208:211], v133 offset:3072
	s_mov_b32 m0, s55
	v_lshl_add_u64 v[248:249], v[246:247], 0, s[14:15]
	ds_read_b128 v[212:215], v170 offset:32768
	ds_read_b128 v[216:219], v170 offset:33792
	ds_read_b128 v[220:223], v170 offset:34816
	ds_read_b128 v[224:227], v170 offset:35840
	ds_read_b128 v[228:231], v170 offset:36864
	ds_read_b128 v[232:235], v170 offset:37888
	ds_read_b128 v[236:239], v170 offset:38912
	ds_read_b128 v[240:243], v170 offset:39936
	global_load_lds_dwordx4 v[248:249], off
	v_lshl_add_u64 v[248:249], v[246:247], 0, s[18:19]
	s_mov_b32 m0, s56
	s_nop 0
	global_load_lds_dwordx4 v[248:249], off
	s_waitcnt vmcnt(8)
	s_waitcnt lgkmcnt(0)
	s_barrier
	s_setprio 1
	s_waitcnt lgkmcnt(0)
	v_mfma_f32_16x16x32_bf16 v[126:129], v[144:147], v[212:215], v[126:129]
	v_mfma_f32_16x16x32_bf16 v[126:129], v[184:187], v[216:219], v[126:129]
	v_mfma_f32_16x16x32_bf16 v[110:113], v[184:187], v[224:227], v[110:113]
	v_mfma_f32_16x16x32_bf16 v[110:113], v[144:147], v[220:223], v[110:113]
	v_mfma_f32_16x16x32_bf16 v[94:97], v[144:147], v[228:231], v[94:97]
	v_mfma_f32_16x16x32_bf16 v[94:97], v[184:187], v[232:235], v[94:97]
	v_mfma_f32_16x16x32_bf16 v[78:81], v[184:187], v[240:243], v[78:81]
	v_mfma_f32_16x16x32_bf16 v[78:81], v[144:147], v[236:239], v[78:81]
	v_mfma_f32_16x16x32_bf16 v[74:77], v[188:191], v[236:239], v[74:77]
	v_mfma_f32_16x16x32_bf16 v[74:77], v[192:195], v[240:243], v[74:77]
	v_mfma_f32_16x16x32_bf16 v[90:93], v[192:195], v[232:235], v[90:93]
	v_mfma_f32_16x16x32_bf16 v[90:93], v[188:191], v[228:231], v[90:93]
	v_mfma_f32_16x16x32_bf16 v[106:109], v[188:191], v[220:223], v[106:109]
	v_mfma_f32_16x16x32_bf16 v[106:109], v[192:195], v[224:227], v[106:109]
	v_mfma_f32_16x16x32_bf16 v[122:125], v[192:195], v[216:219], v[122:125]
	v_mfma_f32_16x16x32_bf16 v[122:125], v[188:191], v[212:215], v[122:125]
	v_mfma_f32_16x16x32_bf16 v[118:121], v[196:199], v[212:215], v[118:121]
	v_mfma_f32_16x16x32_bf16 v[118:121], v[200:203], v[216:219], v[118:121]
	v_mfma_f32_16x16x32_bf16 v[102:105], v[200:203], v[224:227], v[102:105]
	v_mfma_f32_16x16x32_bf16 v[102:105], v[196:199], v[220:223], v[102:105]
	v_mfma_f32_16x16x32_bf16 v[86:89], v[196:199], v[228:231], v[86:89]
	v_mfma_f32_16x16x32_bf16 v[86:89], v[200:203], v[232:235], v[86:89]
	v_mfma_f32_16x16x32_bf16 v[70:73], v[200:203], v[240:243], v[70:73]
	v_mfma_f32_16x16x32_bf16 v[70:73], v[196:199], v[236:239], v[70:73]
	v_mfma_f32_16x16x32_bf16 v[66:69], v[204:207], v[236:239], v[66:69]
	v_mfma_f32_16x16x32_bf16 v[66:69], v[208:211], v[240:243], v[66:69]
	v_mfma_f32_16x16x32_bf16 v[82:85], v[208:211], v[232:235], v[82:85]
	v_mfma_f32_16x16x32_bf16 v[82:85], v[204:207], v[228:231], v[82:85]
	s_barrier
; #define PG8_STAGE(bufoff, gbase, voff) do { if constexpr (!pg8_noload<Epi>::value) { _Pragma("unroll") for (int _i = 0; _i < 2; ++_i) \
;         __builtin_amdgcn_global_load_lds((const unsigned*)((const char*)(gbase) + (size_t)_i * pstep + (voff)[0]), (PG8_LAS unsigned*)(lds + (bufoff) + ldsw + _i * 8192), 16, 0, 0); } } while (0)
; #define PG8_LDA(dst, b, h) do { _Pragma("unroll") for (int m = 0; m < 4; ++m) _Pragma("unroll") for (int k = 0; k < 2; ++k) dst[m][k] = *(const PG8_LAS bf16x8*)(lds + PG8_SA(b, h) + aoff + m * 2048 + k * 1024); } while (0)
; #define PG8_MMA(ai, bj, At, Bt) do { __builtin_amdgcn_s_setprio(1); _Pragma("unroll") for (int m = 0; m < 4; ++m) _Pragma("unroll") for (int n = 0; n < 2; ++n) _Pragma("unroll") for (int k = 0; k < 2; ++k) \
;         acc[ai][bj][m][n] = __builtin_amdgcn_mfma_f32_16x16x32_bf16(Bt[n][k], At[m][k], acc[ai][bj][m][n], 0, 0, 0); __builtin_amdgcn_s_setprio(0); } while (0)
; #define PG8_WAIT_V(n) asm volatile("s_waitcnt vmcnt(" #n ")" ::: "memory")
; #define PG8_WAIT_L(n) asm volatile("s_waitcnt lgkmcnt(" #n ")" ::: "memory")
; #define PG8_BAR __builtin_amdgcn_s_barrier()
; #define PG8_SCHED __builtin_amdgcn_sched_barrier(0)
; template <class Epi, class Sched, bool ALIGN_EPI = false, bool SP2 = false, bool ABLK = false>
; __device__ __forceinline__ void gemm_phase(PG8_LAS unsigned char* lds, const Gemm g, const Sched& S, const Epi& E) {
;     ...
;         for (int t = 0; t < nt; t += 2) {
;             const bool last = (t == nt - 2);
;     ...
;             PG8_WAIT_V(8); PG8_WAIT_L(0); PG8_BAR; PG8_MMA(0, 0, At, B0); PG8_MMA(0, 1, At, B1); PG8_BAR; PG8_SCHED;
;             PG8_LDA(At, 1, 1); PG8_STAGE(PG8_SB(1, 0), b3, voffB); PG8_STAGE(PG8_SB(1, 1), b3 + hstep, voffB); PG8_STAGE(PG8_SA(1, 0), a3, voffA);
;             PG8_WAIT_V(8); PG8_WAIT_L(0); PG8_BAR; PG8_MMA(1, 0, At, B0); PG8_MMA(1, 1, At, B1); PG8_BAR; PG8_SCHED;
	s_setprio 2
	v_mfma_f32_16x16x32_bf16 v[98:101], v[204:207], v[220:223], v[98:101]
	v_mfma_f32_16x16x32_bf16 v[98:101], v[208:211], v[224:227], v[98:101]
	v_mfma_f32_16x16x32_bf16 v[114:117], v[208:211], v[216:219], v[114:117]
	v_mfma_f32_16x16x32_bf16 v[114:117], v[204:207], v[212:215], v[114:117]
	s_setprio 0
	s_nop 0
	s_add_i32 s71, s71, s52
	v_lshl_add_u64 v[248:249], v[244:245], 0, s[28:29]
	s_mov_b32 m0, s71
	ds_read_b128 v[212:215], v170 offset:49152
	ds_read_b128 v[216:219], v170 offset:50176
	ds_read_b128 v[220:223], v170 offset:51200
	ds_read_b128 v[224:227], v170 offset:52224
	ds_read_b128 v[228:231], v170 offset:53248
	ds_read_b128 v[232:235], v170 offset:54272
	ds_read_b128 v[236:239], v170 offset:55296
	ds_read_b128 v[240:243], v170 offset:56320
	global_load_lds_dwordx4 v[248:249], off
	v_lshl_add_u64 v[248:249], v[244:245], 0, s[30:31]
	s_add_i32 m0, s71, 0x2000
	s_add_i32 s71, s73, s52
	global_load_lds_dwordx4 v[248:249], off
	v_lshl_add_u64 v[248:249], v[244:245], 0, s[34:35]
	s_mov_b32 m0, s71
	v_lshl_add_u64 v[244:245], v[244:245], 0, s[36:37]
	global_load_lds_dwordx4 v[248:249], off
	s_add_i32 m0, s71, 0x2000
	s_nop 0
	global_load_lds_dwordx4 v[244:245], off
	v_lshl_add_u64 v[244:245], v[246:247], 0, s[28:29]
	s_mov_b32 m0, s59
	s_nop 0
	global_load_lds_dwordx4 v[244:245], off
	v_lshl_add_u64 v[244:245], v[246:247], 0, s[30:31]
	s_mov_b32 m0, s60
	s_nop 0
	global_load_lds_dwordx4 v[244:245], off
	s_waitcnt vmcnt(8)
	s_waitcnt lgkmcnt(0)
	s_barrier
	s_setprio 1
	s_waitcnt lgkmcnt(0)
	v_mfma_f32_16x16x32_bf16 v[62:65], v[144:147], v[212:215], v[62:65]
	v_mfma_f32_16x16x32_bf16 v[62:65], v[184:187], v[216:219], v[62:65]
	v_mfma_f32_16x16x32_bf16 v[46:49], v[184:187], v[224:227], v[46:49]
	v_mfma_f32_16x16x32_bf16 v[46:49], v[144:147], v[220:223], v[46:49]
	v_mfma_f32_16x16x32_bf16 v[30:33], v[144:147], v[228:231], v[30:33]
	v_mfma_f32_16x16x32_bf16 v[30:33], v[184:187], v[232:235], v[30:33]
	v_mfma_f32_16x16x32_bf16 v[14:17], v[184:187], v[240:243], v[14:17]
	v_mfma_f32_16x16x32_bf16 v[14:17], v[144:147], v[236:239], v[14:17]
	v_mfma_f32_16x16x32_bf16 v[10:13], v[188:191], v[236:239], v[10:13]
	v_mfma_f32_16x16x32_bf16 v[10:13], v[192:195], v[240:243], v[10:13]
	v_mfma_f32_16x16x32_bf16 v[26:29], v[192:195], v[232:235], v[26:29]
	v_mfma_f32_16x16x32_bf16 v[26:29], v[188:191], v[228:231], v[26:29]
	v_mfma_f32_16x16x32_bf16 v[42:45], v[188:191], v[220:223], v[42:45]
	v_mfma_f32_16x16x32_bf16 v[42:45], v[192:195], v[224:227], v[42:45]
	v_mfma_f32_16x16x32_bf16 v[58:61], v[192:195], v[216:219], v[58:61]
	v_mfma_f32_16x16x32_bf16 v[58:61], v[188:191], v[212:215], v[58:61]
	v_mfma_f32_16x16x32_bf16 v[54:57], v[196:199], v[212:215], v[54:57]
	v_mfma_f32_16x16x32_bf16 v[54:57], v[200:203], v[216:219], v[54:57]
	v_mfma_f32_16x16x32_bf16 v[38:41], v[200:203], v[224:227], v[38:41]
	v_mfma_f32_16x16x32_bf16 v[38:41], v[196:199], v[220:223], v[38:41]
	v_mfma_f32_16x16x32_bf16 v[22:25], v[196:199], v[228:231], v[22:25]
	v_mfma_f32_16x16x32_bf16 v[22:25], v[200:203], v[232:235], v[22:25]
	v_mfma_f32_16x16x32_bf16 v[6:9], v[200:203], v[240:243], v[6:9]
	v_mfma_f32_16x16x32_bf16 v[6:9], v[196:199], v[236:239], v[6:9]
	v_mfma_f32_16x16x32_bf16 v[2:5], v[204:207], v[236:239], v[2:5]
	v_mfma_f32_16x16x32_bf16 v[2:5], v[208:211], v[240:243], v[2:5]
	v_mfma_f32_16x16x32_bf16 v[18:21], v[208:211], v[232:235], v[18:21]
	v_mfma_f32_16x16x32_bf16 v[18:21], v[204:207], v[228:231], v[18:21]
	s_barrier
	s_setprio 2
	v_mfma_f32_16x16x32_bf16 v[34:37], v[204:207], v[220:223], v[34:37]
	v_mfma_f32_16x16x32_bf16 v[34:37], v[208:211], v[224:227], v[34:37]
	v_mfma_f32_16x16x32_bf16 v[50:53], v[208:211], v[216:219], v[50:53]
	v_mfma_f32_16x16x32_bf16 v[50:53], v[204:207], v[212:215], v[50:53]
	s_setprio 0
	s_add_i32 s70, s70, 2
	s_add_u32 vcc_lo, vcc_lo, 0x1000
	s_addc_u32 vcc_hi, vcc_hi, 0
	s_add_u32 s16, s16, 0x1000
	s_addc_u32 s17, s17, 0
	s_cmp_gt_u32 s70, 29
	s_cbranch_scc0 .LBB0_114
	s_and_b64 vcc, exec, s[38:39]
	s_cbranch_vccz .LBB0_117
	s_barrier

; #define PG8_STAGE(bufoff, gbase, voff) do { if constexpr (!pg8_noload<Epi>::value) { _Pragma("unroll") for (int _i = 0; _i < 2; ++_i) \
;         __builtin_amdgcn_global_load_lds((const unsigned*)((const char*)(gbase) + (size_t)_i * pstep + (voff)[0]), (PG8_LAS unsigned*)(lds + (bufoff) + ldsw + _i * 8192), 16, 0, 0); } } while (0)
; #define PG8_LDA(dst, b, h) do { _Pragma("unroll") for (int m = 0; m < 4; ++m) _Pragma("unroll") for (int k = 0; k < 2; ++k) dst[m][k] = *(const PG8_LAS bf16x8*)(lds + PG8_SA(b, h) + aoff + m * 2048 + k * 1024); } while (0)
; #define PG8_LDB(dst, b, h) do { _Pragma("unroll") for (int n = 0; n < 2; ++n) _Pragma("unroll") for (int k = 0; k < 2; ++k) dst[n][k] = *(const PG8_LAS bf16x8*)(lds + PG8_SB(b, h) + boff + n * 2048 + k * 1024); } while (0)
; #define PG8_WAIT_V(n) asm volatile("s_waitcnt vmcnt(" #n ")" ::: "memory")
; #define PG8_WAIT_L(n) asm volatile("s_waitcnt lgkmcnt(" #n ")" ::: "memory")
; #define PG8_BAR __builtin_amdgcn_s_barrier()
; #define PG8_SCHED __builtin_amdgcn_sched_barrier(0)
; template <class Epi, class Sched, bool ALIGN_EPI = false, bool SP2 = false, bool ABLK = false>
; __device__ __forceinline__ void gemm_phase(PG8_LAS unsigned char* lds, const Gemm g, const Sched& S, const Epi& E) {
;     ...
;         for (int t = 0; t < nt; t += 2) {
;             const bool last = (t == nt - 2);
;             const char* a1 = cA + (size_t)(t + 1) * kstep;
;             const char* a2 = last ? nA : cA + (size_t)(t + 2) * kstep; const char* b2 = last ? nB : cB + (size_t)(t + 2) * kstepB;
;             const char* a3 = a2 + kstep; const char* b3 = b2 + kstepB;
;             if (last && has_next) S.a_ready(nxt);
;             if constexpr (SP2) {
;             PG8_LDB(B0, 0, 0); PG8_LDB(B1, 0, 1); PG8_SCHED; PG8_LDA(At, 0, 0); PG8_STAGE(PG8_SA(1, 1), a1 + hstep, voffA);
;             PG8_WAIT_V(8); PG8_WAIT_L(0); PG8_BAR; PG8_MMA(0, 0, At, B0); PG8_MMA(0, 1, At, B1); PG8_BAR; PG8_SCHED;
;     ...
; #pragma unroll
;         for (int a = 0; a < 2; ++a)
; #pragma unroll
;             for (int b = 0; b < 2; ++b)
; #pragma unroll
;                 for (int m = 0; m < 4; ++m)
; #pragma unroll
;                     for (int n = 0; n < 2; ++n) acc[a][b][m][n] = (f32x4){0.f, 0.f, 0.f, 0.f};
;         cur = nxt; cA = nA; cB = nB; ++ui; nt = cur.nt;
.LBB0_486:
	s_add_i32 s3, s80, -2
	s_add_u32 s92, s92, 0x100800
	s_addc_u32 s93, s93, 0
	s_add_u32 s11, s94, 0x1000
	v_mov_b32_e32 v2, 0
	s_addc_u32 s37, s95, 0
	s_mov_b32 s39, 0
	s_waitcnt lgkmcnt(0)
	v_mov_b32_e32 v3, v2
	v_mov_b32_e32 v4, v2
	v_mov_b32_e32 v5, v2
	v_mov_b32_e32 v6, v2
	v_mov_b32_e32 v7, v2
	v_mov_b32_e32 v8, v2
	v_mov_b32_e32 v9, v2
	v_mov_b32_e32 v18, v2
	v_mov_b32_e32 v19, v2
	v_mov_b32_e32 v20, v2
	v_mov_b32_e32 v21, v2
	v_mov_b32_e32 v22, v2
	v_mov_b32_e32 v23, v2
	v_mov_b32_e32 v24, v2
	v_mov_b32_e32 v25, v2
	v_mov_b32_e32 v34, v2
	v_mov_b32_e32 v35, v2
	v_mov_b32_e32 v36, v2
	v_mov_b32_e32 v37, v2
	v_mov_b32_e32 v38, v2
	v_mov_b32_e32 v39, v2
	v_mov_b32_e32 v40, v2
	v_mov_b32_e32 v41, v2
	v_mov_b32_e32 v50, v2
	v_mov_b32_e32 v51, v2
	v_mov_b32_e32 v52, v2
	v_mov_b32_e32 v53, v2
	v_mov_b32_e32 v54, v2
	v_mov_b32_e32 v55, v2
	v_mov_b32_e32 v56, v2
	v_mov_b32_e32 v57, v2
	v_mov_b32_e32 v10, v2
	v_mov_b32_e32 v11, v2
	v_mov_b32_e32 v12, v2
	v_mov_b32_e32 v13, v2
	v_mov_b32_e32 v14, v2
	v_mov_b32_e32 v15, v2
	v_mov_b32_e32 v16, v2
	v_mov_b32_e32 v17, v2
	v_mov_b32_e32 v26, v2
	v_mov_b32_e32 v27, v2
	v_mov_b32_e32 v28, v2
	v_mov_b32_e32 v29, v2
	v_mov_b32_e32 v30, v2
	v_mov_b32_e32 v31, v2
	v_mov_b32_e32 v32, v2
	v_mov_b32_e32 v33, v2
	v_mov_b32_e32 v42, v2
	v_mov_b32_e32 v43, v2
	v_mov_b32_e32 v44, v2
	v_mov_b32_e32 v45, v2
	v_mov_b32_e32 v46, v2
	v_mov_b32_e32 v47, v2
	v_mov_b32_e32 v48, v2
	v_mov_b32_e32 v49, v2
	v_mov_b32_e32 v58, v2
	v_mov_b32_e32 v59, v2
	v_mov_b32_e32 v60, v2
	v_mov_b32_e32 v61, v2
	v_mov_b32_e32 v62, v2
	v_mov_b32_e32 v63, v2
	v_mov_b32_e32 v64, v2
	v_mov_b32_e32 v65, v2
	v_mov_b32_e32 v66, v2
	v_mov_b32_e32 v67, v2
	v_mov_b32_e32 v68, v2
	v_mov_b32_e32 v69, v2
	v_mov_b32_e32 v70, v2
	v_mov_b32_e32 v71, v2
	v_mov_b32_e32 v72, v2
	v_mov_b32_e32 v73, v2
	v_mov_b32_e32 v82, v2
	v_mov_b32_e32 v83, v2
	v_mov_b32_e32 v84, v2
	v_mov_b32_e32 v85, v2
	v_mov_b32_e32 v86, v2
	v_mov_b32_e32 v87, v2
	v_mov_b32_e32 v88, v2
	v_mov_b32_e32 v89, v2
	v_mov_b32_e32 v98, v2
	v_mov_b32_e32 v99, v2
	v_mov_b32_e32 v100, v2
	v_mov_b32_e32 v101, v2
	v_mov_b32_e32 v102, v2
	v_mov_b32_e32 v103, v2
	v_mov_b32_e32 v104, v2
	v_mov_b32_e32 v105, v2
	v_mov_b32_e32 v118, v2
	v_mov_b32_e32 v119, v2
	v_mov_b32_e32 v120, v2
	v_mov_b32_e32 v121, v2
	v_mov_b32_e32 v122, v2
	v_mov_b32_e32 v123, v2
	v_mov_b32_e32 v124, v2
	v_mov_b32_e32 v125, v2
	v_mov_b32_e32 v74, v2
	v_mov_b32_e32 v75, v2
	v_mov_b32_e32 v76, v2
	v_mov_b32_e32 v77, v2
	v_mov_b32_e32 v78, v2
	v_mov_b32_e32 v79, v2
	v_mov_b32_e32 v80, v2
	v_mov_b32_e32 v81, v2
	v_mov_b32_e32 v90, v2
	v_mov_b32_e32 v91, v2
	v_mov_b32_e32 v92, v2
	v_mov_b32_e32 v93, v2
	v_mov_b32_e32 v94, v2
	v_mov_b32_e32 v95, v2
	v_mov_b32_e32 v96, v2
	v_mov_b32_e32 v97, v2
	v_mov_b32_e32 v106, v2
	v_mov_b32_e32 v107, v2
	v_mov_b32_e32 v108, v2
	v_mov_b32_e32 v109, v2
	v_mov_b32_e32 v110, v2
	v_mov_b32_e32 v111, v2
	v_mov_b32_e32 v112, v2
	v_mov_b32_e32 v113, v2
	v_mov_b32_e32 v134, v2
	v_mov_b32_e32 v135, v2
	v_mov_b32_e32 v136, v2
	v_mov_b32_e32 v137, v2
	v_mov_b32_e32 v138, v2
	v_mov_b32_e32 v139, v2
	v_mov_b32_e32 v140, v2
	v_mov_b32_e32 v141, v2
	.p2align	6
.LBB0_487:
	s_nop 0
	ds_read_b128 v[114:117], v167
	ds_read_b128 v[126:129], v167 offset:1024
	ds_read_b128 v[130:133], v167 offset:2048
	ds_read_b128 v[142:145], v167 offset:3072
	ds_read_b128 v[146:149], v168
	ds_read_b128 v[150:153], v168 offset:1024
	ds_read_b128 v[174:177], v168 offset:2048
	ds_read_b128 v[178:181], v168 offset:3072
	s_add_i32 s65, s39, 2
	s_add_u32 s68, s92, 0xfff00800
	s_addc_u32 s69, s93, -1
	s_cmp_eq_u32 s3, s39
	s_cselect_b32 s69, s79, s69
	s_cselect_b32 s68, s78, s68
	s_cselect_b32 s71, s89, s37
	s_cselect_b32 s70, s88, s11
	v_lshl_add_u64 v[162:163], s[92:93], 0, v[158:159]
	s_add_i32 m0, s56, 0xc000
	ds_read_b128 v[184:187], v169
	ds_read_b128 v[188:191], v169 offset:1024
	ds_read_b128 v[192:195], v169 offset:2048
	ds_read_b128 v[196:199], v169 offset:3072
	ds_read_b128 v[200:203], v169 offset:4096
	ds_read_b128 v[204:207], v169 offset:5120
	ds_read_b128 v[208:211], v169 offset:6144
	ds_read_b128 v[212:215], v169 offset:7168
	global_load_lds_dwordx4 v[162:163], off
	v_lshl_add_u64 v[162:163], v[162:163], 0, s[12:13]
	s_add_i32 m0, s56, 0xe000
	s_nop 0
	global_load_lds_dwordx4 v[162:163], off
	s_waitcnt vmcnt(8)
	s_waitcnt lgkmcnt(0)
	s_barrier
	s_setprio 1
	s_waitcnt lgkmcnt(0)
	v_mfma_f32_16x16x32_bf16 v[138:141], v[114:117], v[184:187], v[138:141]
	v_mfma_f32_16x16x32_bf16 v[138:141], v[126:129], v[188:191], v[138:141]
	v_mfma_f32_16x16x32_bf16 v[110:113], v[126:129], v[196:199], v[110:113]
	v_mfma_f32_16x16x32_bf16 v[110:113], v[114:117], v[192:195], v[110:113]
	v_mfma_f32_16x16x32_bf16 v[94:97], v[114:117], v[200:203], v[94:97]
	v_mfma_f32_16x16x32_bf16 v[94:97], v[126:129], v[204:207], v[94:97]
	v_mfma_f32_16x16x32_bf16 v[78:81], v[126:129], v[212:215], v[78:81]
	v_mfma_f32_16x16x32_bf16 v[78:81], v[114:117], v[208:211], v[78:81]
	v_mfma_f32_16x16x32_bf16 v[74:77], v[130:133], v[208:211], v[74:77]
	v_mfma_f32_16x16x32_bf16 v[74:77], v[142:145], v[212:215], v[74:77]
	v_mfma_f32_16x16x32_bf16 v[90:93], v[142:145], v[204:207], v[90:93]
	v_mfma_f32_16x16x32_bf16 v[90:93], v[130:133], v[200:203], v[90:93]
	v_mfma_f32_16x16x32_bf16 v[106:109], v[130:133], v[192:195], v[106:109]
	v_mfma_f32_16x16x32_bf16 v[106:109], v[142:145], v[196:199], v[106:109]
	v_mfma_f32_16x16x32_bf16 v[134:137], v[142:145], v[188:191], v[134:137]
	v_mfma_f32_16x16x32_bf16 v[134:137], v[130:133], v[184:187], v[134:137]
	v_mfma_f32_16x16x32_bf16 v[122:125], v[146:149], v[184:187], v[122:125]
	v_mfma_f32_16x16x32_bf16 v[122:125], v[150:153], v[188:191], v[122:125]
	v_mfma_f32_16x16x32_bf16 v[102:105], v[150:153], v[196:199], v[102:105]
	v_mfma_f32_16x16x32_bf16 v[102:105], v[146:149], v[192:195], v[102:105]
	v_mfma_f32_16x16x32_bf16 v[86:89], v[146:149], v[200:203], v[86:89]
	v_mfma_f32_16x16x32_bf16 v[86:89], v[150:153], v[204:207], v[86:89]
	v_mfma_f32_16x16x32_bf16 v[70:73], v[150:153], v[212:215], v[70:73]
	v_mfma_f32_16x16x32_bf16 v[70:73], v[146:149], v[208:211], v[70:73]
	v_mfma_f32_16x16x32_bf16 v[66:69], v[174:177], v[208:211], v[66:69]
	v_mfma_f32_16x16x32_bf16 v[66:69], v[178:181], v[212:215], v[66:69]
	v_mfma_f32_16x16x32_bf16 v[82:85], v[178:181], v[204:207], v[82:85]
	v_mfma_f32_16x16x32_bf16 v[82:85], v[174:177], v[200:203], v[82:85]
	s_barrier
; #define PG8_STAGE(bufoff, gbase, voff) do { if constexpr (!pg8_noload<Epi>::value) { _Pragma("unroll") for (int _i = 0; _i < 2; ++_i) \
;         __builtin_amdgcn_global_load_lds((const unsigned*)((const char*)(gbase) + (size_t)_i * pstep + (voff)[0]), (PG8_LAS unsigned*)(lds + (bufoff) + ldsw + _i * 8192), 16, 0, 0); } } while (0)
; #define PG8_LDA(dst, b, h) do { _Pragma("unroll") for (int m = 0; m < 4; ++m) _Pragma("unroll") for (int k = 0; k < 2; ++k) dst[m][k] = *(const PG8_LAS bf16x8*)(lds + PG8_SA(b, h) + aoff + m * 2048 + k * 1024); } while (0)
; #define PG8_LDB(dst, b, h) do { _Pragma("unroll") for (int n = 0; n < 2; ++n) _Pragma("unroll") for (int k = 0; k < 2; ++k) dst[n][k] = *(const PG8_LAS bf16x8*)(lds + PG8_SB(b, h) + boff + n * 2048 + k * 1024); } while (0)
; #define PG8_MMA(ai, bj, At, Bt) do { __builtin_amdgcn_s_setprio(1); _Pragma("unroll") for (int m = 0; m < 4; ++m) _Pragma("unroll") for (int n = 0; n < 2; ++n) _Pragma("unroll") for (int k = 0; k < 2; ++k) \
;         acc[ai][bj][m][n] = __builtin_amdgcn_mfma_f32_16x16x32_bf16(Bt[n][k], At[m][k], acc[ai][bj][m][n], 0, 0, 0); __builtin_amdgcn_s_setprio(0); } while (0)
; #define PG8_WAIT_V(n) asm volatile("s_waitcnt vmcnt(" #n ")" ::: "memory")
; #define PG8_WAIT_L(n) asm volatile("s_waitcnt lgkmcnt(" #n ")" ::: "memory")
; #define PG8_BAR __builtin_amdgcn_s_barrier()
; template <class Epi, class Sched, bool ALIGN_EPI = false, bool SP2 = false, bool ABLK = false>
; __device__ __forceinline__ void gemm_phase(PG8_LAS unsigned char* lds, const Gemm g, const Sched& S, const Epi& E) {
;     ...
;             PG8_WAIT_V(8); PG8_WAIT_L(0); PG8_BAR; PG8_MMA(0, 0, At, B0); PG8_MMA(0, 1, At, B1); PG8_BAR; PG8_SCHED;
;             PG8_LDA(At, 0, 1); PG8_STAGE(PG8_SB(0, 0), b2, voffB); PG8_STAGE(PG8_SB(0, 1), b2 + hstep, voffB); PG8_STAGE(PG8_SA(0, 0), a2, voffA);
;             PG8_WAIT_V(8); PG8_WAIT_L(0); PG8_BAR; PG8_MMA(1, 0, At, B0); PG8_MMA(1, 1, At, B1); PG8_BAR; PG8_SCHED;
;             PG8_LDB(B0, 1, 0); PG8_LDB(B1, 1, 1); PG8_SCHED; PG8_LDA(At, 1, 0); PG8_STAGE(PG8_SA(0, 1), a2 + hstep, voffA);
;             PG8_WAIT_V(8); PG8_WAIT_L(0); PG8_BAR; PG8_MMA(0, 0, At, B0); PG8_MMA(0, 1, At, B1); PG8_BAR; PG8_SCHED;
;             PG8_LDA(At, 1, 1); PG8_STAGE(PG8_SB(1, 0), b3, voffB); PG8_STAGE(PG8_SB(1, 1), b3 + hstep, voffB); PG8_STAGE(PG8_SA(1, 0), a3, voffA);
	s_setprio 2
	v_mfma_f32_16x16x32_bf16 v[98:101], v[174:177], v[192:195], v[98:101]
	v_mfma_f32_16x16x32_bf16 v[98:101], v[178:181], v[196:199], v[98:101]
	v_mfma_f32_16x16x32_bf16 v[118:121], v[178:181], v[188:191], v[118:121]
	v_mfma_f32_16x16x32_bf16 v[118:121], v[174:177], v[184:187], v[118:121]
	s_setprio 0
	s_nop 0
	s_add_i32 s39, s73, s55
	v_lshl_add_u64 v[162:163], s[70:71], 0, v[154:155]
	s_mov_b32 m0, s39
	ds_read_b128 v[184:187], v169 offset:16384
	ds_read_b128 v[188:191], v169 offset:17408
	ds_read_b128 v[192:195], v169 offset:18432
	ds_read_b128 v[196:199], v169 offset:19456
	ds_read_b128 v[200:203], v169 offset:20480
	ds_read_b128 v[204:207], v169 offset:21504
	ds_read_b128 v[208:211], v169 offset:22528
	ds_read_b128 v[212:215], v169 offset:23552
	global_load_lds_dwordx4 v[162:163], off
	v_lshl_add_u64 v[216:217], v[162:163], 0, s[12:13]
	s_add_i32 m0, s39, 0x2000
	s_add_i32 s39, s74, s55
	global_load_lds_dwordx4 v[216:217], off
	v_lshl_add_u64 v[216:217], v[162:163], 0, s[14:15]
	s_mov_b32 m0, s39
	s_nop 0
	global_load_lds_dwordx4 v[216:217], off
	v_lshl_add_u64 v[216:217], v[162:163], 0, s[16:17]
	s_add_i32 m0, s39, 0x2000
	s_nop 0
	global_load_lds_dwordx4 v[216:217], off
	v_lshl_add_u64 v[216:217], s[68:69], 0, v[154:155]
	s_mov_b32 m0, s56
	v_lshl_add_u64 v[218:219], v[216:217], 0, s[12:13]
	global_load_lds_dwordx4 v[216:217], off
	s_mov_b32 m0, s57
	s_nop 0
	global_load_lds_dwordx4 v[218:219], off
	s_waitcnt vmcnt(8)
	s_waitcnt lgkmcnt(0)
	s_barrier
	s_setprio 1
	s_waitcnt lgkmcnt(0)
	v_mfma_f32_16x16x32_bf16 v[62:65], v[114:117], v[184:187], v[62:65]
	v_mfma_f32_16x16x32_bf16 v[62:65], v[126:129], v[188:191], v[62:65]
	v_mfma_f32_16x16x32_bf16 v[46:49], v[126:129], v[196:199], v[46:49]
	v_mfma_f32_16x16x32_bf16 v[46:49], v[114:117], v[192:195], v[46:49]
	v_mfma_f32_16x16x32_bf16 v[30:33], v[114:117], v[200:203], v[30:33]
	v_mfma_f32_16x16x32_bf16 v[30:33], v[126:129], v[204:207], v[30:33]
	v_mfma_f32_16x16x32_bf16 v[14:17], v[126:129], v[212:215], v[14:17]
	v_mfma_f32_16x16x32_bf16 v[14:17], v[114:117], v[208:211], v[14:17]
	v_mfma_f32_16x16x32_bf16 v[10:13], v[130:133], v[208:211], v[10:13]
	v_mfma_f32_16x16x32_bf16 v[10:13], v[142:145], v[212:215], v[10:13]
	v_mfma_f32_16x16x32_bf16 v[26:29], v[142:145], v[204:207], v[26:29]
	v_mfma_f32_16x16x32_bf16 v[26:29], v[130:133], v[200:203], v[26:29]
	v_mfma_f32_16x16x32_bf16 v[42:45], v[130:133], v[192:195], v[42:45]
	v_mfma_f32_16x16x32_bf16 v[42:45], v[142:145], v[196:199], v[42:45]
	v_mfma_f32_16x16x32_bf16 v[58:61], v[142:145], v[188:191], v[58:61]
	v_mfma_f32_16x16x32_bf16 v[58:61], v[130:133], v[184:187], v[58:61]
	v_mfma_f32_16x16x32_bf16 v[54:57], v[146:149], v[184:187], v[54:57]
	v_mfma_f32_16x16x32_bf16 v[54:57], v[150:153], v[188:191], v[54:57]
	v_mfma_f32_16x16x32_bf16 v[38:41], v[150:153], v[196:199], v[38:41]
	v_mfma_f32_16x16x32_bf16 v[38:41], v[146:149], v[192:195], v[38:41]
	v_mfma_f32_16x16x32_bf16 v[22:25], v[146:149], v[200:203], v[22:25]
	v_mfma_f32_16x16x32_bf16 v[22:25], v[150:153], v[204:207], v[22:25]
	v_mfma_f32_16x16x32_bf16 v[6:9], v[150:153], v[212:215], v[6:9]
	v_mfma_f32_16x16x32_bf16 v[6:9], v[146:149], v[208:211], v[6:9]
	v_mfma_f32_16x16x32_bf16 v[2:5], v[174:177], v[208:211], v[2:5]
	v_mfma_f32_16x16x32_bf16 v[2:5], v[178:181], v[212:215], v[2:5]
	v_mfma_f32_16x16x32_bf16 v[18:21], v[178:181], v[204:207], v[18:21]
	v_mfma_f32_16x16x32_bf16 v[18:21], v[174:177], v[200:203], v[18:21]
	s_barrier
	s_setprio 2
	v_mfma_f32_16x16x32_bf16 v[34:37], v[174:177], v[192:195], v[34:37]
	v_mfma_f32_16x16x32_bf16 v[34:37], v[178:181], v[196:199], v[34:37]
	v_mfma_f32_16x16x32_bf16 v[50:53], v[178:181], v[188:191], v[50:53]
	v_mfma_f32_16x16x32_bf16 v[50:53], v[174:177], v[184:187], v[50:53]
	s_setprio 0
	s_nop 0
	s_add_i32 s39, 0, 0x18000
	s_add_i32 s68, 0, 0x1c000
	v_add_u32_e32 v142, s39, v1
	v_add_u32_e32 v173, s68, v1
	ds_read_b128 v[114:117], v142
	ds_read_b128 v[126:129], v142 offset:1024
	ds_read_b128 v[130:133], v142 offset:2048
	ds_read_b128 v[142:145], v142 offset:3072
	ds_read_b128 v[146:149], v173
	ds_read_b128 v[150:153], v173 offset:1024
	ds_read_b128 v[174:177], v173 offset:2048
	ds_read_b128 v[178:181], v173 offset:3072
	s_mov_b32 m0, s58
	v_lshl_add_u64 v[218:219], v[216:217], 0, s[14:15]
	ds_read_b128 v[184:187], v169 offset:32768
	ds_read_b128 v[188:191], v169 offset:33792
	ds_read_b128 v[192:195], v169 offset:34816
	ds_read_b128 v[196:199], v169 offset:35840
	ds_read_b128 v[200:203], v169 offset:36864
	ds_read_b128 v[204:207], v169 offset:37888
	ds_read_b128 v[208:211], v169 offset:38912
	ds_read_b128 v[212:215], v169 offset:39936
	global_load_lds_dwordx4 v[218:219], off
	v_lshl_add_u64 v[218:219], v[216:217], 0, s[16:17]
	s_mov_b32 m0, s59
	s_nop 0
	global_load_lds_dwordx4 v[218:219], off
	s_waitcnt vmcnt(8)
	s_waitcnt lgkmcnt(0)
	s_barrier
; #define PG8_STAGE(bufoff, gbase, voff) do { if constexpr (!pg8_noload<Epi>::value) { _Pragma("unroll") for (int _i = 0; _i < 2; ++_i) \
;         __builtin_amdgcn_global_load_lds((const unsigned*)((const char*)(gbase) + (size_t)_i * pstep + (voff)[0]), (PG8_LAS unsigned*)(lds + (bufoff) + ldsw + _i * 8192), 16, 0, 0); } } while (0)
; #define PG8_LDA(dst, b, h) do { _Pragma("unroll") for (int m = 0; m < 4; ++m) _Pragma("unroll") for (int k = 0; k < 2; ++k) dst[m][k] = *(const PG8_LAS bf16x8*)(lds + PG8_SA(b, h) + aoff + m * 2048 + k * 1024); } while (0)
; #define PG8_MMA(ai, bj, At, Bt) do { __builtin_amdgcn_s_setprio(1); _Pragma("unroll") for (int m = 0; m < 4; ++m) _Pragma("unroll") for (int n = 0; n < 2; ++n) _Pragma("unroll") for (int k = 0; k < 2; ++k) \
;         acc[ai][bj][m][n] = __builtin_amdgcn_mfma_f32_16x16x32_bf16(Bt[n][k], At[m][k], acc[ai][bj][m][n], 0, 0, 0); __builtin_amdgcn_s_setprio(0); } while (0)
; #define PG8_WAIT_V(n) asm volatile("s_waitcnt vmcnt(" #n ")" ::: "memory")
; #define PG8_WAIT_L(n) asm volatile("s_waitcnt lgkmcnt(" #n ")" ::: "memory")
; #define PG8_BAR __builtin_amdgcn_s_barrier()
; #define PG8_SCHED __builtin_amdgcn_sched_barrier(0)
;     __device__ __forceinline__ void operator()(const f32x4 (&acc)[2][2][4][2], const Unit& u, int wr, int wc, int fr, int fq) const {
;         const int c0 = u.pn * BM + wc * 32 + 8 * fq;
;         if (u.pm * BM < seq) {
; template <class Epi, class Sched, bool ALIGN_EPI = false, bool SP2 = false, bool ABLK = false>
; __device__ __forceinline__ void gemm_phase(PG8_LAS unsigned char* lds, const Gemm g, const Sched& S, const Epi& E) {
;     ...
;             PG8_LDA(At, 1, 1); PG8_STAGE(PG8_SB(1, 0), b3, voffB); PG8_STAGE(PG8_SB(1, 1), b3 + hstep, voffB); PG8_STAGE(PG8_SA(1, 0), a3, voffA);
;             PG8_WAIT_V(8); PG8_WAIT_L(0); PG8_BAR; PG8_MMA(1, 0, At, B0); PG8_MMA(1, 1, At, B1); PG8_BAR; PG8_SCHED;
	s_setprio 1
	s_waitcnt lgkmcnt(0)
	v_mfma_f32_16x16x32_bf16 v[138:141], v[114:117], v[184:187], v[138:141]
	v_mfma_f32_16x16x32_bf16 v[138:141], v[126:129], v[188:191], v[138:141]
	v_mfma_f32_16x16x32_bf16 v[110:113], v[126:129], v[196:199], v[110:113]
	v_mfma_f32_16x16x32_bf16 v[110:113], v[114:117], v[192:195], v[110:113]
	v_mfma_f32_16x16x32_bf16 v[94:97], v[114:117], v[200:203], v[94:97]
	v_mfma_f32_16x16x32_bf16 v[94:97], v[126:129], v[204:207], v[94:97]
	v_mfma_f32_16x16x32_bf16 v[78:81], v[126:129], v[212:215], v[78:81]
	v_mfma_f32_16x16x32_bf16 v[78:81], v[114:117], v[208:211], v[78:81]
	v_mfma_f32_16x16x32_bf16 v[74:77], v[130:133], v[208:211], v[74:77]
	v_mfma_f32_16x16x32_bf16 v[74:77], v[142:145], v[212:215], v[74:77]
	v_mfma_f32_16x16x32_bf16 v[90:93], v[142:145], v[204:207], v[90:93]
	v_mfma_f32_16x16x32_bf16 v[90:93], v[130:133], v[200:203], v[90:93]
	v_mfma_f32_16x16x32_bf16 v[106:109], v[130:133], v[192:195], v[106:109]
	v_mfma_f32_16x16x32_bf16 v[106:109], v[142:145], v[196:199], v[106:109]
	v_mfma_f32_16x16x32_bf16 v[134:137], v[142:145], v[188:191], v[134:137]
	v_mfma_f32_16x16x32_bf16 v[134:137], v[130:133], v[184:187], v[134:137]
	v_mfma_f32_16x16x32_bf16 v[122:125], v[146:149], v[184:187], v[122:125]
	v_mfma_f32_16x16x32_bf16 v[122:125], v[150:153], v[188:191], v[122:125]
	v_mfma_f32_16x16x32_bf16 v[102:105], v[150:153], v[196:199], v[102:105]
	v_mfma_f32_16x16x32_bf16 v[102:105], v[146:149], v[192:195], v[102:105]
	v_mfma_f32_16x16x32_bf16 v[86:89], v[146:149], v[200:203], v[86:89]
	v_mfma_f32_16x16x32_bf16 v[86:89], v[150:153], v[204:207], v[86:89]
	v_mfma_f32_16x16x32_bf16 v[70:73], v[150:153], v[212:215], v[70:73]
	v_mfma_f32_16x16x32_bf16 v[70:73], v[146:149], v[208:211], v[70:73]
	v_mfma_f32_16x16x32_bf16 v[66:69], v[174:177], v[208:211], v[66:69]
	v_mfma_f32_16x16x32_bf16 v[66:69], v[178:181], v[212:215], v[66:69]
	v_mfma_f32_16x16x32_bf16 v[82:85], v[178:181], v[204:207], v[82:85]
	v_mfma_f32_16x16x32_bf16 v[82:85], v[174:177], v[200:203], v[82:85]
	s_barrier
	s_setprio 2
	v_mfma_f32_16x16x32_bf16 v[98:101], v[174:177], v[192:195], v[98:101]
	v_mfma_f32_16x16x32_bf16 v[98:101], v[178:181], v[196:199], v[98:101]
	v_mfma_f32_16x16x32_bf16 v[118:121], v[178:181], v[188:191], v[118:121]
	v_mfma_f32_16x16x32_bf16 v[118:121], v[174:177], v[184:187], v[118:121]
	s_setprio 0
	s_nop 0
	s_add_i32 s39, s39, s55
	v_lshl_add_u64 v[218:219], v[162:163], 0, s[24:25]
	s_mov_b32 m0, s39
	ds_read_b128 v[184:187], v169 offset:49152
	ds_read_b128 v[188:191], v169 offset:50176
	ds_read_b128 v[192:195], v169 offset:51200
	ds_read_b128 v[196:199], v169 offset:52224
	ds_read_b128 v[200:203], v169 offset:53248
	ds_read_b128 v[204:207], v169 offset:54272
	ds_read_b128 v[208:211], v169 offset:55296
	ds_read_b128 v[212:215], v169 offset:56320
	global_load_lds_dwordx4 v[218:219], off
	v_lshl_add_u64 v[218:219], v[162:163], 0, s[26:27]
	s_add_i32 m0, s39, 0x2000
	s_add_i32 s39, s68, s55
	global_load_lds_dwordx4 v[218:219], off
	v_lshl_add_u64 v[218:219], v[162:163], 0, s[28:29]
	s_mov_b32 m0, s39
	v_lshl_add_u64 v[162:163], v[162:163], 0, s[30:31]
	global_load_lds_dwordx4 v[218:219], off
	s_add_i32 m0, s39, 0x2000
	s_nop 0
	global_load_lds_dwordx4 v[162:163], off
	v_lshl_add_u64 v[162:163], v[216:217], 0, s[24:25]
	s_mov_b32 m0, s62
	s_nop 0
	global_load_lds_dwordx4 v[162:163], off
	v_lshl_add_u64 v[162:163], v[216:217], 0, s[26:27]
	s_mov_b32 m0, s63
	s_nop 0
	global_load_lds_dwordx4 v[162:163], off
	s_waitcnt vmcnt(8)
	s_waitcnt lgkmcnt(0)
	s_barrier
	s_setprio 1
	s_waitcnt lgkmcnt(0)
	v_mfma_f32_16x16x32_bf16 v[62:65], v[114:117], v[184:187], v[62:65]
	v_mfma_f32_16x16x32_bf16 v[62:65], v[126:129], v[188:191], v[62:65]
	v_mfma_f32_16x16x32_bf16 v[46:49], v[126:129], v[196:199], v[46:49]
	v_mfma_f32_16x16x32_bf16 v[46:49], v[114:117], v[192:195], v[46:49]
	v_mfma_f32_16x16x32_bf16 v[30:33], v[114:117], v[200:203], v[30:33]
	v_mfma_f32_16x16x32_bf16 v[30:33], v[126:129], v[204:207], v[30:33]
	v_mfma_f32_16x16x32_bf16 v[14:17], v[126:129], v[212:215], v[14:17]
	v_mfma_f32_16x16x32_bf16 v[14:17], v[114:117], v[208:211], v[14:17]
	v_mfma_f32_16x16x32_bf16 v[10:13], v[130:133], v[208:211], v[10:13]
	v_mfma_f32_16x16x32_bf16 v[10:13], v[142:145], v[212:215], v[10:13]
	v_mfma_f32_16x16x32_bf16 v[26:29], v[142:145], v[204:207], v[26:29]
	v_mfma_f32_16x16x32_bf16 v[26:29], v[130:133], v[200:203], v[26:29]
	v_mfma_f32_16x16x32_bf16 v[42:45], v[130:133], v[192:195], v[42:45]
	v_mfma_f32_16x16x32_bf16 v[42:45], v[142:145], v[196:199], v[42:45]
	v_mfma_f32_16x16x32_bf16 v[58:61], v[142:145], v[188:191], v[58:61]
	v_mfma_f32_16x16x32_bf16 v[58:61], v[130:133], v[184:187], v[58:61]
	v_mfma_f32_16x16x32_bf16 v[54:57], v[146:149], v[184:187], v[54:57]
	v_mfma_f32_16x16x32_bf16 v[54:57], v[150:153], v[188:191], v[54:57]
	v_mfma_f32_16x16x32_bf16 v[38:41], v[150:153], v[196:199], v[38:41]
	v_mfma_f32_16x16x32_bf16 v[38:41], v[146:149], v[192:195], v[38:41]
	v_mfma_f32_16x16x32_bf16 v[22:25], v[146:149], v[200:203], v[22:25]
	v_mfma_f32_16x16x32_bf16 v[22:25], v[150:153], v[204:207], v[22:25]
	v_mfma_f32_16x16x32_bf16 v[6:9], v[150:153], v[212:215], v[6:9]
	v_mfma_f32_16x16x32_bf16 v[6:9], v[146:149], v[208:211], v[6:9]
	v_mfma_f32_16x16x32_bf16 v[2:5], v[174:177], v[208:211], v[2:5]
	v_mfma_f32_16x16x32_bf16 v[2:5], v[178:181], v[212:215], v[2:5]
	v_mfma_f32_16x16x32_bf16 v[18:21], v[178:181], v[204:207], v[18:21]
	v_mfma_f32_16x16x32_bf16 v[18:21], v[174:177], v[200:203], v[18:21]
	s_barrier
	s_setprio 2
	v_mfma_f32_16x16x32_bf16 v[34:37], v[174:177], v[192:195], v[34:37]
	v_mfma_f32_16x16x32_bf16 v[34:37], v[178:181], v[196:199], v[34:37]
	v_mfma_f32_16x16x32_bf16 v[50:53], v[178:181], v[188:191], v[50:53]
	v_mfma_f32_16x16x32_bf16 v[50:53], v[174:177], v[184:187], v[50:53]
	s_setprio 0
	s_add_u32 s92, s92, 0x1000
	s_addc_u32 s93, s93, 0
	s_add_u32 s11, s11, 0x1000
	s_addc_u32 s37, s37, 0
	s_cmp_ge_i32 s65, s80
	s_mov_b32 s39, s65
	s_cbranch_scc0 .LBB0_487
	s_and_b64 vcc, exec, s[34:35]
	s_cbranch_vccnz .LBB0_492
	s_lshl_b32 s11, s2, 8
	s_cmp_gt_i32 s2, 63
	s_mov_b64 s[68:69], -1
	s_cbranch_scc1 .LBB0_493

; #define PG8_STAGE(bufoff, gbase, voff) do { if constexpr (!pg8_noload<Epi>::value) { _Pragma("unroll") for (int _i = 0; _i < 2; ++_i) \
;         __builtin_amdgcn_global_load_lds((const unsigned*)((const char*)(gbase) + (size_t)_i * pstep + (voff)[0]), (PG8_LAS unsigned*)(lds + (bufoff) + ldsw + _i * 8192), 16, 0, 0); } } while (0)
; #define PG8_LDA(dst, b, h) do { _Pragma("unroll") for (int m = 0; m < 4; ++m) _Pragma("unroll") for (int k = 0; k < 2; ++k) dst[m][k] = *(const PG8_LAS bf16x8*)(lds + PG8_SA(b, h) + aoff + m * 2048 + k * 1024); } while (0)
; #define PG8_LDB(dst, b, h) do { _Pragma("unroll") for (int n = 0; n < 2; ++n) _Pragma("unroll") for (int k = 0; k < 2; ++k) dst[n][k] = *(const PG8_LAS bf16x8*)(lds + PG8_SB(b, h) + boff + n * 2048 + k * 1024); } while (0)
; #define PG8_MMA(ai, bj, At, Bt) do { __builtin_amdgcn_s_setprio(1); _Pragma("unroll") for (int m = 0; m < 4; ++m) _Pragma("unroll") for (int n = 0; n < 2; ++n) _Pragma("unroll") for (int k = 0; k < 2; ++k) \
;         acc[ai][bj][m][n] = __builtin_amdgcn_mfma_f32_16x16x32_bf16(Bt[n][k], At[m][k], acc[ai][bj][m][n], 0, 0, 0); __builtin_amdgcn_s_setprio(0); } while (0)
; #define PG8_WAIT_V(n) asm volatile("s_waitcnt vmcnt(" #n ")" ::: "memory")
; #define PG8_WAIT_L(n) asm volatile("s_waitcnt lgkmcnt(" #n ")" ::: "memory")
; #define PG8_BAR __builtin_amdgcn_s_barrier()
; #define PG8_SCHED __builtin_amdgcn_sched_barrier(0)
; template <class Epi, class Sched, bool ALIGN_EPI = false, bool SP2 = false, bool ABLK = false>
; __device__ __forceinline__ void gemm_phase(PG8_LAS unsigned char* lds, const Gemm g, const Sched& S, const Epi& E) {
;     ...
;             if (last && has_next) S.a_ready(nxt);
;             if constexpr (SP2) {
;             PG8_LDB(B0, 0, 0); PG8_LDB(B1, 0, 1); PG8_SCHED; PG8_LDA(At, 0, 0); PG8_STAGE(PG8_SA(1, 1), a1 + hstep, voffA);
;             PG8_WAIT_V(8); PG8_WAIT_L(0); PG8_BAR; PG8_MMA(0, 0, At, B0); PG8_MMA(0, 1, At, B1); PG8_BAR; PG8_SCHED;
.LBB0_618:
	s_or_b64 exec, exec, s[72:73]
	s_barrier
	.p2align	6
.LBB0_619:
	s_or_b32 s28, s57, 1
	s_lshl_b64 s[58:59], s[28:29], 11
	s_add_u32 s58, s2, s58
	s_addc_u32 s59, s3, s59
	s_add_i32 s28, s57, 2
	v_add_u32_e32 v160, s78, v168
	v_add_u32_e32 v180, s79, v168
	s_lshl_b64 s[60:61], s[28:29], 11
	ds_read_b128 v[130:133], v160
	ds_read_b128 v[134:137], v160 offset:1024
	ds_read_b128 v[156:159], v160 offset:2048
	ds_read_b128 v[160:163], v160 offset:3072
	ds_read_b128 v[164:167], v180
	ds_read_b128 v[176:179], v180 offset:1024
	ds_read_b128 v[184:187], v180 offset:2048
	ds_read_b128 v[188:191], v180 offset:3072
	s_add_u32 s66, s2, s60
	s_addc_u32 s67, s3, s61
	s_and_b64 s[62:63], s[68:69], exec
	s_cselect_b32 s73, s67, s7
	s_cselect_b32 s72, s66, s15
	s_add_u32 s62, s16, s60
	s_addc_u32 s63, s17, s61
	s_and_b64 s[60:61], s[68:69], exec
	s_cselect_b32 s61, s63, s9
	s_cselect_b32 s60, s62, s56
	v_lshl_add_u64 v[180:181], s[58:59], 0, v[138:139]
	v_lshl_add_u64 v[224:225], v[180:181], 0, s[24:25]
	s_add_i32 m0, s70, 0xc000
	ds_read_b128 v[192:195], v173
	ds_read_b128 v[196:199], v173 offset:1024
	ds_read_b128 v[200:203], v173 offset:2048
	ds_read_b128 v[204:207], v173 offset:3072
	ds_read_b128 v[208:211], v173 offset:4096
	ds_read_b128 v[212:215], v173 offset:5120
	ds_read_b128 v[216:219], v173 offset:6144
	ds_read_b128 v[220:223], v173 offset:7168
	global_load_lds_dwordx4 v[224:225], off
	v_lshl_add_u64 v[180:181], v[180:181], 0, s[26:27]
	s_add_i32 m0, s70, 0xe000
	s_nop 0
	global_load_lds_dwordx4 v[180:181], off
	s_waitcnt vmcnt(8)
	s_waitcnt lgkmcnt(0)
	s_barrier
	s_setprio 1
	s_waitcnt lgkmcnt(0)
	v_mfma_f32_16x16x32_bf16 v[126:129], v[130:133], v[192:195], v[126:129]
	v_mfma_f32_16x16x32_bf16 v[126:129], v[134:137], v[196:199], v[126:129]
	v_mfma_f32_16x16x32_bf16 v[110:113], v[134:137], v[204:207], v[110:113]
	v_mfma_f32_16x16x32_bf16 v[110:113], v[130:133], v[200:203], v[110:113]
	v_mfma_f32_16x16x32_bf16 v[94:97], v[130:133], v[208:211], v[94:97]
	v_mfma_f32_16x16x32_bf16 v[94:97], v[134:137], v[212:215], v[94:97]
	v_mfma_f32_16x16x32_bf16 v[78:81], v[134:137], v[220:223], v[78:81]
	v_mfma_f32_16x16x32_bf16 v[78:81], v[130:133], v[216:219], v[78:81]
	v_mfma_f32_16x16x32_bf16 v[74:77], v[156:159], v[216:219], v[74:77]
	v_mfma_f32_16x16x32_bf16 v[74:77], v[160:163], v[220:223], v[74:77]
	v_mfma_f32_16x16x32_bf16 v[90:93], v[160:163], v[212:215], v[90:93]
	v_mfma_f32_16x16x32_bf16 v[90:93], v[156:159], v[208:211], v[90:93]
	v_mfma_f32_16x16x32_bf16 v[106:109], v[156:159], v[200:203], v[106:109]
	v_mfma_f32_16x16x32_bf16 v[106:109], v[160:163], v[204:207], v[106:109]
	v_mfma_f32_16x16x32_bf16 v[122:125], v[160:163], v[196:199], v[122:125]
	v_mfma_f32_16x16x32_bf16 v[122:125], v[156:159], v[192:195], v[122:125]
	v_mfma_f32_16x16x32_bf16 v[118:121], v[164:167], v[192:195], v[118:121]
	v_mfma_f32_16x16x32_bf16 v[118:121], v[176:179], v[196:199], v[118:121]
	v_mfma_f32_16x16x32_bf16 v[102:105], v[176:179], v[204:207], v[102:105]
	v_mfma_f32_16x16x32_bf16 v[102:105], v[164:167], v[200:203], v[102:105]
	v_mfma_f32_16x16x32_bf16 v[86:89], v[164:167], v[208:211], v[86:89]
	v_mfma_f32_16x16x32_bf16 v[86:89], v[176:179], v[212:215], v[86:89]
	v_mfma_f32_16x16x32_bf16 v[70:73], v[176:179], v[220:223], v[70:73]
	v_mfma_f32_16x16x32_bf16 v[70:73], v[164:167], v[216:219], v[70:73]
	v_mfma_f32_16x16x32_bf16 v[66:69], v[184:187], v[216:219], v[66:69]
	v_mfma_f32_16x16x32_bf16 v[66:69], v[188:191], v[220:223], v[66:69]
	v_mfma_f32_16x16x32_bf16 v[82:85], v[188:191], v[212:215], v[82:85]
	v_mfma_f32_16x16x32_bf16 v[82:85], v[184:187], v[208:211], v[82:85]
	s_barrier
	s_setprio 2
	v_mfma_f32_16x16x32_bf16 v[98:101], v[184:187], v[200:203], v[98:101]
	v_mfma_f32_16x16x32_bf16 v[98:101], v[188:191], v[204:207], v[98:101]
	v_mfma_f32_16x16x32_bf16 v[114:117], v[188:191], v[196:199], v[114:117]
	v_mfma_f32_16x16x32_bf16 v[114:117], v[184:187], v[192:195], v[114:117]
	s_setprio 0
	s_nop 0
	s_add_i32 s58, s78, s91
	v_lshl_add_u64 v[180:181], s[60:61], 0, v[138:139]
	s_mov_b32 m0, s58
	ds_read_b128 v[192:195], v173 offset:16384
	ds_read_b128 v[196:199], v173 offset:17408
	ds_read_b128 v[200:203], v173 offset:18432
	ds_read_b128 v[204:207], v173 offset:19456
	ds_read_b128 v[208:211], v173 offset:20480
	ds_read_b128 v[212:215], v173 offset:21504
	ds_read_b128 v[216:219], v173 offset:22528
	ds_read_b128 v[220:223], v173 offset:23552
	global_load_lds_dwordx4 v[180:181], off
	v_lshl_add_u64 v[224:225], v[180:181], 0, s[22:23]
	s_add_i32 m0, s58, 0x2000
	s_add_i32 s58, s79, s91
	global_load_lds_dwordx4 v[224:225], off
	v_lshl_add_u64 v[224:225], v[180:181], 0, s[24:25]
	s_mov_b32 m0, s58
	s_nop 0
	global_load_lds_dwordx4 v[224:225], off
	v_lshl_add_u64 v[224:225], v[180:181], 0, s[26:27]
	s_add_i32 m0, s58, 0x2000
	s_nop 0
	global_load_lds_dwordx4 v[224:225], off
	v_lshl_add_u64 v[224:225], s[72:73], 0, v[138:139]
	s_mov_b32 m0, s70
	v_lshl_add_u64 v[226:227], v[224:225], 0, s[22:23]
	global_load_lds_dwordx4 v[224:225], off
	s_mov_b32 m0, s71
	s_nop 0
	global_load_lds_dwordx4 v[226:227], off
	s_waitcnt vmcnt(8)
	s_waitcnt lgkmcnt(0)
	s_barrier
; #define PG8_STAGE(bufoff, gbase, voff) do { if constexpr (!pg8_noload<Epi>::value) { _Pragma("unroll") for (int _i = 0; _i < 2; ++_i) \
;         __builtin_amdgcn_global_load_lds((const unsigned*)((const char*)(gbase) + (size_t)_i * pstep + (voff)[0]), (PG8_LAS unsigned*)(lds + (bufoff) + ldsw + _i * 8192), 16, 0, 0); } } while (0)
; #define PG8_LDA(dst, b, h) do { _Pragma("unroll") for (int m = 0; m < 4; ++m) _Pragma("unroll") for (int k = 0; k < 2; ++k) dst[m][k] = *(const PG8_LAS bf16x8*)(lds + PG8_SA(b, h) + aoff + m * 2048 + k * 1024); } while (0)
; #define PG8_LDB(dst, b, h) do { _Pragma("unroll") for (int n = 0; n < 2; ++n) _Pragma("unroll") for (int k = 0; k < 2; ++k) dst[n][k] = *(const PG8_LAS bf16x8*)(lds + PG8_SB(b, h) + boff + n * 2048 + k * 1024); } while (0)
; #define PG8_MMA(ai, bj, At, Bt) do { __builtin_amdgcn_s_setprio(1); _Pragma("unroll") for (int m = 0; m < 4; ++m) _Pragma("unroll") for (int n = 0; n < 2; ++n) _Pragma("unroll") for (int k = 0; k < 2; ++k) \
;         acc[ai][bj][m][n] = __builtin_amdgcn_mfma_f32_16x16x32_bf16(Bt[n][k], At[m][k], acc[ai][bj][m][n], 0, 0, 0); __builtin_amdgcn_s_setprio(0); } while (0)
; #define PG8_WAIT_V(n) asm volatile("s_waitcnt vmcnt(" #n ")" ::: "memory")
; #define PG8_WAIT_L(n) asm volatile("s_waitcnt lgkmcnt(" #n ")" ::: "memory")
; #define PG8_BAR __builtin_amdgcn_s_barrier()
; #define PG8_SCHED __builtin_amdgcn_sched_barrier(0)
; template <class Epi, class Sched, bool ALIGN_EPI = false, bool SP2 = false, bool ABLK = false>
; __device__ __forceinline__ void gemm_phase(PG8_LAS unsigned char* lds, const Gemm g, const Sched& S, const Epi& E) {
;     ...
;             PG8_WAIT_V(8); PG8_WAIT_L(0); PG8_BAR; PG8_MMA(0, 0, At, B0); PG8_MMA(0, 1, At, B1); PG8_BAR; PG8_SCHED;
;             PG8_LDA(At, 0, 1); PG8_STAGE(PG8_SB(0, 0), b2, voffB); PG8_STAGE(PG8_SB(0, 1), b2 + hstep, voffB); PG8_STAGE(PG8_SA(0, 0), a2, voffA);
;             PG8_WAIT_V(8); PG8_WAIT_L(0); PG8_BAR; PG8_MMA(1, 0, At, B0); PG8_MMA(1, 1, At, B1); PG8_BAR; PG8_SCHED;
;             PG8_LDB(B0, 1, 0); PG8_LDB(B1, 1, 1); PG8_SCHED; PG8_LDA(At, 1, 0); PG8_STAGE(PG8_SA(0, 1), a2 + hstep, voffA);
;             PG8_WAIT_V(8); PG8_WAIT_L(0); PG8_BAR; PG8_MMA(0, 0, At, B0); PG8_MMA(0, 1, At, B1); PG8_BAR; PG8_SCHED;
	s_setprio 1
	s_waitcnt lgkmcnt(0)
	v_mfma_f32_16x16x32_bf16 v[62:65], v[130:133], v[192:195], v[62:65]
	v_mfma_f32_16x16x32_bf16 v[62:65], v[134:137], v[196:199], v[62:65]
	v_mfma_f32_16x16x32_bf16 v[46:49], v[134:137], v[204:207], v[46:49]
	v_mfma_f32_16x16x32_bf16 v[46:49], v[130:133], v[200:203], v[46:49]
	v_mfma_f32_16x16x32_bf16 v[30:33], v[130:133], v[208:211], v[30:33]
	v_mfma_f32_16x16x32_bf16 v[30:33], v[134:137], v[212:215], v[30:33]
	v_mfma_f32_16x16x32_bf16 v[14:17], v[134:137], v[220:223], v[14:17]
	v_mfma_f32_16x16x32_bf16 v[14:17], v[130:133], v[216:219], v[14:17]
	v_mfma_f32_16x16x32_bf16 v[10:13], v[156:159], v[216:219], v[10:13]
	v_mfma_f32_16x16x32_bf16 v[10:13], v[160:163], v[220:223], v[10:13]
	v_mfma_f32_16x16x32_bf16 v[26:29], v[160:163], v[212:215], v[26:29]
	v_mfma_f32_16x16x32_bf16 v[26:29], v[156:159], v[208:211], v[26:29]
	v_mfma_f32_16x16x32_bf16 v[42:45], v[156:159], v[200:203], v[42:45]
	v_mfma_f32_16x16x32_bf16 v[42:45], v[160:163], v[204:207], v[42:45]
	v_mfma_f32_16x16x32_bf16 v[58:61], v[160:163], v[196:199], v[58:61]
	v_mfma_f32_16x16x32_bf16 v[58:61], v[156:159], v[192:195], v[58:61]
	v_mfma_f32_16x16x32_bf16 v[54:57], v[164:167], v[192:195], v[54:57]
	v_mfma_f32_16x16x32_bf16 v[54:57], v[176:179], v[196:199], v[54:57]
	v_mfma_f32_16x16x32_bf16 v[38:41], v[176:179], v[204:207], v[38:41]
	v_mfma_f32_16x16x32_bf16 v[38:41], v[164:167], v[200:203], v[38:41]
	v_mfma_f32_16x16x32_bf16 v[22:25], v[164:167], v[208:211], v[22:25]
	v_mfma_f32_16x16x32_bf16 v[22:25], v[176:179], v[212:215], v[22:25]
	v_mfma_f32_16x16x32_bf16 v[6:9], v[176:179], v[220:223], v[6:9]
	v_mfma_f32_16x16x32_bf16 v[6:9], v[164:167], v[216:219], v[6:9]
	v_mfma_f32_16x16x32_bf16 v[2:5], v[184:187], v[216:219], v[2:5]
	v_mfma_f32_16x16x32_bf16 v[2:5], v[188:191], v[220:223], v[2:5]
	v_mfma_f32_16x16x32_bf16 v[18:21], v[188:191], v[212:215], v[18:21]
	v_mfma_f32_16x16x32_bf16 v[18:21], v[184:187], v[208:211], v[18:21]
	s_barrier
	s_setprio 2
	v_mfma_f32_16x16x32_bf16 v[34:37], v[184:187], v[200:203], v[34:37]
	v_mfma_f32_16x16x32_bf16 v[34:37], v[188:191], v[204:207], v[34:37]
	v_mfma_f32_16x16x32_bf16 v[50:53], v[188:191], v[196:199], v[50:53]
	v_mfma_f32_16x16x32_bf16 v[50:53], v[184:187], v[192:195], v[50:53]
	s_setprio 0
	s_nop 0
	s_add_i32 s58, 0, 0x18000
	s_add_i32 s59, 0, 0x1c000
	v_add_u32_e32 v160, s58, v168
	v_add_u32_e32 v188, s59, v168
	ds_read_b128 v[130:133], v160
	ds_read_b128 v[134:137], v160 offset:1024
	ds_read_b128 v[156:159], v160 offset:2048
	ds_read_b128 v[160:163], v160 offset:3072
	ds_read_b128 v[164:167], v188
	ds_read_b128 v[176:179], v188 offset:1024
	ds_read_b128 v[184:187], v188 offset:2048
	ds_read_b128 v[188:191], v188 offset:3072
	s_mov_b32 m0, s34
	v_lshl_add_u64 v[226:227], v[224:225], 0, s[24:25]
	ds_read_b128 v[192:195], v173 offset:32768
	ds_read_b128 v[196:199], v173 offset:33792
	ds_read_b128 v[200:203], v173 offset:34816
	ds_read_b128 v[204:207], v173 offset:35840
	ds_read_b128 v[208:211], v173 offset:36864
	ds_read_b128 v[212:215], v173 offset:37888
	ds_read_b128 v[216:219], v173 offset:38912
	ds_read_b128 v[220:223], v173 offset:39936
	global_load_lds_dwordx4 v[226:227], off
	v_lshl_add_u64 v[226:227], v[224:225], 0, s[26:27]
	s_mov_b32 m0, s35
	s_nop 0
	global_load_lds_dwordx4 v[226:227], off
	s_waitcnt vmcnt(8)
	s_waitcnt lgkmcnt(0)
	s_barrier
	s_setprio 1
	s_waitcnt lgkmcnt(0)
	v_mfma_f32_16x16x32_bf16 v[126:129], v[130:133], v[192:195], v[126:129]
	v_mfma_f32_16x16x32_bf16 v[126:129], v[134:137], v[196:199], v[126:129]
	v_mfma_f32_16x16x32_bf16 v[110:113], v[134:137], v[204:207], v[110:113]
	v_mfma_f32_16x16x32_bf16 v[110:113], v[130:133], v[200:203], v[110:113]
	v_mfma_f32_16x16x32_bf16 v[94:97], v[130:133], v[208:211], v[94:97]
	v_mfma_f32_16x16x32_bf16 v[94:97], v[134:137], v[212:215], v[94:97]
	v_mfma_f32_16x16x32_bf16 v[78:81], v[134:137], v[220:223], v[78:81]
	v_mfma_f32_16x16x32_bf16 v[78:81], v[130:133], v[216:219], v[78:81]
	v_mfma_f32_16x16x32_bf16 v[74:77], v[156:159], v[216:219], v[74:77]
	v_mfma_f32_16x16x32_bf16 v[74:77], v[160:163], v[220:223], v[74:77]
	v_mfma_f32_16x16x32_bf16 v[90:93], v[160:163], v[212:215], v[90:93]
	v_mfma_f32_16x16x32_bf16 v[90:93], v[156:159], v[208:211], v[90:93]
	v_mfma_f32_16x16x32_bf16 v[106:109], v[156:159], v[200:203], v[106:109]
	v_mfma_f32_16x16x32_bf16 v[106:109], v[160:163], v[204:207], v[106:109]
	v_mfma_f32_16x16x32_bf16 v[122:125], v[160:163], v[196:199], v[122:125]
	v_mfma_f32_16x16x32_bf16 v[122:125], v[156:159], v[192:195], v[122:125]
	v_mfma_f32_16x16x32_bf16 v[118:121], v[164:167], v[192:195], v[118:121]
	v_mfma_f32_16x16x32_bf16 v[118:121], v[176:179], v[196:199], v[118:121]
	v_mfma_f32_16x16x32_bf16 v[102:105], v[176:179], v[204:207], v[102:105]
	v_mfma_f32_16x16x32_bf16 v[102:105], v[164:167], v[200:203], v[102:105]
	v_mfma_f32_16x16x32_bf16 v[86:89], v[164:167], v[208:211], v[86:89]
	v_mfma_f32_16x16x32_bf16 v[86:89], v[176:179], v[212:215], v[86:89]
	v_mfma_f32_16x16x32_bf16 v[70:73], v[176:179], v[220:223], v[70:73]
	v_mfma_f32_16x16x32_bf16 v[70:73], v[164:167], v[216:219], v[70:73]
	v_mfma_f32_16x16x32_bf16 v[66:69], v[184:187], v[216:219], v[66:69]
	v_mfma_f32_16x16x32_bf16 v[66:69], v[188:191], v[220:223], v[66:69]
	v_mfma_f32_16x16x32_bf16 v[82:85], v[188:191], v[212:215], v[82:85]
	v_mfma_f32_16x16x32_bf16 v[82:85], v[184:187], v[208:211], v[82:85]
	s_barrier
; #define PG8_STAGE(bufoff, gbase, voff) do { if constexpr (!pg8_noload<Epi>::value) { _Pragma("unroll") for (int _i = 0; _i < 2; ++_i) \
;         __builtin_amdgcn_global_load_lds((const unsigned*)((const char*)(gbase) + (size_t)_i * pstep + (voff)[0]), (PG8_LAS unsigned*)(lds + (bufoff) + ldsw + _i * 8192), 16, 0, 0); } } while (0)
; #define PG8_LDA(dst, b, h) do { _Pragma("unroll") for (int m = 0; m < 4; ++m) _Pragma("unroll") for (int k = 0; k < 2; ++k) dst[m][k] = *(const PG8_LAS bf16x8*)(lds + PG8_SA(b, h) + aoff + m * 2048 + k * 1024); } while (0)
; #define PG8_MMA(ai, bj, At, Bt) do { __builtin_amdgcn_s_setprio(1); _Pragma("unroll") for (int m = 0; m < 4; ++m) _Pragma("unroll") for (int n = 0; n < 2; ++n) _Pragma("unroll") for (int k = 0; k < 2; ++k) \
;         acc[ai][bj][m][n] = __builtin_amdgcn_mfma_f32_16x16x32_bf16(Bt[n][k], At[m][k], acc[ai][bj][m][n], 0, 0, 0); __builtin_amdgcn_s_setprio(0); } while (0)
; #define PG8_WAIT_V(n) asm volatile("s_waitcnt vmcnt(" #n ")" ::: "memory")
; #define PG8_WAIT_L(n) asm volatile("s_waitcnt lgkmcnt(" #n ")" ::: "memory")
; #define PG8_BAR __builtin_amdgcn_s_barrier()
; #define PG8_SCHED __builtin_amdgcn_sched_barrier(0)
; template <class Epi, class Sched, bool ALIGN_EPI = false, bool SP2 = false, bool ABLK = false>
; __device__ __forceinline__ void gemm_phase(PG8_LAS unsigned char* lds, const Gemm g, const Sched& S, const Epi& E) {
;     ...
;             PG8_WAIT_V(8); PG8_WAIT_L(0); PG8_BAR; PG8_MMA(0, 0, At, B0); PG8_MMA(0, 1, At, B1); PG8_BAR; PG8_SCHED;
;             PG8_LDA(At, 1, 1); PG8_STAGE(PG8_SB(1, 0), b3, voffB); PG8_STAGE(PG8_SB(1, 1), b3 + hstep, voffB); PG8_STAGE(PG8_SA(1, 0), a3, voffA);
;             PG8_WAIT_V(8); PG8_WAIT_L(0); PG8_BAR; PG8_MMA(1, 0, At, B0); PG8_MMA(1, 1, At, B1); PG8_BAR; PG8_SCHED;
	s_setprio 2
	v_mfma_f32_16x16x32_bf16 v[98:101], v[184:187], v[200:203], v[98:101]
	v_mfma_f32_16x16x32_bf16 v[98:101], v[188:191], v[204:207], v[98:101]
	v_mfma_f32_16x16x32_bf16 v[114:117], v[188:191], v[196:199], v[114:117]
	v_mfma_f32_16x16x32_bf16 v[114:117], v[184:187], v[192:195], v[114:117]
	s_setprio 0
	s_nop 0
	s_add_i32 s58, s58, s91
	v_lshl_add_u64 v[226:227], v[180:181], 0, s[92:93]
	s_mov_b32 m0, s58
	ds_read_b128 v[192:195], v173 offset:49152
	ds_read_b128 v[196:199], v173 offset:50176
	ds_read_b128 v[200:203], v173 offset:51200
	ds_read_b128 v[204:207], v173 offset:52224
	ds_read_b128 v[208:211], v173 offset:53248
	ds_read_b128 v[212:215], v173 offset:54272
	ds_read_b128 v[216:219], v173 offset:55296
	ds_read_b128 v[220:223], v173 offset:56320
	global_load_lds_dwordx4 v[226:227], off
	v_lshl_add_u64 v[226:227], v[180:181], 0, s[94:95]
	s_add_i32 m0, s58, 0x2000
	s_add_i32 s58, s59, s91
	global_load_lds_dwordx4 v[226:227], off
	v_lshl_add_u64 v[226:227], v[180:181], 0, s[96:97]
	s_mov_b32 m0, s58
	v_lshl_add_u64 v[180:181], v[180:181], 0, s[88:89]
	global_load_lds_dwordx4 v[226:227], off
	s_add_i32 m0, s58, 0x2000
	s_nop 0
	global_load_lds_dwordx4 v[180:181], off
	v_lshl_add_u64 v[180:181], v[224:225], 0, s[92:93]
	s_mov_b32 m0, s10
	s_nop 0
	global_load_lds_dwordx4 v[180:181], off
	v_lshl_add_u64 v[180:181], v[224:225], 0, s[94:95]
	s_mov_b32 m0, s11
	s_nop 0
	global_load_lds_dwordx4 v[180:181], off
	s_waitcnt vmcnt(8)
	s_waitcnt lgkmcnt(0)
	s_barrier
	s_setprio 1
	s_waitcnt lgkmcnt(0)
	v_mfma_f32_16x16x32_bf16 v[62:65], v[130:133], v[192:195], v[62:65]
	v_mfma_f32_16x16x32_bf16 v[62:65], v[134:137], v[196:199], v[62:65]
	v_mfma_f32_16x16x32_bf16 v[46:49], v[134:137], v[204:207], v[46:49]
	v_mfma_f32_16x16x32_bf16 v[46:49], v[130:133], v[200:203], v[46:49]
	v_mfma_f32_16x16x32_bf16 v[30:33], v[130:133], v[208:211], v[30:33]
	v_mfma_f32_16x16x32_bf16 v[30:33], v[134:137], v[212:215], v[30:33]
	v_mfma_f32_16x16x32_bf16 v[14:17], v[134:137], v[220:223], v[14:17]
	v_mfma_f32_16x16x32_bf16 v[14:17], v[130:133], v[216:219], v[14:17]
	v_mfma_f32_16x16x32_bf16 v[10:13], v[156:159], v[216:219], v[10:13]
	v_mfma_f32_16x16x32_bf16 v[10:13], v[160:163], v[220:223], v[10:13]
	v_mfma_f32_16x16x32_bf16 v[26:29], v[160:163], v[212:215], v[26:29]
	v_mfma_f32_16x16x32_bf16 v[26:29], v[156:159], v[208:211], v[26:29]
	v_mfma_f32_16x16x32_bf16 v[42:45], v[156:159], v[200:203], v[42:45]
	v_mfma_f32_16x16x32_bf16 v[42:45], v[160:163], v[204:207], v[42:45]
	v_mfma_f32_16x16x32_bf16 v[58:61], v[160:163], v[196:199], v[58:61]
	v_mfma_f32_16x16x32_bf16 v[58:61], v[156:159], v[192:195], v[58:61]
	v_mfma_f32_16x16x32_bf16 v[54:57], v[164:167], v[192:195], v[54:57]
	v_mfma_f32_16x16x32_bf16 v[54:57], v[176:179], v[196:199], v[54:57]
	v_mfma_f32_16x16x32_bf16 v[38:41], v[176:179], v[204:207], v[38:41]
	v_mfma_f32_16x16x32_bf16 v[38:41], v[164:167], v[200:203], v[38:41]
	v_mfma_f32_16x16x32_bf16 v[22:25], v[164:167], v[208:211], v[22:25]
	v_mfma_f32_16x16x32_bf16 v[22:25], v[176:179], v[212:215], v[22:25]
	v_mfma_f32_16x16x32_bf16 v[6:9], v[176:179], v[220:223], v[6:9]
	v_mfma_f32_16x16x32_bf16 v[6:9], v[164:167], v[216:219], v[6:9]
	v_mfma_f32_16x16x32_bf16 v[2:5], v[184:187], v[216:219], v[2:5]
	v_mfma_f32_16x16x32_bf16 v[2:5], v[188:191], v[220:223], v[2:5]
	v_mfma_f32_16x16x32_bf16 v[18:21], v[188:191], v[212:215], v[18:21]
	v_mfma_f32_16x16x32_bf16 v[18:21], v[184:187], v[208:211], v[18:21]
	s_barrier
	s_setprio 2
	v_mfma_f32_16x16x32_bf16 v[34:37], v[184:187], v[200:203], v[34:37]
	v_mfma_f32_16x16x32_bf16 v[34:37], v[188:191], v[204:207], v[34:37]
	v_mfma_f32_16x16x32_bf16 v[50:53], v[188:191], v[196:199], v[50:53]
	v_mfma_f32_16x16x32_bf16 v[50:53], v[184:187], v[192:195], v[50:53]
	s_setprio 0
	s_cmp_gt_u32 s57, 29
	s_mov_b32 s57, s28
	s_cbranch_scc1 .LBB0_631

; #define PG8_STAGE(bufoff, gbase, voff) do { if constexpr (!pg8_noload<Epi>::value) { _Pragma("unroll") for (int _i = 0; _i < 2; ++_i) \
;         __builtin_amdgcn_global_load_lds((const unsigned*)((const char*)(gbase) + (size_t)_i * pstep + (voff)[0]), (PG8_LAS unsigned*)(lds + (bufoff) + ldsw + _i * 8192), 16, 0, 0); } } while (0)
; #define PG8_LDA(dst, b, h) do { _Pragma("unroll") for (int m = 0; m < 4; ++m) _Pragma("unroll") for (int k = 0; k < 2; ++k) dst[m][k] = *(const PG8_LAS bf16x8*)(lds + PG8_SA(b, h) + aoff + m * 2048 + k * 1024); } while (0)
; #define PG8_LDB(dst, b, h) do { _Pragma("unroll") for (int n = 0; n < 2; ++n) _Pragma("unroll") for (int k = 0; k < 2; ++k) dst[n][k] = *(const PG8_LAS bf16x8*)(lds + PG8_SB(b, h) + boff + n * 2048 + k * 1024); } while (0)
; #define PG8_WAIT_V(n) asm volatile("s_waitcnt vmcnt(" #n ")" ::: "memory")
; #define PG8_WAIT_L(n) asm volatile("s_waitcnt lgkmcnt(" #n ")" ::: "memory")
; #define PG8_BAR __builtin_amdgcn_s_barrier()
; #define PG8_SCHED __builtin_amdgcn_sched_barrier(0)
; template <class Epi, class Sched, bool ALIGN_EPI = false, bool SP2 = false, bool ABLK = false>
; __device__ __forceinline__ void gemm_phase(PG8_LAS unsigned char* lds, const Gemm g, const Sched& S, const Epi& E) {
;     ...
;         for (int t = 0; t < nt; t += 2) {
;             const bool last = (t == nt - 2);
;             const char* a1 = cA + (size_t)(t + 1) * kstep;
;             const char* a2 = last ? nA : cA + (size_t)(t + 2) * kstep; const char* b2 = last ? nB : cB + (size_t)(t + 2) * kstepB;
;             const char* a3 = a2 + kstep; const char* b3 = b2 + kstepB;
;             if (last && has_next) S.a_ready(nxt);
;             if constexpr (SP2) {
;             PG8_LDB(B0, 0, 0); PG8_LDB(B1, 0, 1); PG8_SCHED; PG8_LDA(At, 0, 0); PG8_STAGE(PG8_SA(1, 1), a1 + hstep, voffA);
;             PG8_WAIT_V(8); PG8_WAIT_L(0); PG8_BAR; PG8_MMA(0, 0, At, B0); PG8_MMA(0, 1, At, B1); PG8_BAR; PG8_SCHED;
;     ...
; #pragma unroll
;         for (int a = 0; a < 2; ++a)
; #pragma unroll
;             for (int b = 0; b < 2; ++b)
; #pragma unroll
;                 for (int m = 0; m < 4; ++m)
; #pragma unroll
;                     for (int n = 0; n < 2; ++n) acc[a][b][m][n] = (f32x4){0.f, 0.f, 0.f, 0.f};
;         cur = nxt; cA = nA; cB = nB; ++ui; nt = cur.nt;
.LBB0_1532:
	s_add_i32 s3, s79, -2
	s_add_u32 s68, s68, 0x100800
	s_addc_u32 s69, s69, 0
	s_add_u32 s11, s70, 0x1000
	v_mov_b32_e32 v2, 0
	s_addc_u32 s37, s71, 0
	s_mov_b32 s39, 0
	s_waitcnt lgkmcnt(0)
	v_mov_b32_e32 v3, v2
	v_mov_b32_e32 v4, v2
	v_mov_b32_e32 v5, v2
	v_mov_b32_e32 v6, v2
	v_mov_b32_e32 v7, v2
	v_mov_b32_e32 v8, v2
	v_mov_b32_e32 v9, v2
	v_mov_b32_e32 v18, v2
	v_mov_b32_e32 v19, v2
	v_mov_b32_e32 v20, v2
	v_mov_b32_e32 v21, v2
	v_mov_b32_e32 v22, v2
	v_mov_b32_e32 v23, v2
	v_mov_b32_e32 v24, v2
	v_mov_b32_e32 v25, v2
	v_mov_b32_e32 v34, v2
	v_mov_b32_e32 v35, v2
	v_mov_b32_e32 v36, v2
	v_mov_b32_e32 v37, v2
	v_mov_b32_e32 v38, v2
	v_mov_b32_e32 v39, v2
	v_mov_b32_e32 v40, v2
	v_mov_b32_e32 v41, v2
	v_mov_b32_e32 v50, v2
	v_mov_b32_e32 v51, v2
	v_mov_b32_e32 v52, v2
	v_mov_b32_e32 v53, v2
	v_mov_b32_e32 v54, v2
	v_mov_b32_e32 v55, v2
	v_mov_b32_e32 v56, v2
	v_mov_b32_e32 v57, v2
	v_mov_b32_e32 v10, v2
	v_mov_b32_e32 v11, v2
	v_mov_b32_e32 v12, v2
	v_mov_b32_e32 v13, v2
	v_mov_b32_e32 v14, v2
	v_mov_b32_e32 v15, v2
	v_mov_b32_e32 v16, v2
	v_mov_b32_e32 v17, v2
	v_mov_b32_e32 v26, v2
	v_mov_b32_e32 v27, v2
	v_mov_b32_e32 v28, v2
	v_mov_b32_e32 v29, v2
	v_mov_b32_e32 v30, v2
	v_mov_b32_e32 v31, v2
	v_mov_b32_e32 v32, v2
	v_mov_b32_e32 v33, v2
	v_mov_b32_e32 v42, v2
	v_mov_b32_e32 v43, v2
	v_mov_b32_e32 v44, v2
	v_mov_b32_e32 v45, v2
	v_mov_b32_e32 v46, v2
	v_mov_b32_e32 v47, v2
	v_mov_b32_e32 v48, v2
	v_mov_b32_e32 v49, v2
	v_mov_b32_e32 v58, v2
	v_mov_b32_e32 v59, v2
	v_mov_b32_e32 v60, v2
	v_mov_b32_e32 v61, v2
	v_mov_b32_e32 v62, v2
	v_mov_b32_e32 v63, v2
	v_mov_b32_e32 v64, v2
	v_mov_b32_e32 v65, v2
	v_mov_b32_e32 v66, v2
	v_mov_b32_e32 v67, v2
	v_mov_b32_e32 v68, v2
	v_mov_b32_e32 v69, v2
	v_mov_b32_e32 v70, v2
	v_mov_b32_e32 v71, v2
	v_mov_b32_e32 v72, v2
	v_mov_b32_e32 v73, v2
	v_mov_b32_e32 v82, v2
	v_mov_b32_e32 v83, v2
	v_mov_b32_e32 v84, v2
	v_mov_b32_e32 v85, v2
	v_mov_b32_e32 v86, v2
	v_mov_b32_e32 v87, v2
	v_mov_b32_e32 v88, v2
	v_mov_b32_e32 v89, v2
	v_mov_b32_e32 v98, v2
	v_mov_b32_e32 v99, v2
	v_mov_b32_e32 v100, v2
	v_mov_b32_e32 v101, v2
	v_mov_b32_e32 v102, v2
	v_mov_b32_e32 v103, v2
	v_mov_b32_e32 v104, v2
	v_mov_b32_e32 v105, v2
	v_mov_b32_e32 v118, v2
	v_mov_b32_e32 v119, v2
	v_mov_b32_e32 v120, v2
	v_mov_b32_e32 v121, v2
	v_mov_b32_e32 v122, v2
	v_mov_b32_e32 v123, v2
	v_mov_b32_e32 v124, v2
	v_mov_b32_e32 v125, v2
	v_mov_b32_e32 v74, v2
	v_mov_b32_e32 v75, v2
	v_mov_b32_e32 v76, v2
	v_mov_b32_e32 v77, v2
	v_mov_b32_e32 v78, v2
	v_mov_b32_e32 v79, v2
	v_mov_b32_e32 v80, v2
	v_mov_b32_e32 v81, v2
	v_mov_b32_e32 v90, v2
	v_mov_b32_e32 v91, v2
	v_mov_b32_e32 v92, v2
	v_mov_b32_e32 v93, v2
	v_mov_b32_e32 v94, v2
	v_mov_b32_e32 v95, v2
	v_mov_b32_e32 v96, v2
	v_mov_b32_e32 v97, v2
	v_mov_b32_e32 v106, v2
	v_mov_b32_e32 v107, v2
	v_mov_b32_e32 v108, v2
	v_mov_b32_e32 v109, v2
	v_mov_b32_e32 v110, v2
	v_mov_b32_e32 v111, v2
	v_mov_b32_e32 v112, v2
	v_mov_b32_e32 v113, v2
	v_mov_b32_e32 v134, v2
	v_mov_b32_e32 v135, v2
	v_mov_b32_e32 v136, v2
	v_mov_b32_e32 v137, v2
	v_mov_b32_e32 v138, v2
	v_mov_b32_e32 v139, v2
	v_mov_b32_e32 v140, v2
	v_mov_b32_e32 v141, v2
	.p2align	6
.LBB0_1533:
	s_nop 0
	ds_read_b128 v[114:117], v167
	ds_read_b128 v[126:129], v167 offset:1024
	ds_read_b128 v[130:133], v167 offset:2048
	ds_read_b128 v[142:145], v167 offset:3072
	ds_read_b128 v[146:149], v168
	ds_read_b128 v[150:153], v168 offset:1024
	ds_read_b128 v[174:177], v168 offset:2048
	ds_read_b128 v[178:181], v168 offset:3072
	s_add_i32 s41, s39, 2
	s_add_u32 s70, s68, 0xfff00800
	s_addc_u32 s71, s69, -1
	s_cmp_eq_u32 s3, s39
	s_cselect_b32 s71, s43, s71
	s_cselect_b32 s70, s42, s70
	s_cselect_b32 s81, s65, s37
	s_cselect_b32 s80, s64, s11
	v_lshl_add_u64 v[162:163], s[68:69], 0, v[158:159]
	s_add_i32 m0, s56, 0xc000
	ds_read_b128 v[184:187], v169
	ds_read_b128 v[188:191], v169 offset:1024
	ds_read_b128 v[192:195], v169 offset:2048
	ds_read_b128 v[196:199], v169 offset:3072
	ds_read_b128 v[200:203], v169 offset:4096
	ds_read_b128 v[204:207], v169 offset:5120
	ds_read_b128 v[208:211], v169 offset:6144
	ds_read_b128 v[212:215], v169 offset:7168
	global_load_lds_dwordx4 v[162:163], off
	v_lshl_add_u64 v[162:163], v[162:163], 0, s[12:13]
	s_add_i32 m0, s56, 0xe000
	s_nop 0
	global_load_lds_dwordx4 v[162:163], off
	s_waitcnt vmcnt(8)
	s_waitcnt lgkmcnt(0)
	s_barrier
	s_setprio 1
	s_waitcnt lgkmcnt(0)
	v_mfma_f32_16x16x32_bf16 v[138:141], v[114:117], v[184:187], v[138:141]
	v_mfma_f32_16x16x32_bf16 v[138:141], v[126:129], v[188:191], v[138:141]
	v_mfma_f32_16x16x32_bf16 v[110:113], v[126:129], v[196:199], v[110:113]
	v_mfma_f32_16x16x32_bf16 v[110:113], v[114:117], v[192:195], v[110:113]
	v_mfma_f32_16x16x32_bf16 v[94:97], v[114:117], v[200:203], v[94:97]
	v_mfma_f32_16x16x32_bf16 v[94:97], v[126:129], v[204:207], v[94:97]
	v_mfma_f32_16x16x32_bf16 v[78:81], v[126:129], v[212:215], v[78:81]
	v_mfma_f32_16x16x32_bf16 v[78:81], v[114:117], v[208:211], v[78:81]
	v_mfma_f32_16x16x32_bf16 v[74:77], v[130:133], v[208:211], v[74:77]
	v_mfma_f32_16x16x32_bf16 v[74:77], v[142:145], v[212:215], v[74:77]
	v_mfma_f32_16x16x32_bf16 v[90:93], v[142:145], v[204:207], v[90:93]
	v_mfma_f32_16x16x32_bf16 v[90:93], v[130:133], v[200:203], v[90:93]
	v_mfma_f32_16x16x32_bf16 v[106:109], v[130:133], v[192:195], v[106:109]
	v_mfma_f32_16x16x32_bf16 v[106:109], v[142:145], v[196:199], v[106:109]
	v_mfma_f32_16x16x32_bf16 v[134:137], v[142:145], v[188:191], v[134:137]
	v_mfma_f32_16x16x32_bf16 v[134:137], v[130:133], v[184:187], v[134:137]
	v_mfma_f32_16x16x32_bf16 v[122:125], v[146:149], v[184:187], v[122:125]
	v_mfma_f32_16x16x32_bf16 v[122:125], v[150:153], v[188:191], v[122:125]
	v_mfma_f32_16x16x32_bf16 v[102:105], v[150:153], v[196:199], v[102:105]
	v_mfma_f32_16x16x32_bf16 v[102:105], v[146:149], v[192:195], v[102:105]
	v_mfma_f32_16x16x32_bf16 v[86:89], v[146:149], v[200:203], v[86:89]
	v_mfma_f32_16x16x32_bf16 v[86:89], v[150:153], v[204:207], v[86:89]
	v_mfma_f32_16x16x32_bf16 v[70:73], v[150:153], v[212:215], v[70:73]
	v_mfma_f32_16x16x32_bf16 v[70:73], v[146:149], v[208:211], v[70:73]
	v_mfma_f32_16x16x32_bf16 v[66:69], v[174:177], v[208:211], v[66:69]
	v_mfma_f32_16x16x32_bf16 v[66:69], v[178:181], v[212:215], v[66:69]
	v_mfma_f32_16x16x32_bf16 v[82:85], v[178:181], v[204:207], v[82:85]
	v_mfma_f32_16x16x32_bf16 v[82:85], v[174:177], v[200:203], v[82:85]
	s_barrier
; #define PG8_STAGE(bufoff, gbase, voff) do { if constexpr (!pg8_noload<Epi>::value) { _Pragma("unroll") for (int _i = 0; _i < 2; ++_i) \
;         __builtin_amdgcn_global_load_lds((const unsigned*)((const char*)(gbase) + (size_t)_i * pstep + (voff)[0]), (PG8_LAS unsigned*)(lds + (bufoff) + ldsw + _i * 8192), 16, 0, 0); } } while (0)
; #define PG8_LDA(dst, b, h) do { _Pragma("unroll") for (int m = 0; m < 4; ++m) _Pragma("unroll") for (int k = 0; k < 2; ++k) dst[m][k] = *(const PG8_LAS bf16x8*)(lds + PG8_SA(b, h) + aoff + m * 2048 + k * 1024); } while (0)
; #define PG8_LDB(dst, b, h) do { _Pragma("unroll") for (int n = 0; n < 2; ++n) _Pragma("unroll") for (int k = 0; k < 2; ++k) dst[n][k] = *(const PG8_LAS bf16x8*)(lds + PG8_SB(b, h) + boff + n * 2048 + k * 1024); } while (0)
; #define PG8_MMA(ai, bj, At, Bt) do { __builtin_amdgcn_s_setprio(1); _Pragma("unroll") for (int m = 0; m < 4; ++m) _Pragma("unroll") for (int n = 0; n < 2; ++n) _Pragma("unroll") for (int k = 0; k < 2; ++k) \
;         acc[ai][bj][m][n] = __builtin_amdgcn_mfma_f32_16x16x32_bf16(Bt[n][k], At[m][k], acc[ai][bj][m][n], 0, 0, 0); __builtin_amdgcn_s_setprio(0); } while (0)
; #define PG8_WAIT_V(n) asm volatile("s_waitcnt vmcnt(" #n ")" ::: "memory")
; #define PG8_WAIT_L(n) asm volatile("s_waitcnt lgkmcnt(" #n ")" ::: "memory")
; #define PG8_BAR __builtin_amdgcn_s_barrier()
; template <class Epi, class Sched, bool ALIGN_EPI = false, bool SP2 = false, bool ABLK = false>
; __device__ __forceinline__ void gemm_phase(PG8_LAS unsigned char* lds, const Gemm g, const Sched& S, const Epi& E) {
;     ...
;             PG8_WAIT_V(8); PG8_WAIT_L(0); PG8_BAR; PG8_MMA(0, 0, At, B0); PG8_MMA(0, 1, At, B1); PG8_BAR; PG8_SCHED;
;             PG8_LDA(At, 0, 1); PG8_STAGE(PG8_SB(0, 0), b2, voffB); PG8_STAGE(PG8_SB(0, 1), b2 + hstep, voffB); PG8_STAGE(PG8_SA(0, 0), a2, voffA);
;             PG8_WAIT_V(8); PG8_WAIT_L(0); PG8_BAR; PG8_MMA(1, 0, At, B0); PG8_MMA(1, 1, At, B1); PG8_BAR; PG8_SCHED;
;             PG8_LDB(B0, 1, 0); PG8_LDB(B1, 1, 1); PG8_SCHED; PG8_LDA(At, 1, 0); PG8_STAGE(PG8_SA(0, 1), a2 + hstep, voffA);
;             PG8_WAIT_V(8); PG8_WAIT_L(0); PG8_BAR; PG8_MMA(0, 0, At, B0); PG8_MMA(0, 1, At, B1); PG8_BAR; PG8_SCHED;
;             PG8_LDA(At, 1, 1); PG8_STAGE(PG8_SB(1, 0), b3, voffB); PG8_STAGE(PG8_SB(1, 1), b3 + hstep, voffB); PG8_STAGE(PG8_SA(1, 0), a3, voffA);
	s_setprio 2
	v_mfma_f32_16x16x32_bf16 v[98:101], v[174:177], v[192:195], v[98:101]
	v_mfma_f32_16x16x32_bf16 v[98:101], v[178:181], v[196:199], v[98:101]
	v_mfma_f32_16x16x32_bf16 v[118:121], v[178:181], v[188:191], v[118:121]
	v_mfma_f32_16x16x32_bf16 v[118:121], v[174:177], v[184:187], v[118:121]
	s_setprio 0
	s_nop 0
	s_add_i32 s39, s74, s55
	v_lshl_add_u64 v[162:163], s[80:81], 0, v[154:155]
	s_mov_b32 m0, s39
	ds_read_b128 v[184:187], v169 offset:16384
	ds_read_b128 v[188:191], v169 offset:17408
	ds_read_b128 v[192:195], v169 offset:18432
	ds_read_b128 v[196:199], v169 offset:19456
	ds_read_b128 v[200:203], v169 offset:20480
	ds_read_b128 v[204:207], v169 offset:21504
	ds_read_b128 v[208:211], v169 offset:22528
	ds_read_b128 v[212:215], v169 offset:23552
	global_load_lds_dwordx4 v[162:163], off
	v_lshl_add_u64 v[216:217], v[162:163], 0, s[12:13]
	s_add_i32 m0, s39, 0x2000
	s_add_i32 s39, s75, s55
	global_load_lds_dwordx4 v[216:217], off
	v_lshl_add_u64 v[216:217], v[162:163], 0, s[14:15]
	s_mov_b32 m0, s39
	s_nop 0
	global_load_lds_dwordx4 v[216:217], off
	v_lshl_add_u64 v[216:217], v[162:163], 0, s[16:17]
	s_add_i32 m0, s39, 0x2000
	s_nop 0
	global_load_lds_dwordx4 v[216:217], off
	v_lshl_add_u64 v[216:217], s[70:71], 0, v[154:155]
	s_mov_b32 m0, s56
	v_lshl_add_u64 v[218:219], v[216:217], 0, s[12:13]
	global_load_lds_dwordx4 v[216:217], off
	s_mov_b32 m0, s57
	s_nop 0
	global_load_lds_dwordx4 v[218:219], off
	s_waitcnt vmcnt(8)
	s_waitcnt lgkmcnt(0)
	s_barrier
	s_setprio 1
	s_waitcnt lgkmcnt(0)
	v_mfma_f32_16x16x32_bf16 v[62:65], v[114:117], v[184:187], v[62:65]
	v_mfma_f32_16x16x32_bf16 v[62:65], v[126:129], v[188:191], v[62:65]
	v_mfma_f32_16x16x32_bf16 v[46:49], v[126:129], v[196:199], v[46:49]
	v_mfma_f32_16x16x32_bf16 v[46:49], v[114:117], v[192:195], v[46:49]
	v_mfma_f32_16x16x32_bf16 v[30:33], v[114:117], v[200:203], v[30:33]
	v_mfma_f32_16x16x32_bf16 v[30:33], v[126:129], v[204:207], v[30:33]
	v_mfma_f32_16x16x32_bf16 v[14:17], v[126:129], v[212:215], v[14:17]
	v_mfma_f32_16x16x32_bf16 v[14:17], v[114:117], v[208:211], v[14:17]
	v_mfma_f32_16x16x32_bf16 v[10:13], v[130:133], v[208:211], v[10:13]
	v_mfma_f32_16x16x32_bf16 v[10:13], v[142:145], v[212:215], v[10:13]
	v_mfma_f32_16x16x32_bf16 v[26:29], v[142:145], v[204:207], v[26:29]
	v_mfma_f32_16x16x32_bf16 v[26:29], v[130:133], v[200:203], v[26:29]
	v_mfma_f32_16x16x32_bf16 v[42:45], v[130:133], v[192:195], v[42:45]
	v_mfma_f32_16x16x32_bf16 v[42:45], v[142:145], v[196:199], v[42:45]
	v_mfma_f32_16x16x32_bf16 v[58:61], v[142:145], v[188:191], v[58:61]
	v_mfma_f32_16x16x32_bf16 v[58:61], v[130:133], v[184:187], v[58:61]
	v_mfma_f32_16x16x32_bf16 v[54:57], v[146:149], v[184:187], v[54:57]
	v_mfma_f32_16x16x32_bf16 v[54:57], v[150:153], v[188:191], v[54:57]
	v_mfma_f32_16x16x32_bf16 v[38:41], v[150:153], v[196:199], v[38:41]
	v_mfma_f32_16x16x32_bf16 v[38:41], v[146:149], v[192:195], v[38:41]
	v_mfma_f32_16x16x32_bf16 v[22:25], v[146:149], v[200:203], v[22:25]
	v_mfma_f32_16x16x32_bf16 v[22:25], v[150:153], v[204:207], v[22:25]
	v_mfma_f32_16x16x32_bf16 v[6:9], v[150:153], v[212:215], v[6:9]
	v_mfma_f32_16x16x32_bf16 v[6:9], v[146:149], v[208:211], v[6:9]
	v_mfma_f32_16x16x32_bf16 v[2:5], v[174:177], v[208:211], v[2:5]
	v_mfma_f32_16x16x32_bf16 v[2:5], v[178:181], v[212:215], v[2:5]
	v_mfma_f32_16x16x32_bf16 v[18:21], v[178:181], v[204:207], v[18:21]
	v_mfma_f32_16x16x32_bf16 v[18:21], v[174:177], v[200:203], v[18:21]
	s_barrier
	s_setprio 2
	v_mfma_f32_16x16x32_bf16 v[34:37], v[174:177], v[192:195], v[34:37]
	v_mfma_f32_16x16x32_bf16 v[34:37], v[178:181], v[196:199], v[34:37]
	v_mfma_f32_16x16x32_bf16 v[50:53], v[178:181], v[188:191], v[50:53]
	v_mfma_f32_16x16x32_bf16 v[50:53], v[174:177], v[184:187], v[50:53]
	s_setprio 0
	s_nop 0
	s_add_i32 s39, 0, 0x18000
	s_add_i32 s70, 0, 0x1c000
	v_add_u32_e32 v142, s39, v1
	v_add_u32_e32 v173, s70, v1
	ds_read_b128 v[114:117], v142
	ds_read_b128 v[126:129], v142 offset:1024
	ds_read_b128 v[130:133], v142 offset:2048
	ds_read_b128 v[142:145], v142 offset:3072
	ds_read_b128 v[146:149], v173
	ds_read_b128 v[150:153], v173 offset:1024
	ds_read_b128 v[174:177], v173 offset:2048
	ds_read_b128 v[178:181], v173 offset:3072
	s_mov_b32 m0, s58
	v_lshl_add_u64 v[218:219], v[216:217], 0, s[14:15]
	ds_read_b128 v[184:187], v169 offset:32768
	ds_read_b128 v[188:191], v169 offset:33792
	ds_read_b128 v[192:195], v169 offset:34816
	ds_read_b128 v[196:199], v169 offset:35840
	ds_read_b128 v[200:203], v169 offset:36864
	ds_read_b128 v[204:207], v169 offset:37888
	ds_read_b128 v[208:211], v169 offset:38912
	ds_read_b128 v[212:215], v169 offset:39936
	global_load_lds_dwordx4 v[218:219], off
	v_lshl_add_u64 v[218:219], v[216:217], 0, s[16:17]
	s_mov_b32 m0, s59
	s_nop 0
	global_load_lds_dwordx4 v[218:219], off
	s_waitcnt vmcnt(8)
	s_waitcnt lgkmcnt(0)
	s_barrier
; #define PG8_STAGE(bufoff, gbase, voff) do { if constexpr (!pg8_noload<Epi>::value) { _Pragma("unroll") for (int _i = 0; _i < 2; ++_i) \
;         __builtin_amdgcn_global_load_lds((const unsigned*)((const char*)(gbase) + (size_t)_i * pstep + (voff)[0]), (PG8_LAS unsigned*)(lds + (bufoff) + ldsw + _i * 8192), 16, 0, 0); } } while (0)
; #define PG8_LDA(dst, b, h) do { _Pragma("unroll") for (int m = 0; m < 4; ++m) _Pragma("unroll") for (int k = 0; k < 2; ++k) dst[m][k] = *(const PG8_LAS bf16x8*)(lds + PG8_SA(b, h) + aoff + m * 2048 + k * 1024); } while (0)
; #define PG8_LDB(dst, b, h) do { _Pragma("unroll") for (int n = 0; n < 2; ++n) _Pragma("unroll") for (int k = 0; k < 2; ++k) dst[n][k] = *(const PG8_LAS bf16x8*)(lds + PG8_SB(b, h) + boff + n * 2048 + k * 1024); } while (0)
; #define PG8_MMA(ai, bj, At, Bt) do { __builtin_amdgcn_s_setprio(1); _Pragma("unroll") for (int m = 0; m < 4; ++m) _Pragma("unroll") for (int n = 0; n < 2; ++n) _Pragma("unroll") for (int k = 0; k < 2; ++k) \
;         acc[ai][bj][m][n] = __builtin_amdgcn_mfma_f32_16x16x32_bf16(Bt[n][k], At[m][k], acc[ai][bj][m][n], 0, 0, 0); __builtin_amdgcn_s_setprio(0); } while (0)
; template <class Epi, class Sched, bool ALIGN_EPI = false, bool SP2 = false, bool ABLK = false>
; __device__ __forceinline__ void gemm_phase(PG8_LAS unsigned char* lds, const Gemm g, const Sched& S, const Epi& E) {
;     ...
;             PG8_LDB(B0, 0, 0); PG8_LDB(B1, 0, 1); PG8_SCHED; PG8_LDA(At, 0, 0); PG8_STAGE(PG8_SA(1, 1), a1 + hstep, voffA);
;             PG8_WAIT_V(8); PG8_WAIT_L(0); PG8_BAR; PG8_MMA(0, 0, At, B0); PG8_MMA(0, 1, At, B1); PG8_BAR; PG8_SCHED;
;             PG8_LDA(At, 0, 1); PG8_STAGE(PG8_SB(0, 0), b2, voffB); PG8_STAGE(PG8_SB(0, 1), b2 + hstep, voffB); PG8_STAGE(PG8_SA(0, 0), a2, voffA);
;             PG8_WAIT_V(8); PG8_WAIT_L(0); PG8_BAR; PG8_MMA(1, 0, At, B0); PG8_MMA(1, 1, At, B1); PG8_BAR; PG8_SCHED;
;             PG8_LDB(B0, 1, 0); PG8_LDB(B1, 1, 1); PG8_SCHED; PG8_LDA(At, 1, 0); PG8_STAGE(PG8_SA(0, 1), a2 + hstep, voffA);
;             PG8_WAIT_V(8); PG8_WAIT_L(0); PG8_BAR; PG8_MMA(0, 0, At, B0); PG8_MMA(0, 1, At, B1); PG8_BAR; PG8_SCHED;
;             PG8_LDA(At, 1, 1); PG8_STAGE(PG8_SB(1, 0), b3, voffB); PG8_STAGE(PG8_SB(1, 1), b3 + hstep, voffB); PG8_STAGE(PG8_SA(1, 0), a3, voffA);
;             PG8_WAIT_V(8); PG8_WAIT_L(0); PG8_BAR; PG8_MMA(1, 0, At, B0); PG8_MMA(1, 1, At, B1); PG8_BAR; PG8_SCHED;
	s_setprio 1
	s_waitcnt lgkmcnt(0)
	v_mfma_f32_16x16x32_bf16 v[138:141], v[114:117], v[184:187], v[138:141]
	v_mfma_f32_16x16x32_bf16 v[138:141], v[126:129], v[188:191], v[138:141]
	v_mfma_f32_16x16x32_bf16 v[110:113], v[126:129], v[196:199], v[110:113]
	v_mfma_f32_16x16x32_bf16 v[110:113], v[114:117], v[192:195], v[110:113]
	v_mfma_f32_16x16x32_bf16 v[94:97], v[114:117], v[200:203], v[94:97]
	v_mfma_f32_16x16x32_bf16 v[94:97], v[126:129], v[204:207], v[94:97]
	v_mfma_f32_16x16x32_bf16 v[78:81], v[126:129], v[212:215], v[78:81]
	v_mfma_f32_16x16x32_bf16 v[78:81], v[114:117], v[208:211], v[78:81]
	v_mfma_f32_16x16x32_bf16 v[74:77], v[130:133], v[208:211], v[74:77]
	v_mfma_f32_16x16x32_bf16 v[74:77], v[142:145], v[212:215], v[74:77]
	v_mfma_f32_16x16x32_bf16 v[90:93], v[142:145], v[204:207], v[90:93]
	v_mfma_f32_16x16x32_bf16 v[90:93], v[130:133], v[200:203], v[90:93]
	v_mfma_f32_16x16x32_bf16 v[106:109], v[130:133], v[192:195], v[106:109]
	v_mfma_f32_16x16x32_bf16 v[106:109], v[142:145], v[196:199], v[106:109]
	v_mfma_f32_16x16x32_bf16 v[134:137], v[142:145], v[188:191], v[134:137]
	v_mfma_f32_16x16x32_bf16 v[134:137], v[130:133], v[184:187], v[134:137]
	v_mfma_f32_16x16x32_bf16 v[122:125], v[146:149], v[184:187], v[122:125]
	v_mfma_f32_16x16x32_bf16 v[122:125], v[150:153], v[188:191], v[122:125]
	v_mfma_f32_16x16x32_bf16 v[102:105], v[150:153], v[196:199], v[102:105]
	v_mfma_f32_16x16x32_bf16 v[102:105], v[146:149], v[192:195], v[102:105]
	v_mfma_f32_16x16x32_bf16 v[86:89], v[146:149], v[200:203], v[86:89]
	v_mfma_f32_16x16x32_bf16 v[86:89], v[150:153], v[204:207], v[86:89]
	v_mfma_f32_16x16x32_bf16 v[70:73], v[150:153], v[212:215], v[70:73]
	v_mfma_f32_16x16x32_bf16 v[70:73], v[146:149], v[208:211], v[70:73]
	v_mfma_f32_16x16x32_bf16 v[66:69], v[174:177], v[208:211], v[66:69]
	v_mfma_f32_16x16x32_bf16 v[66:69], v[178:181], v[212:215], v[66:69]
	v_mfma_f32_16x16x32_bf16 v[82:85], v[178:181], v[204:207], v[82:85]
	v_mfma_f32_16x16x32_bf16 v[82:85], v[174:177], v[200:203], v[82:85]
	s_barrier
	s_setprio 2
	v_mfma_f32_16x16x32_bf16 v[98:101], v[174:177], v[192:195], v[98:101]
	v_mfma_f32_16x16x32_bf16 v[98:101], v[178:181], v[196:199], v[98:101]
	v_mfma_f32_16x16x32_bf16 v[118:121], v[178:181], v[188:191], v[118:121]
	v_mfma_f32_16x16x32_bf16 v[118:121], v[174:177], v[184:187], v[118:121]
	s_setprio 0
	s_nop 0
	s_add_i32 s39, s39, s55
	v_lshl_add_u64 v[218:219], v[162:163], 0, s[24:25]
	s_mov_b32 m0, s39
	ds_read_b128 v[184:187], v169 offset:49152
	ds_read_b128 v[188:191], v169 offset:50176
	ds_read_b128 v[192:195], v169 offset:51200
	ds_read_b128 v[196:199], v169 offset:52224
	ds_read_b128 v[200:203], v169 offset:53248
	ds_read_b128 v[204:207], v169 offset:54272
	ds_read_b128 v[208:211], v169 offset:55296
	ds_read_b128 v[212:215], v169 offset:56320
	global_load_lds_dwordx4 v[218:219], off
	v_lshl_add_u64 v[218:219], v[162:163], 0, s[26:27]
	s_add_i32 m0, s39, 0x2000
	s_add_i32 s39, s70, s55
	global_load_lds_dwordx4 v[218:219], off
	v_lshl_add_u64 v[218:219], v[162:163], 0, s[28:29]
	s_mov_b32 m0, s39
	v_lshl_add_u64 v[162:163], v[162:163], 0, s[30:31]
	global_load_lds_dwordx4 v[218:219], off
	s_add_i32 m0, s39, 0x2000
	s_nop 0
	global_load_lds_dwordx4 v[162:163], off
	v_lshl_add_u64 v[162:163], v[216:217], 0, s[24:25]
	s_mov_b32 m0, s62
	s_nop 0
	global_load_lds_dwordx4 v[162:163], off
	v_lshl_add_u64 v[162:163], v[216:217], 0, s[26:27]
	s_mov_b32 m0, s63
	s_nop 0
	global_load_lds_dwordx4 v[162:163], off
	s_waitcnt vmcnt(8)
	s_waitcnt lgkmcnt(0)
	s_barrier
	s_setprio 1
	s_waitcnt lgkmcnt(0)
	v_mfma_f32_16x16x32_bf16 v[62:65], v[114:117], v[184:187], v[62:65]
	v_mfma_f32_16x16x32_bf16 v[62:65], v[126:129], v[188:191], v[62:65]
	v_mfma_f32_16x16x32_bf16 v[46:49], v[126:129], v[196:199], v[46:49]
	v_mfma_f32_16x16x32_bf16 v[46:49], v[114:117], v[192:195], v[46:49]
	v_mfma_f32_16x16x32_bf16 v[30:33], v[114:117], v[200:203], v[30:33]
	v_mfma_f32_16x16x32_bf16 v[30:33], v[126:129], v[204:207], v[30:33]
	v_mfma_f32_16x16x32_bf16 v[14:17], v[126:129], v[212:215], v[14:17]
	v_mfma_f32_16x16x32_bf16 v[14:17], v[114:117], v[208:211], v[14:17]
	v_mfma_f32_16x16x32_bf16 v[10:13], v[130:133], v[208:211], v[10:13]
	v_mfma_f32_16x16x32_bf16 v[10:13], v[142:145], v[212:215], v[10:13]
	v_mfma_f32_16x16x32_bf16 v[26:29], v[142:145], v[204:207], v[26:29]
	v_mfma_f32_16x16x32_bf16 v[26:29], v[130:133], v[200:203], v[26:29]
	v_mfma_f32_16x16x32_bf16 v[42:45], v[130:133], v[192:195], v[42:45]
	v_mfma_f32_16x16x32_bf16 v[42:45], v[142:145], v[196:199], v[42:45]
	v_mfma_f32_16x16x32_bf16 v[58:61], v[142:145], v[188:191], v[58:61]
	v_mfma_f32_16x16x32_bf16 v[58:61], v[130:133], v[184:187], v[58:61]
	v_mfma_f32_16x16x32_bf16 v[54:57], v[146:149], v[184:187], v[54:57]
	v_mfma_f32_16x16x32_bf16 v[54:57], v[150:153], v[188:191], v[54:57]
	v_mfma_f32_16x16x32_bf16 v[38:41], v[150:153], v[196:199], v[38:41]
	v_mfma_f32_16x16x32_bf16 v[38:41], v[146:149], v[192:195], v[38:41]
	v_mfma_f32_16x16x32_bf16 v[22:25], v[146:149], v[200:203], v[22:25]
	v_mfma_f32_16x16x32_bf16 v[22:25], v[150:153], v[204:207], v[22:25]
	v_mfma_f32_16x16x32_bf16 v[6:9], v[150:153], v[212:215], v[6:9]
	v_mfma_f32_16x16x32_bf16 v[6:9], v[146:149], v[208:211], v[6:9]
	v_mfma_f32_16x16x32_bf16 v[2:5], v[174:177], v[208:211], v[2:5]
	v_mfma_f32_16x16x32_bf16 v[2:5], v[178:181], v[212:215], v[2:5]
	v_mfma_f32_16x16x32_bf16 v[18:21], v[178:181], v[204:207], v[18:21]
	v_mfma_f32_16x16x32_bf16 v[18:21], v[174:177], v[200:203], v[18:21]
	s_barrier
	s_setprio 2
	v_mfma_f32_16x16x32_bf16 v[34:37], v[174:177], v[192:195], v[34:37]
	v_mfma_f32_16x16x32_bf16 v[34:37], v[178:181], v[196:199], v[34:37]
	v_mfma_f32_16x16x32_bf16 v[50:53], v[178:181], v[188:191], v[50:53]
	v_mfma_f32_16x16x32_bf16 v[50:53], v[174:177], v[184:187], v[50:53]
	s_setprio 0
	s_add_u32 s68, s68, 0x1000
	s_addc_u32 s69, s69, 0
	s_add_u32 s11, s11, 0x1000
	s_addc_u32 s37, s37, 0
	s_cmp_ge_i32 s41, s79
	s_mov_b32 s39, s41
	s_cbranch_scc0 .LBB0_1533
	s_and_b64 vcc, exec, s[34:35]
	s_cbranch_vccnz .LBB0_1538
	s_lshl_b32 s11, s2, 8
	s_cmp_gt_i32 s2, 63
	s_mov_b64 s[68:69], -1
	s_cbranch_scc1 .LBB0_1539

; #define PG8_STAGE(bufoff, gbase, voff) do { if constexpr (!pg8_noload<Epi>::value) { _Pragma("unroll") for (int _i = 0; _i < 2; ++_i) \
;         __builtin_amdgcn_global_load_lds((const unsigned*)((const char*)(gbase) + (size_t)_i * pstep + (voff)[0]), (PG8_LAS unsigned*)(lds + (bufoff) + ldsw + _i * 8192), 16, 0, 0); } } while (0)
; #define PG8_LDA(dst, b, h) do { _Pragma("unroll") for (int m = 0; m < 4; ++m) _Pragma("unroll") for (int k = 0; k < 2; ++k) dst[m][k] = *(const PG8_LAS bf16x8*)(lds + PG8_SA(b, h) + aoff + m * 2048 + k * 1024); } while (0)
; #define PG8_LDB(dst, b, h) do { _Pragma("unroll") for (int n = 0; n < 2; ++n) _Pragma("unroll") for (int k = 0; k < 2; ++k) dst[n][k] = *(const PG8_LAS bf16x8*)(lds + PG8_SB(b, h) + boff + n * 2048 + k * 1024); } while (0)
; #define PG8_MMA(ai, bj, At, Bt) do { __builtin_amdgcn_s_setprio(1); _Pragma("unroll") for (int m = 0; m < 4; ++m) _Pragma("unroll") for (int n = 0; n < 2; ++n) _Pragma("unroll") for (int k = 0; k < 2; ++k) \
;         acc[ai][bj][m][n] = __builtin_amdgcn_mfma_f32_16x16x32_bf16(Bt[n][k], At[m][k], acc[ai][bj][m][n], 0, 0, 0); __builtin_amdgcn_s_setprio(0); } while (0)
; #define PG8_WAIT_V(n) asm volatile("s_waitcnt vmcnt(" #n ")" ::: "memory")
; #define PG8_WAIT_L(n) asm volatile("s_waitcnt lgkmcnt(" #n ")" ::: "memory")
; template <class Epi, class Sched, bool ALIGN_EPI = false, bool SP2 = false, bool ABLK = false>
; __device__ __forceinline__ void gemm_phase(PG8_LAS unsigned char* lds, const Gemm g, const Sched& S, const Epi& E) {
;     ...
;             const char* a1 = cA + (size_t)(t + 1) * kstep;
;             const char* a2 = last ? nA : cA + (size_t)(t + 2) * kstep; const char* b2 = last ? nB : cB + (size_t)(t + 2) * kstepB;
;             const char* a3 = a2 + kstep; const char* b3 = b2 + kstepB;
;             if (last && has_next) S.a_ready(nxt);
;             if constexpr (SP2) {
;             PG8_LDB(B0, 0, 0); PG8_LDB(B1, 0, 1); PG8_SCHED; PG8_LDA(At, 0, 0); PG8_STAGE(PG8_SA(1, 1), a1 + hstep, voffA);
;             PG8_WAIT_V(8); PG8_WAIT_L(0); PG8_BAR; PG8_MMA(0, 0, At, B0); PG8_MMA(0, 1, At, B1); PG8_BAR; PG8_SCHED;
;             PG8_LDA(At, 0, 1); PG8_STAGE(PG8_SB(0, 0), b2, voffB); PG8_STAGE(PG8_SB(0, 1), b2 + hstep, voffB); PG8_STAGE(PG8_SA(0, 0), a2, voffA);
;             PG8_WAIT_V(8); PG8_WAIT_L(0); PG8_BAR; PG8_MMA(1, 0, At, B0); PG8_MMA(1, 1, At, B1); PG8_BAR; PG8_SCHED;
.LBB0_1656:
	s_or_b64 exec, exec, s[82:83]
	s_barrier
	.p2align	6
.LBB0_1657:
	s_or_b32 s26, s94, 1
	s_lshl_b64 s[82:83], s[26:27], 11
	s_add_u32 s88, s74, s82
	v_add_u32_e32 v140, s12, v173
	s_addc_u32 s89, s75, s83
	s_add_i32 s26, s94, 2
	ds_read_b128 v[130:133], v140
	ds_read_b128 v[134:137], v140 offset:1024
	ds_read_b128 v[154:157], v140 offset:2048
	ds_read_b128 v[158:161], v140 offset:3072
	v_add_u32_e32 v140, s13, v173
	s_lshl_b64 s[90:91], s[26:27], 11
	ds_read_b128 v[162:165], v140
	ds_read_b128 v[166:169], v140 offset:1024
	ds_read_b128 v[184:187], v140 offset:2048
	ds_read_b128 v[188:191], v140 offset:3072
	s_add_u32 s92, s74, s90
	s_addc_u32 s93, s75, s91
	s_and_b64 s[82:83], s[80:81], exec
	s_cselect_b32 s83, s93, s3
	s_cselect_b32 s82, s92, s25
	s_add_u32 s90, s76, s90
	s_addc_u32 s91, s77, s91
	s_and_b64 s[80:81], s[80:81], exec
	s_cselect_b32 s81, s91, s65
	s_cselect_b32 s80, s90, s67
	v_lshl_add_u64 v[170:171], s[88:89], 0, v[138:139]
	v_lshl_add_u64 v[224:225], v[170:171], 0, s[20:21]
	s_add_i32 m0, s56, 0xc000
	ds_read_b128 v[192:195], v178
	ds_read_b128 v[196:199], v178 offset:1024
	ds_read_b128 v[200:203], v178 offset:2048
	ds_read_b128 v[204:207], v178 offset:3072
	ds_read_b128 v[208:211], v178 offset:4096
	ds_read_b128 v[212:215], v178 offset:5120
	ds_read_b128 v[216:219], v178 offset:6144
	ds_read_b128 v[220:223], v178 offset:7168
	global_load_lds_dwordx4 v[224:225], off
	v_lshl_add_u64 v[170:171], v[170:171], 0, s[22:23]
	s_add_i32 m0, s56, 0xe000
	s_nop 0
	global_load_lds_dwordx4 v[170:171], off
	s_waitcnt vmcnt(8)
	s_waitcnt lgkmcnt(0)
	s_barrier
	s_setprio 1
	s_waitcnt lgkmcnt(0)
	v_mfma_f32_16x16x32_bf16 v[126:129], v[130:133], v[192:195], v[126:129]
	v_mfma_f32_16x16x32_bf16 v[126:129], v[134:137], v[196:199], v[126:129]
	v_mfma_f32_16x16x32_bf16 v[110:113], v[134:137], v[204:207], v[110:113]
	v_mfma_f32_16x16x32_bf16 v[110:113], v[130:133], v[200:203], v[110:113]
	v_mfma_f32_16x16x32_bf16 v[94:97], v[130:133], v[208:211], v[94:97]
	v_mfma_f32_16x16x32_bf16 v[94:97], v[134:137], v[212:215], v[94:97]
	v_mfma_f32_16x16x32_bf16 v[78:81], v[134:137], v[220:223], v[78:81]
	v_mfma_f32_16x16x32_bf16 v[78:81], v[130:133], v[216:219], v[78:81]
	v_mfma_f32_16x16x32_bf16 v[74:77], v[154:157], v[216:219], v[74:77]
	v_mfma_f32_16x16x32_bf16 v[74:77], v[158:161], v[220:223], v[74:77]
	v_mfma_f32_16x16x32_bf16 v[90:93], v[158:161], v[212:215], v[90:93]
	v_mfma_f32_16x16x32_bf16 v[90:93], v[154:157], v[208:211], v[90:93]
	v_mfma_f32_16x16x32_bf16 v[106:109], v[154:157], v[200:203], v[106:109]
	v_mfma_f32_16x16x32_bf16 v[106:109], v[158:161], v[204:207], v[106:109]
	v_mfma_f32_16x16x32_bf16 v[122:125], v[158:161], v[196:199], v[122:125]
	v_mfma_f32_16x16x32_bf16 v[122:125], v[154:157], v[192:195], v[122:125]
	v_mfma_f32_16x16x32_bf16 v[118:121], v[162:165], v[192:195], v[118:121]
	v_mfma_f32_16x16x32_bf16 v[118:121], v[166:169], v[196:199], v[118:121]
	v_mfma_f32_16x16x32_bf16 v[102:105], v[166:169], v[204:207], v[102:105]
	v_mfma_f32_16x16x32_bf16 v[102:105], v[162:165], v[200:203], v[102:105]
	v_mfma_f32_16x16x32_bf16 v[86:89], v[162:165], v[208:211], v[86:89]
	v_mfma_f32_16x16x32_bf16 v[86:89], v[166:169], v[212:215], v[86:89]
	v_mfma_f32_16x16x32_bf16 v[70:73], v[166:169], v[220:223], v[70:73]
	v_mfma_f32_16x16x32_bf16 v[70:73], v[162:165], v[216:219], v[70:73]
	v_mfma_f32_16x16x32_bf16 v[66:69], v[184:187], v[216:219], v[66:69]
	v_mfma_f32_16x16x32_bf16 v[66:69], v[188:191], v[220:223], v[66:69]
	v_mfma_f32_16x16x32_bf16 v[82:85], v[188:191], v[212:215], v[82:85]
	v_mfma_f32_16x16x32_bf16 v[82:85], v[184:187], v[208:211], v[82:85]
	s_barrier
	s_setprio 2
	v_mfma_f32_16x16x32_bf16 v[98:101], v[184:187], v[200:203], v[98:101]
	v_mfma_f32_16x16x32_bf16 v[98:101], v[188:191], v[204:207], v[98:101]
	v_mfma_f32_16x16x32_bf16 v[114:117], v[188:191], v[196:199], v[114:117]
	v_mfma_f32_16x16x32_bf16 v[114:117], v[184:187], v[192:195], v[114:117]
	s_setprio 0
	s_nop 0
	v_lshl_add_u64 v[170:171], s[80:81], 0, v[138:139]
	s_add_i32 s80, s12, s55
	s_mov_b32 m0, s80
	ds_read_b128 v[192:195], v178 offset:16384
	ds_read_b128 v[196:199], v178 offset:17408
	ds_read_b128 v[200:203], v178 offset:18432
	ds_read_b128 v[204:207], v178 offset:19456
	ds_read_b128 v[208:211], v178 offset:20480
	ds_read_b128 v[212:215], v178 offset:21504
	ds_read_b128 v[216:219], v178 offset:22528
	ds_read_b128 v[220:223], v178 offset:23552
	global_load_lds_dwordx4 v[170:171], off
	v_lshl_add_u64 v[224:225], v[170:171], 0, s[18:19]
	s_add_i32 m0, s80, 0x2000
	s_add_i32 s80, s13, s55
	global_load_lds_dwordx4 v[224:225], off
	v_lshl_add_u64 v[224:225], v[170:171], 0, s[20:21]
	s_mov_b32 m0, s80
	s_nop 0
	global_load_lds_dwordx4 v[224:225], off
	v_lshl_add_u64 v[224:225], v[170:171], 0, s[22:23]
	s_add_i32 m0, s80, 0x2000
	s_nop 0
	global_load_lds_dwordx4 v[224:225], off
	v_lshl_add_u64 v[224:225], s[82:83], 0, v[138:139]
	s_mov_b32 m0, s56
	v_lshl_add_u64 v[226:227], v[224:225], 0, s[18:19]
	global_load_lds_dwordx4 v[224:225], off
	s_mov_b32 m0, s57
	s_nop 0
	global_load_lds_dwordx4 v[226:227], off
	s_waitcnt vmcnt(8)
	s_waitcnt lgkmcnt(0)
	s_barrier
; #define PG8_STAGE(bufoff, gbase, voff) do { if constexpr (!pg8_noload<Epi>::value) { _Pragma("unroll") for (int _i = 0; _i < 2; ++_i) \
;         __builtin_amdgcn_global_load_lds((const unsigned*)((const char*)(gbase) + (size_t)_i * pstep + (voff)[0]), (PG8_LAS unsigned*)(lds + (bufoff) + ldsw + _i * 8192), 16, 0, 0); } } while (0)
; #define PG8_LDA(dst, b, h) do { _Pragma("unroll") for (int m = 0; m < 4; ++m) _Pragma("unroll") for (int k = 0; k < 2; ++k) dst[m][k] = *(const PG8_LAS bf16x8*)(lds + PG8_SA(b, h) + aoff + m * 2048 + k * 1024); } while (0)
; #define PG8_LDB(dst, b, h) do { _Pragma("unroll") for (int n = 0; n < 2; ++n) _Pragma("unroll") for (int k = 0; k < 2; ++k) dst[n][k] = *(const PG8_LAS bf16x8*)(lds + PG8_SB(b, h) + boff + n * 2048 + k * 1024); } while (0)
; #define PG8_MMA(ai, bj, At, Bt) do { __builtin_amdgcn_s_setprio(1); _Pragma("unroll") for (int m = 0; m < 4; ++m) _Pragma("unroll") for (int n = 0; n < 2; ++n) _Pragma("unroll") for (int k = 0; k < 2; ++k) \
;         acc[ai][bj][m][n] = __builtin_amdgcn_mfma_f32_16x16x32_bf16(Bt[n][k], At[m][k], acc[ai][bj][m][n], 0, 0, 0); __builtin_amdgcn_s_setprio(0); } while (0)
; #define PG8_WAIT_V(n) asm volatile("s_waitcnt vmcnt(" #n ")" ::: "memory")
; #define PG8_WAIT_L(n) asm volatile("s_waitcnt lgkmcnt(" #n ")" ::: "memory")
; #define PG8_BAR __builtin_amdgcn_s_barrier()
; #define PG8_SCHED __builtin_amdgcn_sched_barrier(0)
; template <class Epi, class Sched, bool ALIGN_EPI = false, bool SP2 = false, bool ABLK = false>
; __device__ __forceinline__ void gemm_phase(PG8_LAS unsigned char* lds, const Gemm g, const Sched& S, const Epi& E) {
;     ...
;             PG8_LDB(B0, 0, 0); PG8_LDB(B1, 0, 1); PG8_SCHED; PG8_LDA(At, 0, 0); PG8_STAGE(PG8_SA(1, 1), a1 + hstep, voffA);
;             PG8_WAIT_V(8); PG8_WAIT_L(0); PG8_BAR; PG8_MMA(0, 0, At, B0); PG8_MMA(0, 1, At, B1); PG8_BAR; PG8_SCHED;
;             PG8_LDA(At, 0, 1); PG8_STAGE(PG8_SB(0, 0), b2, voffB); PG8_STAGE(PG8_SB(0, 1), b2 + hstep, voffB); PG8_STAGE(PG8_SA(0, 0), a2, voffA);
;             PG8_WAIT_V(8); PG8_WAIT_L(0); PG8_BAR; PG8_MMA(1, 0, At, B0); PG8_MMA(1, 1, At, B1); PG8_BAR; PG8_SCHED;
;             PG8_LDB(B0, 1, 0); PG8_LDB(B1, 1, 1); PG8_SCHED; PG8_LDA(At, 1, 0); PG8_STAGE(PG8_SA(0, 1), a2 + hstep, voffA);
;             PG8_WAIT_V(8); PG8_WAIT_L(0); PG8_BAR; PG8_MMA(0, 0, At, B0); PG8_MMA(0, 1, At, B1); PG8_BAR; PG8_SCHED;
	s_setprio 1
	s_waitcnt lgkmcnt(0)
	v_mfma_f32_16x16x32_bf16 v[62:65], v[130:133], v[192:195], v[62:65]
	v_mfma_f32_16x16x32_bf16 v[62:65], v[134:137], v[196:199], v[62:65]
	v_mfma_f32_16x16x32_bf16 v[46:49], v[134:137], v[204:207], v[46:49]
	v_mfma_f32_16x16x32_bf16 v[46:49], v[130:133], v[200:203], v[46:49]
	v_mfma_f32_16x16x32_bf16 v[30:33], v[130:133], v[208:211], v[30:33]
	v_mfma_f32_16x16x32_bf16 v[30:33], v[134:137], v[212:215], v[30:33]
	v_mfma_f32_16x16x32_bf16 v[14:17], v[134:137], v[220:223], v[14:17]
	v_mfma_f32_16x16x32_bf16 v[14:17], v[130:133], v[216:219], v[14:17]
	v_mfma_f32_16x16x32_bf16 v[10:13], v[154:157], v[216:219], v[10:13]
	v_mfma_f32_16x16x32_bf16 v[10:13], v[158:161], v[220:223], v[10:13]
	v_mfma_f32_16x16x32_bf16 v[26:29], v[158:161], v[212:215], v[26:29]
	v_mfma_f32_16x16x32_bf16 v[26:29], v[154:157], v[208:211], v[26:29]
	v_mfma_f32_16x16x32_bf16 v[42:45], v[154:157], v[200:203], v[42:45]
	v_mfma_f32_16x16x32_bf16 v[42:45], v[158:161], v[204:207], v[42:45]
	v_mfma_f32_16x16x32_bf16 v[58:61], v[158:161], v[196:199], v[58:61]
	v_mfma_f32_16x16x32_bf16 v[58:61], v[154:157], v[192:195], v[58:61]
	v_mfma_f32_16x16x32_bf16 v[54:57], v[162:165], v[192:195], v[54:57]
	v_mfma_f32_16x16x32_bf16 v[54:57], v[166:169], v[196:199], v[54:57]
	v_mfma_f32_16x16x32_bf16 v[38:41], v[166:169], v[204:207], v[38:41]
	v_mfma_f32_16x16x32_bf16 v[38:41], v[162:165], v[200:203], v[38:41]
	v_mfma_f32_16x16x32_bf16 v[22:25], v[162:165], v[208:211], v[22:25]
	v_mfma_f32_16x16x32_bf16 v[22:25], v[166:169], v[212:215], v[22:25]
	v_mfma_f32_16x16x32_bf16 v[6:9], v[166:169], v[220:223], v[6:9]
	v_mfma_f32_16x16x32_bf16 v[6:9], v[162:165], v[216:219], v[6:9]
	v_mfma_f32_16x16x32_bf16 v[2:5], v[184:187], v[216:219], v[2:5]
	v_mfma_f32_16x16x32_bf16 v[2:5], v[188:191], v[220:223], v[2:5]
	v_mfma_f32_16x16x32_bf16 v[18:21], v[188:191], v[212:215], v[18:21]
	v_mfma_f32_16x16x32_bf16 v[18:21], v[184:187], v[208:211], v[18:21]
	s_barrier
	s_setprio 2
	v_mfma_f32_16x16x32_bf16 v[34:37], v[184:187], v[200:203], v[34:37]
	v_mfma_f32_16x16x32_bf16 v[34:37], v[188:191], v[204:207], v[34:37]
	v_mfma_f32_16x16x32_bf16 v[50:53], v[188:191], v[196:199], v[50:53]
	v_mfma_f32_16x16x32_bf16 v[50:53], v[184:187], v[192:195], v[50:53]
	s_setprio 0
	s_nop 0
	s_add_i32 s80, 0, 0x18000
	v_add_u32_e32 v140, s80, v173
	s_add_i32 s81, 0, 0x1c000
	ds_read_b128 v[130:133], v140
	ds_read_b128 v[134:137], v140 offset:1024
	ds_read_b128 v[154:157], v140 offset:2048
	ds_read_b128 v[158:161], v140 offset:3072
	v_add_u32_e32 v140, s81, v173
	ds_read_b128 v[162:165], v140
	ds_read_b128 v[166:169], v140 offset:1024
	ds_read_b128 v[184:187], v140 offset:2048
	ds_read_b128 v[188:191], v140 offset:3072
	s_mov_b32 m0, s58
	v_lshl_add_u64 v[226:227], v[224:225], 0, s[20:21]
	ds_read_b128 v[192:195], v178 offset:32768
	ds_read_b128 v[196:199], v178 offset:33792
	ds_read_b128 v[200:203], v178 offset:34816
	ds_read_b128 v[204:207], v178 offset:35840
	ds_read_b128 v[208:211], v178 offset:36864
	ds_read_b128 v[212:215], v178 offset:37888
	ds_read_b128 v[216:219], v178 offset:38912
	ds_read_b128 v[220:223], v178 offset:39936
	global_load_lds_dwordx4 v[226:227], off
	v_lshl_add_u64 v[226:227], v[224:225], 0, s[22:23]
	s_mov_b32 m0, s59
	s_nop 0
	global_load_lds_dwordx4 v[226:227], off
	s_waitcnt vmcnt(8)
	s_waitcnt lgkmcnt(0)
	s_barrier
	s_setprio 1
	s_waitcnt lgkmcnt(0)
	v_mfma_f32_16x16x32_bf16 v[126:129], v[130:133], v[192:195], v[126:129]
	v_mfma_f32_16x16x32_bf16 v[126:129], v[134:137], v[196:199], v[126:129]
	v_mfma_f32_16x16x32_bf16 v[110:113], v[134:137], v[204:207], v[110:113]
	v_mfma_f32_16x16x32_bf16 v[110:113], v[130:133], v[200:203], v[110:113]
	v_mfma_f32_16x16x32_bf16 v[94:97], v[130:133], v[208:211], v[94:97]
	v_mfma_f32_16x16x32_bf16 v[94:97], v[134:137], v[212:215], v[94:97]
	v_mfma_f32_16x16x32_bf16 v[78:81], v[134:137], v[220:223], v[78:81]
	v_mfma_f32_16x16x32_bf16 v[78:81], v[130:133], v[216:219], v[78:81]
	v_mfma_f32_16x16x32_bf16 v[74:77], v[154:157], v[216:219], v[74:77]
	v_mfma_f32_16x16x32_bf16 v[74:77], v[158:161], v[220:223], v[74:77]
	v_mfma_f32_16x16x32_bf16 v[90:93], v[158:161], v[212:215], v[90:93]
	v_mfma_f32_16x16x32_bf16 v[90:93], v[154:157], v[208:211], v[90:93]
	v_mfma_f32_16x16x32_bf16 v[106:109], v[154:157], v[200:203], v[106:109]
	v_mfma_f32_16x16x32_bf16 v[106:109], v[158:161], v[204:207], v[106:109]
	v_mfma_f32_16x16x32_bf16 v[122:125], v[158:161], v[196:199], v[122:125]
	v_mfma_f32_16x16x32_bf16 v[122:125], v[154:157], v[192:195], v[122:125]
	v_mfma_f32_16x16x32_bf16 v[118:121], v[162:165], v[192:195], v[118:121]
	v_mfma_f32_16x16x32_bf16 v[118:121], v[166:169], v[196:199], v[118:121]
	v_mfma_f32_16x16x32_bf16 v[102:105], v[166:169], v[204:207], v[102:105]
	v_mfma_f32_16x16x32_bf16 v[102:105], v[162:165], v[200:203], v[102:105]
	v_mfma_f32_16x16x32_bf16 v[86:89], v[162:165], v[208:211], v[86:89]
	v_mfma_f32_16x16x32_bf16 v[86:89], v[166:169], v[212:215], v[86:89]
	v_mfma_f32_16x16x32_bf16 v[70:73], v[166:169], v[220:223], v[70:73]
	v_mfma_f32_16x16x32_bf16 v[70:73], v[162:165], v[216:219], v[70:73]
	v_mfma_f32_16x16x32_bf16 v[66:69], v[184:187], v[216:219], v[66:69]
	v_mfma_f32_16x16x32_bf16 v[66:69], v[188:191], v[220:223], v[66:69]
	v_mfma_f32_16x16x32_bf16 v[82:85], v[188:191], v[212:215], v[82:85]
	v_mfma_f32_16x16x32_bf16 v[82:85], v[184:187], v[208:211], v[82:85]
	s_barrier
; #define PG8_STAGE(bufoff, gbase, voff) do { if constexpr (!pg8_noload<Epi>::value) { _Pragma("unroll") for (int _i = 0; _i < 2; ++_i) \
;         __builtin_amdgcn_global_load_lds((const unsigned*)((const char*)(gbase) + (size_t)_i * pstep + (voff)[0]), (PG8_LAS unsigned*)(lds + (bufoff) + ldsw + _i * 8192), 16, 0, 0); } } while (0)
; #define PG8_LDA(dst, b, h) do { _Pragma("unroll") for (int m = 0; m < 4; ++m) _Pragma("unroll") for (int k = 0; k < 2; ++k) dst[m][k] = *(const PG8_LAS bf16x8*)(lds + PG8_SA(b, h) + aoff + m * 2048 + k * 1024); } while (0)
; #define PG8_MMA(ai, bj, At, Bt) do { __builtin_amdgcn_s_setprio(1); _Pragma("unroll") for (int m = 0; m < 4; ++m) _Pragma("unroll") for (int n = 0; n < 2; ++n) _Pragma("unroll") for (int k = 0; k < 2; ++k) \
;         acc[ai][bj][m][n] = __builtin_amdgcn_mfma_f32_16x16x32_bf16(Bt[n][k], At[m][k], acc[ai][bj][m][n], 0, 0, 0); __builtin_amdgcn_s_setprio(0); } while (0)
; #define PG8_WAIT_V(n) asm volatile("s_waitcnt vmcnt(" #n ")" ::: "memory")
; #define PG8_WAIT_L(n) asm volatile("s_waitcnt lgkmcnt(" #n ")" ::: "memory")
; #define PG8_BAR __builtin_amdgcn_s_barrier()
; #define PG8_SCHED __builtin_amdgcn_sched_barrier(0)
; template <class Epi, class Sched, bool ALIGN_EPI = false, bool SP2 = false, bool ABLK = false>
; __device__ __forceinline__ void gemm_phase(PG8_LAS unsigned char* lds, const Gemm g, const Sched& S, const Epi& E) {
;     ...
;             PG8_WAIT_V(8); PG8_WAIT_L(0); PG8_BAR; PG8_MMA(0, 0, At, B0); PG8_MMA(0, 1, At, B1); PG8_BAR; PG8_SCHED;
;             PG8_LDA(At, 1, 1); PG8_STAGE(PG8_SB(1, 0), b3, voffB); PG8_STAGE(PG8_SB(1, 1), b3 + hstep, voffB); PG8_STAGE(PG8_SA(1, 0), a3, voffA);
;             PG8_WAIT_V(8); PG8_WAIT_L(0); PG8_BAR; PG8_MMA(1, 0, At, B0); PG8_MMA(1, 1, At, B1); PG8_BAR; PG8_SCHED;
	s_setprio 2
	v_mfma_f32_16x16x32_bf16 v[98:101], v[184:187], v[200:203], v[98:101]
	v_mfma_f32_16x16x32_bf16 v[98:101], v[188:191], v[204:207], v[98:101]
	v_mfma_f32_16x16x32_bf16 v[114:117], v[188:191], v[196:199], v[114:117]
	v_mfma_f32_16x16x32_bf16 v[114:117], v[184:187], v[192:195], v[114:117]
	s_setprio 0
	s_nop 0
	s_add_i32 s80, s80, s55
	v_lshl_add_u64 v[226:227], v[170:171], 0, s[30:31]
	s_mov_b32 m0, s80
	ds_read_b128 v[192:195], v178 offset:49152
	ds_read_b128 v[196:199], v178 offset:50176
	ds_read_b128 v[200:203], v178 offset:51200
	ds_read_b128 v[204:207], v178 offset:52224
	ds_read_b128 v[208:211], v178 offset:53248
	ds_read_b128 v[212:215], v178 offset:54272
	ds_read_b128 v[216:219], v178 offset:55296
	ds_read_b128 v[220:223], v178 offset:56320
	global_load_lds_dwordx4 v[226:227], off
	v_lshl_add_u64 v[226:227], v[170:171], 0, s[34:35]
	s_add_i32 m0, s80, 0x2000
	s_add_i32 s80, s81, s55
	global_load_lds_dwordx4 v[226:227], off
	v_lshl_add_u64 v[226:227], v[170:171], 0, s[36:37]
	s_mov_b32 m0, s80
	v_lshl_add_u64 v[170:171], v[170:171], 0, s[38:39]
	global_load_lds_dwordx4 v[226:227], off
	s_add_i32 m0, s80, 0x2000
	s_nop 0
	global_load_lds_dwordx4 v[170:171], off
	v_lshl_add_u64 v[170:171], v[224:225], 0, s[30:31]
	s_mov_b32 m0, s63
	s_nop 0
	global_load_lds_dwordx4 v[170:171], off
	v_lshl_add_u64 v[170:171], v[224:225], 0, s[34:35]
	s_mov_b32 m0, s73
	s_nop 0
	global_load_lds_dwordx4 v[170:171], off
	s_waitcnt vmcnt(8)
	s_waitcnt lgkmcnt(0)
	s_barrier
	s_setprio 1
	s_waitcnt lgkmcnt(0)
	v_mfma_f32_16x16x32_bf16 v[62:65], v[130:133], v[192:195], v[62:65]
	v_mfma_f32_16x16x32_bf16 v[62:65], v[134:137], v[196:199], v[62:65]
	v_mfma_f32_16x16x32_bf16 v[46:49], v[134:137], v[204:207], v[46:49]
	v_mfma_f32_16x16x32_bf16 v[46:49], v[130:133], v[200:203], v[46:49]
	v_mfma_f32_16x16x32_bf16 v[30:33], v[130:133], v[208:211], v[30:33]
	v_mfma_f32_16x16x32_bf16 v[30:33], v[134:137], v[212:215], v[30:33]
	v_mfma_f32_16x16x32_bf16 v[14:17], v[134:137], v[220:223], v[14:17]
	v_mfma_f32_16x16x32_bf16 v[14:17], v[130:133], v[216:219], v[14:17]
	v_mfma_f32_16x16x32_bf16 v[10:13], v[154:157], v[216:219], v[10:13]
	v_mfma_f32_16x16x32_bf16 v[10:13], v[158:161], v[220:223], v[10:13]
	v_mfma_f32_16x16x32_bf16 v[26:29], v[158:161], v[212:215], v[26:29]
	v_mfma_f32_16x16x32_bf16 v[26:29], v[154:157], v[208:211], v[26:29]
	v_mfma_f32_16x16x32_bf16 v[42:45], v[154:157], v[200:203], v[42:45]
	v_mfma_f32_16x16x32_bf16 v[42:45], v[158:161], v[204:207], v[42:45]
	v_mfma_f32_16x16x32_bf16 v[58:61], v[158:161], v[196:199], v[58:61]
	v_mfma_f32_16x16x32_bf16 v[58:61], v[154:157], v[192:195], v[58:61]
	v_mfma_f32_16x16x32_bf16 v[54:57], v[162:165], v[192:195], v[54:57]
	v_mfma_f32_16x16x32_bf16 v[54:57], v[166:169], v[196:199], v[54:57]
	v_mfma_f32_16x16x32_bf16 v[38:41], v[166:169], v[204:207], v[38:41]
	v_mfma_f32_16x16x32_bf16 v[38:41], v[162:165], v[200:203], v[38:41]
	v_mfma_f32_16x16x32_bf16 v[22:25], v[162:165], v[208:211], v[22:25]
	v_mfma_f32_16x16x32_bf16 v[22:25], v[166:169], v[212:215], v[22:25]
	v_mfma_f32_16x16x32_bf16 v[6:9], v[166:169], v[220:223], v[6:9]
	v_mfma_f32_16x16x32_bf16 v[6:9], v[162:165], v[216:219], v[6:9]
	v_mfma_f32_16x16x32_bf16 v[2:5], v[184:187], v[216:219], v[2:5]
	v_mfma_f32_16x16x32_bf16 v[2:5], v[188:191], v[220:223], v[2:5]
	v_mfma_f32_16x16x32_bf16 v[18:21], v[188:191], v[212:215], v[18:21]
	v_mfma_f32_16x16x32_bf16 v[18:21], v[184:187], v[208:211], v[18:21]
	s_barrier
	s_setprio 2
	v_mfma_f32_16x16x32_bf16 v[34:37], v[184:187], v[200:203], v[34:37]
	v_mfma_f32_16x16x32_bf16 v[34:37], v[188:191], v[204:207], v[34:37]
	v_mfma_f32_16x16x32_bf16 v[50:53], v[188:191], v[196:199], v[50:53]
	v_mfma_f32_16x16x32_bf16 v[50:53], v[184:187], v[192:195], v[50:53]
	s_setprio 0
	s_cmp_gt_u32 s94, 29
	s_mov_b32 s94, s26
	s_cbranch_scc1 .LBB0_1669

; #define PG8_STAGE(bufoff, gbase, voff) do { if constexpr (!pg8_noload<Epi>::value) { _Pragma("unroll") for (int _i = 0; _i < 2; ++_i) \
;         __builtin_amdgcn_global_load_lds((const unsigned*)((const char*)(gbase) + (size_t)_i * pstep + (voff)[0]), (PG8_LAS unsigned*)(lds + (bufoff) + ldsw + _i * 8192), 16, 0, 0); } } while (0)
; #define PG8_LDA(dst, b, h) do { _Pragma("unroll") for (int m = 0; m < 4; ++m) _Pragma("unroll") for (int k = 0; k < 2; ++k) dst[m][k] = *(const PG8_LAS bf16x8*)(lds + PG8_SA(b, h) + aoff + m * 2048 + k * 1024); } while (0)
; #define PG8_LDB(dst, b, h) do { _Pragma("unroll") for (int n = 0; n < 2; ++n) _Pragma("unroll") for (int k = 0; k < 2; ++k) dst[n][k] = *(const PG8_LAS bf16x8*)(lds + PG8_SB(b, h) + boff + n * 2048 + k * 1024); } while (0)
; #define PG8_MMA(ai, bj, At, Bt) do { __builtin_amdgcn_s_setprio(1); _Pragma("unroll") for (int m = 0; m < 4; ++m) _Pragma("unroll") for (int n = 0; n < 2; ++n) _Pragma("unroll") for (int k = 0; k < 2; ++k) \
;         acc[ai][bj][m][n] = __builtin_amdgcn_mfma_f32_16x16x32_bf16(Bt[n][k], At[m][k], acc[ai][bj][m][n], 0, 0, 0); __builtin_amdgcn_s_setprio(0); } while (0)
; #define PG8_WAIT_V(n) asm volatile("s_waitcnt vmcnt(" #n ")" ::: "memory")
; #define PG8_WAIT_L(n) asm volatile("s_waitcnt lgkmcnt(" #n ")" ::: "memory")
; template <class Epi, class Sched, bool ALIGN_EPI = false, bool SP2 = false, bool ABLK = false>
; __device__ __forceinline__ void gemm_phase(PG8_LAS unsigned char* lds, const Gemm g, const Sched& S, const Epi& E) {
;     ...
;             PG8_LDB(B0, 0, 0); PG8_LDB(B1, 0, 1); PG8_SCHED; PG8_LDA(At, 0, 0); PG8_STAGE(PG8_SA(1, 1), a1 + hstep, voffA);
;             PG8_WAIT_V(8); PG8_WAIT_L(0); PG8_BAR; PG8_MMA(0, 0, At, B0); PG8_MMA(0, 1, At, B1); PG8_BAR; PG8_SCHED;
;             PG8_LDA(At, 0, 1); PG8_STAGE(PG8_SB(0, 0), b2, voffB); PG8_STAGE(PG8_SB(0, 1), b2 + hstep, voffB); PG8_STAGE(PG8_SA(0, 0), a2, voffA);
;             PG8_WAIT_V(8); PG8_WAIT_L(0); PG8_BAR; PG8_MMA(1, 0, At, B0); PG8_MMA(1, 1, At, B1); PG8_BAR; PG8_SCHED;
;     ...
; #pragma unroll
;         for (int a = 0; a < 2; ++a)
; #pragma unroll
;             for (int b = 0; b < 2; ++b)
; #pragma unroll
;                 for (int m = 0; m < 4; ++m)
; #pragma unroll
;                     for (int n = 0; n < 2; ++n) acc[a][b][m][n] = (f32x4){0.f, 0.f, 0.f, 0.f};
;         cur = nxt; cA = nA; cB = nB; ++ui; nt = cur.nt;
.LBB0_1996:
	s_add_i32 s3, s75, -2
	s_add_u32 s52, s52, 0x80800
	s_addc_u32 s53, s53, 0
	s_add_u32 s11, s62, 0x1000
	v_mov_b32_e32 v2, 0
	s_addc_u32 s39, s63, 0
	s_mov_b32 s41, 0
	s_waitcnt lgkmcnt(0)
	v_mov_b32_e32 v3, v2
	v_mov_b32_e32 v4, v2
	v_mov_b32_e32 v5, v2
	v_mov_b32_e32 v6, v2
	v_mov_b32_e32 v7, v2
	v_mov_b32_e32 v8, v2
	v_mov_b32_e32 v9, v2
	v_mov_b32_e32 v18, v2
	v_mov_b32_e32 v19, v2
	v_mov_b32_e32 v20, v2
	v_mov_b32_e32 v21, v2
	v_mov_b32_e32 v22, v2
	v_mov_b32_e32 v23, v2
	v_mov_b32_e32 v24, v2
	v_mov_b32_e32 v25, v2
	v_mov_b32_e32 v34, v2
	v_mov_b32_e32 v35, v2
	v_mov_b32_e32 v36, v2
	v_mov_b32_e32 v37, v2
	v_mov_b32_e32 v38, v2
	v_mov_b32_e32 v39, v2
	v_mov_b32_e32 v40, v2
	v_mov_b32_e32 v41, v2
	v_mov_b32_e32 v50, v2
	v_mov_b32_e32 v51, v2
	v_mov_b32_e32 v52, v2
	v_mov_b32_e32 v53, v2
	v_mov_b32_e32 v54, v2
	v_mov_b32_e32 v55, v2
	v_mov_b32_e32 v56, v2
	v_mov_b32_e32 v57, v2
	v_mov_b32_e32 v10, v2
	v_mov_b32_e32 v11, v2
	v_mov_b32_e32 v12, v2
	v_mov_b32_e32 v13, v2
	v_mov_b32_e32 v14, v2
	v_mov_b32_e32 v15, v2
	v_mov_b32_e32 v16, v2
	v_mov_b32_e32 v17, v2
	v_mov_b32_e32 v26, v2
	v_mov_b32_e32 v27, v2
	v_mov_b32_e32 v28, v2
	v_mov_b32_e32 v29, v2
	v_mov_b32_e32 v30, v2
	v_mov_b32_e32 v31, v2
	v_mov_b32_e32 v32, v2
	v_mov_b32_e32 v33, v2
	v_mov_b32_e32 v42, v2
	v_mov_b32_e32 v43, v2
	v_mov_b32_e32 v44, v2
	v_mov_b32_e32 v45, v2
	v_mov_b32_e32 v46, v2
	v_mov_b32_e32 v47, v2
	v_mov_b32_e32 v48, v2
	v_mov_b32_e32 v49, v2
	v_mov_b32_e32 v58, v2
	v_mov_b32_e32 v59, v2
	v_mov_b32_e32 v60, v2
	v_mov_b32_e32 v61, v2
	v_mov_b32_e32 v62, v2
	v_mov_b32_e32 v63, v2
	v_mov_b32_e32 v64, v2
	v_mov_b32_e32 v65, v2
	v_mov_b32_e32 v66, v2
	v_mov_b32_e32 v67, v2
	v_mov_b32_e32 v68, v2
	v_mov_b32_e32 v69, v2
	v_mov_b32_e32 v70, v2
	v_mov_b32_e32 v71, v2
	v_mov_b32_e32 v72, v2
	v_mov_b32_e32 v73, v2
	v_mov_b32_e32 v82, v2
	v_mov_b32_e32 v83, v2
	v_mov_b32_e32 v84, v2
	v_mov_b32_e32 v85, v2
	v_mov_b32_e32 v86, v2
	v_mov_b32_e32 v87, v2
	v_mov_b32_e32 v88, v2
	v_mov_b32_e32 v89, v2
	v_mov_b32_e32 v98, v2
	v_mov_b32_e32 v99, v2
	v_mov_b32_e32 v100, v2
	v_mov_b32_e32 v101, v2
	v_mov_b32_e32 v102, v2
	v_mov_b32_e32 v103, v2
	v_mov_b32_e32 v104, v2
	v_mov_b32_e32 v105, v2
	v_mov_b32_e32 v114, v2
	v_mov_b32_e32 v115, v2
	v_mov_b32_e32 v116, v2
	v_mov_b32_e32 v117, v2
	v_mov_b32_e32 v118, v2
	v_mov_b32_e32 v119, v2
	v_mov_b32_e32 v120, v2
	v_mov_b32_e32 v121, v2
	v_mov_b32_e32 v74, v2
	v_mov_b32_e32 v75, v2
	v_mov_b32_e32 v76, v2
	v_mov_b32_e32 v77, v2
	v_mov_b32_e32 v78, v2
	v_mov_b32_e32 v79, v2
	v_mov_b32_e32 v80, v2
	v_mov_b32_e32 v81, v2
	v_mov_b32_e32 v90, v2
	v_mov_b32_e32 v91, v2
	v_mov_b32_e32 v92, v2
	v_mov_b32_e32 v93, v2
	v_mov_b32_e32 v94, v2
	v_mov_b32_e32 v95, v2
	v_mov_b32_e32 v96, v2
	v_mov_b32_e32 v97, v2
	v_mov_b32_e32 v106, v2
	v_mov_b32_e32 v107, v2
	v_mov_b32_e32 v108, v2
	v_mov_b32_e32 v109, v2
	v_mov_b32_e32 v110, v2
	v_mov_b32_e32 v111, v2
	v_mov_b32_e32 v112, v2
	v_mov_b32_e32 v113, v2
	v_mov_b32_e32 v122, v2
	v_mov_b32_e32 v123, v2
	v_mov_b32_e32 v124, v2
	v_mov_b32_e32 v125, v2
	v_mov_b32_e32 v126, v2
	v_mov_b32_e32 v127, v2
	v_mov_b32_e32 v128, v2
	v_mov_b32_e32 v129, v2
	.p2align	6
.LBB0_1997:
	s_nop 0
	ds_read_b128 v[130:133], v175
	ds_read_b128 v[134:137], v175 offset:1024
	ds_read_b128 v[138:141], v175 offset:2048
	ds_read_b128 v[142:145], v175 offset:3072
	ds_read_b128 v[146:149], v176
	ds_read_b128 v[150:153], v176 offset:1024
	ds_read_b128 v[154:157], v176 offset:2048
	ds_read_b128 v[158:161], v176 offset:3072
	s_add_i32 s43, s41, 2
	s_add_u32 s62, s52, 0xfff80800
	s_addc_u32 s63, s53, -1
	s_cmp_eq_u32 s3, s41
	s_cselect_b32 s63, s45, s63
	s_cselect_b32 s62, s44, s62
	s_cselect_b32 s77, s47, s39
	s_cselect_b32 s76, s46, s11
	v_lshl_add_u64 v[170:171], s[52:53], 0, v[166:167]
	s_add_i32 m0, s49, 0xc000
	ds_read_b128 v[184:187], v177
	ds_read_b128 v[188:191], v177 offset:1024
	ds_read_b128 v[192:195], v177 offset:2048
	ds_read_b128 v[196:199], v177 offset:3072
	ds_read_b128 v[200:203], v177 offset:4096
	ds_read_b128 v[204:207], v177 offset:5120
	ds_read_b128 v[208:211], v177 offset:6144
	ds_read_b128 v[212:215], v177 offset:7168
	global_load_lds_dwordx4 v[170:171], off
	v_lshl_add_u64 v[170:171], v[170:171], 0, s[12:13]
	s_add_i32 m0, s49, 0xe000
	s_nop 0
	global_load_lds_dwordx4 v[170:171], off
	s_waitcnt vmcnt(8)
	s_waitcnt lgkmcnt(0)
	s_barrier
	s_setprio 1
	s_waitcnt lgkmcnt(0)
	v_mfma_f32_16x16x32_bf16 v[126:129], v[130:133], v[184:187], v[126:129]
	v_mfma_f32_16x16x32_bf16 v[126:129], v[134:137], v[188:191], v[126:129]
	v_mfma_f32_16x16x32_bf16 v[110:113], v[134:137], v[196:199], v[110:113]
	v_mfma_f32_16x16x32_bf16 v[110:113], v[130:133], v[192:195], v[110:113]
	v_mfma_f32_16x16x32_bf16 v[94:97], v[130:133], v[200:203], v[94:97]
	v_mfma_f32_16x16x32_bf16 v[94:97], v[134:137], v[204:207], v[94:97]
	v_mfma_f32_16x16x32_bf16 v[78:81], v[134:137], v[212:215], v[78:81]
	v_mfma_f32_16x16x32_bf16 v[78:81], v[130:133], v[208:211], v[78:81]
	v_mfma_f32_16x16x32_bf16 v[74:77], v[138:141], v[208:211], v[74:77]
	v_mfma_f32_16x16x32_bf16 v[74:77], v[142:145], v[212:215], v[74:77]
	v_mfma_f32_16x16x32_bf16 v[90:93], v[142:145], v[204:207], v[90:93]
	v_mfma_f32_16x16x32_bf16 v[90:93], v[138:141], v[200:203], v[90:93]
	v_mfma_f32_16x16x32_bf16 v[106:109], v[138:141], v[192:195], v[106:109]
	v_mfma_f32_16x16x32_bf16 v[106:109], v[142:145], v[196:199], v[106:109]
	v_mfma_f32_16x16x32_bf16 v[122:125], v[142:145], v[188:191], v[122:125]
	v_mfma_f32_16x16x32_bf16 v[122:125], v[138:141], v[184:187], v[122:125]
	v_mfma_f32_16x16x32_bf16 v[118:121], v[146:149], v[184:187], v[118:121]
	v_mfma_f32_16x16x32_bf16 v[118:121], v[150:153], v[188:191], v[118:121]
	v_mfma_f32_16x16x32_bf16 v[102:105], v[150:153], v[196:199], v[102:105]
	v_mfma_f32_16x16x32_bf16 v[102:105], v[146:149], v[192:195], v[102:105]
	v_mfma_f32_16x16x32_bf16 v[86:89], v[146:149], v[200:203], v[86:89]
	v_mfma_f32_16x16x32_bf16 v[86:89], v[150:153], v[204:207], v[86:89]
	v_mfma_f32_16x16x32_bf16 v[70:73], v[150:153], v[212:215], v[70:73]
	v_mfma_f32_16x16x32_bf16 v[70:73], v[146:149], v[208:211], v[70:73]
	v_mfma_f32_16x16x32_bf16 v[66:69], v[154:157], v[208:211], v[66:69]
	v_mfma_f32_16x16x32_bf16 v[66:69], v[158:161], v[212:215], v[66:69]
	v_mfma_f32_16x16x32_bf16 v[82:85], v[158:161], v[204:207], v[82:85]
	v_mfma_f32_16x16x32_bf16 v[82:85], v[154:157], v[200:203], v[82:85]
	s_barrier
; #define PG8_STAGE(bufoff, gbase, voff) do { if constexpr (!pg8_noload<Epi>::value) { _Pragma("unroll") for (int _i = 0; _i < 2; ++_i) \
;         __builtin_amdgcn_global_load_lds((const unsigned*)((const char*)(gbase) + (size_t)_i * pstep + (voff)[0]), (PG8_LAS unsigned*)(lds + (bufoff) + ldsw + _i * 8192), 16, 0, 0); } } while (0)
; #define PG8_LDA(dst, b, h) do { _Pragma("unroll") for (int m = 0; m < 4; ++m) _Pragma("unroll") for (int k = 0; k < 2; ++k) dst[m][k] = *(const PG8_LAS bf16x8*)(lds + PG8_SA(b, h) + aoff + m * 2048 + k * 1024); } while (0)
; #define PG8_LDB(dst, b, h) do { _Pragma("unroll") for (int n = 0; n < 2; ++n) _Pragma("unroll") for (int k = 0; k < 2; ++k) dst[n][k] = *(const PG8_LAS bf16x8*)(lds + PG8_SB(b, h) + boff + n * 2048 + k * 1024); } while (0)
; #define PG8_MMA(ai, bj, At, Bt) do { __builtin_amdgcn_s_setprio(1); _Pragma("unroll") for (int m = 0; m < 4; ++m) _Pragma("unroll") for (int n = 0; n < 2; ++n) _Pragma("unroll") for (int k = 0; k < 2; ++k) \
;         acc[ai][bj][m][n] = __builtin_amdgcn_mfma_f32_16x16x32_bf16(Bt[n][k], At[m][k], acc[ai][bj][m][n], 0, 0, 0); __builtin_amdgcn_s_setprio(0); } while (0)
; #define PG8_WAIT_V(n) asm volatile("s_waitcnt vmcnt(" #n ")" ::: "memory")
; #define PG8_WAIT_L(n) asm volatile("s_waitcnt lgkmcnt(" #n ")" ::: "memory")
; #define PG8_BAR __builtin_amdgcn_s_barrier()
; #define PG8_SCHED __builtin_amdgcn_sched_barrier(0)
; template <class Epi, class Sched, bool ALIGN_EPI = false, bool SP2 = false, bool ABLK = false>
; __device__ __forceinline__ void gemm_phase(PG8_LAS unsigned char* lds, const Gemm g, const Sched& S, const Epi& E) {
;     ...
;             PG8_LDB(B0, 0, 0); PG8_LDB(B1, 0, 1); PG8_SCHED; PG8_LDA(At, 0, 0); PG8_STAGE(PG8_SA(1, 1), a1 + hstep, voffA);
;             PG8_WAIT_V(8); PG8_WAIT_L(0); PG8_BAR; PG8_MMA(0, 0, At, B0); PG8_MMA(0, 1, At, B1); PG8_BAR; PG8_SCHED;
;             PG8_LDA(At, 0, 1); PG8_STAGE(PG8_SB(0, 0), b2, voffB); PG8_STAGE(PG8_SB(0, 1), b2 + hstep, voffB); PG8_STAGE(PG8_SA(0, 0), a2, voffA);
;             PG8_WAIT_V(8); PG8_WAIT_L(0); PG8_BAR; PG8_MMA(1, 0, At, B0); PG8_MMA(1, 1, At, B1); PG8_BAR; PG8_SCHED;
;             PG8_LDB(B0, 1, 0); PG8_LDB(B1, 1, 1); PG8_SCHED; PG8_LDA(At, 1, 0); PG8_STAGE(PG8_SA(0, 1), a2 + hstep, voffA);
;             PG8_WAIT_V(8); PG8_WAIT_L(0); PG8_BAR; PG8_MMA(0, 0, At, B0); PG8_MMA(0, 1, At, B1); PG8_BAR; PG8_SCHED;
	s_setprio 2
	v_mfma_f32_16x16x32_bf16 v[98:101], v[154:157], v[192:195], v[98:101]
	v_mfma_f32_16x16x32_bf16 v[98:101], v[158:161], v[196:199], v[98:101]
	v_mfma_f32_16x16x32_bf16 v[114:117], v[158:161], v[188:191], v[114:117]
	v_mfma_f32_16x16x32_bf16 v[114:117], v[154:157], v[184:187], v[114:117]
	s_setprio 0
	s_nop 0
	s_add_i32 s41, s70, s57
	v_lshl_add_u64 v[170:171], s[76:77], 0, v[162:163]
	s_mov_b32 m0, s41
	ds_read_b128 v[184:187], v177 offset:16384
	ds_read_b128 v[188:191], v177 offset:17408
	ds_read_b128 v[192:195], v177 offset:18432
	ds_read_b128 v[196:199], v177 offset:19456
	ds_read_b128 v[200:203], v177 offset:20480
	ds_read_b128 v[204:207], v177 offset:21504
	ds_read_b128 v[208:211], v177 offset:22528
	ds_read_b128 v[212:215], v177 offset:23552
	global_load_lds_dwordx4 v[170:171], off
	v_lshl_add_u64 v[216:217], v[170:171], 0, s[12:13]
	s_add_i32 m0, s41, 0x2000
	s_add_i32 s41, s71, s57
	global_load_lds_dwordx4 v[216:217], off
	v_lshl_add_u64 v[216:217], v[170:171], 0, s[14:15]
	s_mov_b32 m0, s41
	s_nop 0
	global_load_lds_dwordx4 v[216:217], off
	v_lshl_add_u64 v[216:217], v[170:171], 0, s[16:17]
	s_add_i32 m0, s41, 0x2000
	s_nop 0
	global_load_lds_dwordx4 v[216:217], off
	v_lshl_add_u64 v[216:217], s[62:63], 0, v[162:163]
	s_mov_b32 m0, s49
	v_lshl_add_u64 v[218:219], v[216:217], 0, s[12:13]
	global_load_lds_dwordx4 v[216:217], off
	s_mov_b32 m0, s58
	s_nop 0
	global_load_lds_dwordx4 v[218:219], off
	s_waitcnt vmcnt(8)
	s_waitcnt lgkmcnt(0)
	s_barrier
	s_setprio 1
	s_waitcnt lgkmcnt(0)
	v_mfma_f32_16x16x32_bf16 v[62:65], v[130:133], v[184:187], v[62:65]
	v_mfma_f32_16x16x32_bf16 v[62:65], v[134:137], v[188:191], v[62:65]
	v_mfma_f32_16x16x32_bf16 v[46:49], v[134:137], v[196:199], v[46:49]
	v_mfma_f32_16x16x32_bf16 v[46:49], v[130:133], v[192:195], v[46:49]
	v_mfma_f32_16x16x32_bf16 v[30:33], v[130:133], v[200:203], v[30:33]
	v_mfma_f32_16x16x32_bf16 v[30:33], v[134:137], v[204:207], v[30:33]
	v_mfma_f32_16x16x32_bf16 v[14:17], v[134:137], v[212:215], v[14:17]
	v_mfma_f32_16x16x32_bf16 v[14:17], v[130:133], v[208:211], v[14:17]
	v_mfma_f32_16x16x32_bf16 v[10:13], v[138:141], v[208:211], v[10:13]
	v_mfma_f32_16x16x32_bf16 v[10:13], v[142:145], v[212:215], v[10:13]
	v_mfma_f32_16x16x32_bf16 v[26:29], v[142:145], v[204:207], v[26:29]
	v_mfma_f32_16x16x32_bf16 v[26:29], v[138:141], v[200:203], v[26:29]
	v_mfma_f32_16x16x32_bf16 v[42:45], v[138:141], v[192:195], v[42:45]
	v_mfma_f32_16x16x32_bf16 v[42:45], v[142:145], v[196:199], v[42:45]
	v_mfma_f32_16x16x32_bf16 v[58:61], v[142:145], v[188:191], v[58:61]
	v_mfma_f32_16x16x32_bf16 v[58:61], v[138:141], v[184:187], v[58:61]
	v_mfma_f32_16x16x32_bf16 v[54:57], v[146:149], v[184:187], v[54:57]
	v_mfma_f32_16x16x32_bf16 v[54:57], v[150:153], v[188:191], v[54:57]
	v_mfma_f32_16x16x32_bf16 v[38:41], v[150:153], v[196:199], v[38:41]
	v_mfma_f32_16x16x32_bf16 v[38:41], v[146:149], v[192:195], v[38:41]
	v_mfma_f32_16x16x32_bf16 v[22:25], v[146:149], v[200:203], v[22:25]
	v_mfma_f32_16x16x32_bf16 v[22:25], v[150:153], v[204:207], v[22:25]
	v_mfma_f32_16x16x32_bf16 v[6:9], v[150:153], v[212:215], v[6:9]
	v_mfma_f32_16x16x32_bf16 v[6:9], v[146:149], v[208:211], v[6:9]
	v_mfma_f32_16x16x32_bf16 v[2:5], v[154:157], v[208:211], v[2:5]
	v_mfma_f32_16x16x32_bf16 v[2:5], v[158:161], v[212:215], v[2:5]
	v_mfma_f32_16x16x32_bf16 v[18:21], v[158:161], v[204:207], v[18:21]
	v_mfma_f32_16x16x32_bf16 v[18:21], v[154:157], v[200:203], v[18:21]
	s_barrier
	s_setprio 2
	v_mfma_f32_16x16x32_bf16 v[34:37], v[154:157], v[192:195], v[34:37]
	v_mfma_f32_16x16x32_bf16 v[34:37], v[158:161], v[196:199], v[34:37]
	v_mfma_f32_16x16x32_bf16 v[50:53], v[158:161], v[188:191], v[50:53]
	v_mfma_f32_16x16x32_bf16 v[50:53], v[154:157], v[184:187], v[50:53]
	s_setprio 0
	s_nop 0
	s_add_i32 s41, 0, 0x18000
	s_add_i32 s62, 0, 0x1c000
	v_add_u32_e32 v142, s41, v1
	v_add_u32_e32 v158, s62, v1
	ds_read_b128 v[130:133], v142
	ds_read_b128 v[134:137], v142 offset:1024
	ds_read_b128 v[138:141], v142 offset:2048
	ds_read_b128 v[142:145], v142 offset:3072
	ds_read_b128 v[146:149], v158
	ds_read_b128 v[150:153], v158 offset:1024
	ds_read_b128 v[154:157], v158 offset:2048
	ds_read_b128 v[158:161], v158 offset:3072
	s_mov_b32 m0, s59
	v_lshl_add_u64 v[218:219], v[216:217], 0, s[14:15]
	ds_read_b128 v[184:187], v177 offset:32768
	ds_read_b128 v[188:191], v177 offset:33792
	ds_read_b128 v[192:195], v177 offset:34816
	ds_read_b128 v[196:199], v177 offset:35840
	ds_read_b128 v[200:203], v177 offset:36864
	ds_read_b128 v[204:207], v177 offset:37888
	ds_read_b128 v[208:211], v177 offset:38912
	ds_read_b128 v[212:215], v177 offset:39936
	global_load_lds_dwordx4 v[218:219], off
	v_lshl_add_u64 v[218:219], v[216:217], 0, s[16:17]
	s_mov_b32 m0, s60
	s_nop 0
	global_load_lds_dwordx4 v[218:219], off
	s_waitcnt vmcnt(8)
	s_waitcnt lgkmcnt(0)
	s_barrier
; #define PG8_STAGE(bufoff, gbase, voff) do { if constexpr (!pg8_noload<Epi>::value) { _Pragma("unroll") for (int _i = 0; _i < 2; ++_i) \
;         __builtin_amdgcn_global_load_lds((const unsigned*)((const char*)(gbase) + (size_t)_i * pstep + (voff)[0]), (PG8_LAS unsigned*)(lds + (bufoff) + ldsw + _i * 8192), 16, 0, 0); } } while (0)
; #define PG8_LDA(dst, b, h) do { _Pragma("unroll") for (int m = 0; m < 4; ++m) _Pragma("unroll") for (int k = 0; k < 2; ++k) dst[m][k] = *(const PG8_LAS bf16x8*)(lds + PG8_SA(b, h) + aoff + m * 2048 + k * 1024); } while (0)
; #define PG8_MMA(ai, bj, At, Bt) do { __builtin_amdgcn_s_setprio(1); _Pragma("unroll") for (int m = 0; m < 4; ++m) _Pragma("unroll") for (int n = 0; n < 2; ++n) _Pragma("unroll") for (int k = 0; k < 2; ++k) \
;         acc[ai][bj][m][n] = __builtin_amdgcn_mfma_f32_16x16x32_bf16(Bt[n][k], At[m][k], acc[ai][bj][m][n], 0, 0, 0); __builtin_amdgcn_s_setprio(0); } while (0)
; #define PG8_WAIT_V(n) asm volatile("s_waitcnt vmcnt(" #n ")" ::: "memory")
; #define PG8_WAIT_L(n) asm volatile("s_waitcnt lgkmcnt(" #n ")" ::: "memory")
; #define PG8_BAR __builtin_amdgcn_s_barrier()
; #define PG8_SCHED __builtin_amdgcn_sched_barrier(0)
; template <class Epi, class Sched, bool ALIGN_EPI = false, bool SP2 = false, bool ABLK = false>
; __device__ __forceinline__ void gemm_phase(PG8_LAS unsigned char* lds, const Gemm g, const Sched& S, const Epi& E) {
;     ...
;             PG8_WAIT_V(8); PG8_WAIT_L(0); PG8_BAR; PG8_MMA(0, 0, At, B0); PG8_MMA(0, 1, At, B1); PG8_BAR; PG8_SCHED;
;             PG8_LDA(At, 1, 1); PG8_STAGE(PG8_SB(1, 0), b3, voffB); PG8_STAGE(PG8_SB(1, 1), b3 + hstep, voffB); PG8_STAGE(PG8_SA(1, 0), a3, voffA);
;             PG8_WAIT_V(8); PG8_WAIT_L(0); PG8_BAR; PG8_MMA(1, 0, At, B0); PG8_MMA(1, 1, At, B1); PG8_BAR; PG8_SCHED;
	s_setprio 1
	s_waitcnt lgkmcnt(0)
	v_mfma_f32_16x16x32_bf16 v[126:129], v[130:133], v[184:187], v[126:129]
	v_mfma_f32_16x16x32_bf16 v[126:129], v[134:137], v[188:191], v[126:129]
	v_mfma_f32_16x16x32_bf16 v[110:113], v[134:137], v[196:199], v[110:113]
	v_mfma_f32_16x16x32_bf16 v[110:113], v[130:133], v[192:195], v[110:113]
	v_mfma_f32_16x16x32_bf16 v[94:97], v[130:133], v[200:203], v[94:97]
	v_mfma_f32_16x16x32_bf16 v[94:97], v[134:137], v[204:207], v[94:97]
	v_mfma_f32_16x16x32_bf16 v[78:81], v[134:137], v[212:215], v[78:81]
	v_mfma_f32_16x16x32_bf16 v[78:81], v[130:133], v[208:211], v[78:81]
	v_mfma_f32_16x16x32_bf16 v[74:77], v[138:141], v[208:211], v[74:77]
	v_mfma_f32_16x16x32_bf16 v[74:77], v[142:145], v[212:215], v[74:77]
	v_mfma_f32_16x16x32_bf16 v[90:93], v[142:145], v[204:207], v[90:93]
	v_mfma_f32_16x16x32_bf16 v[90:93], v[138:141], v[200:203], v[90:93]
	v_mfma_f32_16x16x32_bf16 v[106:109], v[138:141], v[192:195], v[106:109]
	v_mfma_f32_16x16x32_bf16 v[106:109], v[142:145], v[196:199], v[106:109]
	v_mfma_f32_16x16x32_bf16 v[122:125], v[142:145], v[188:191], v[122:125]
	v_mfma_f32_16x16x32_bf16 v[122:125], v[138:141], v[184:187], v[122:125]
	v_mfma_f32_16x16x32_bf16 v[118:121], v[146:149], v[184:187], v[118:121]
	v_mfma_f32_16x16x32_bf16 v[118:121], v[150:153], v[188:191], v[118:121]
	v_mfma_f32_16x16x32_bf16 v[102:105], v[150:153], v[196:199], v[102:105]
	v_mfma_f32_16x16x32_bf16 v[102:105], v[146:149], v[192:195], v[102:105]
	v_mfma_f32_16x16x32_bf16 v[86:89], v[146:149], v[200:203], v[86:89]
	v_mfma_f32_16x16x32_bf16 v[86:89], v[150:153], v[204:207], v[86:89]
	v_mfma_f32_16x16x32_bf16 v[70:73], v[150:153], v[212:215], v[70:73]
	v_mfma_f32_16x16x32_bf16 v[70:73], v[146:149], v[208:211], v[70:73]
	v_mfma_f32_16x16x32_bf16 v[66:69], v[154:157], v[208:211], v[66:69]
	v_mfma_f32_16x16x32_bf16 v[66:69], v[158:161], v[212:215], v[66:69]
	v_mfma_f32_16x16x32_bf16 v[82:85], v[158:161], v[204:207], v[82:85]
	v_mfma_f32_16x16x32_bf16 v[82:85], v[154:157], v[200:203], v[82:85]
	s_barrier
	s_setprio 2
	v_mfma_f32_16x16x32_bf16 v[98:101], v[154:157], v[192:195], v[98:101]
	v_mfma_f32_16x16x32_bf16 v[98:101], v[158:161], v[196:199], v[98:101]
	v_mfma_f32_16x16x32_bf16 v[114:117], v[158:161], v[188:191], v[114:117]
	v_mfma_f32_16x16x32_bf16 v[114:117], v[154:157], v[184:187], v[114:117]
	s_setprio 0
	s_nop 0
	s_add_i32 s41, s41, s57
	v_lshl_add_u64 v[218:219], v[170:171], 0, s[24:25]
	s_mov_b32 m0, s41
	ds_read_b128 v[184:187], v177 offset:49152
	ds_read_b128 v[188:191], v177 offset:50176
	ds_read_b128 v[192:195], v177 offset:51200
	ds_read_b128 v[196:199], v177 offset:52224
	ds_read_b128 v[200:203], v177 offset:53248
	ds_read_b128 v[204:207], v177 offset:54272
	ds_read_b128 v[208:211], v177 offset:55296
	ds_read_b128 v[212:215], v177 offset:56320
	global_load_lds_dwordx4 v[218:219], off
	v_lshl_add_u64 v[218:219], v[170:171], 0, s[26:27]
	s_add_i32 m0, s41, 0x2000
	s_add_i32 s41, s62, s57
	global_load_lds_dwordx4 v[218:219], off
	v_lshl_add_u64 v[218:219], v[170:171], 0, s[28:29]
	s_mov_b32 m0, s41
	v_lshl_add_u64 v[170:171], v[170:171], 0, s[30:31]
	global_load_lds_dwordx4 v[218:219], off
	s_add_i32 m0, s41, 0x2000
	s_nop 0
	global_load_lds_dwordx4 v[170:171], off
	v_lshl_add_u64 v[170:171], v[216:217], 0, s[24:25]
	s_mov_b32 m0, s65
	s_nop 0
	global_load_lds_dwordx4 v[170:171], off
	v_lshl_add_u64 v[170:171], v[216:217], 0, s[26:27]
	s_mov_b32 m0, s66
	s_nop 0
	global_load_lds_dwordx4 v[170:171], off
	s_waitcnt vmcnt(8)
	s_waitcnt lgkmcnt(0)
	s_barrier
	s_setprio 1
	s_waitcnt lgkmcnt(0)
	v_mfma_f32_16x16x32_bf16 v[62:65], v[130:133], v[184:187], v[62:65]
	v_mfma_f32_16x16x32_bf16 v[62:65], v[134:137], v[188:191], v[62:65]
	v_mfma_f32_16x16x32_bf16 v[46:49], v[134:137], v[196:199], v[46:49]
	v_mfma_f32_16x16x32_bf16 v[46:49], v[130:133], v[192:195], v[46:49]
	v_mfma_f32_16x16x32_bf16 v[30:33], v[130:133], v[200:203], v[30:33]
	v_mfma_f32_16x16x32_bf16 v[30:33], v[134:137], v[204:207], v[30:33]
	v_mfma_f32_16x16x32_bf16 v[14:17], v[134:137], v[212:215], v[14:17]
	v_mfma_f32_16x16x32_bf16 v[14:17], v[130:133], v[208:211], v[14:17]
	v_mfma_f32_16x16x32_bf16 v[10:13], v[138:141], v[208:211], v[10:13]
	v_mfma_f32_16x16x32_bf16 v[10:13], v[142:145], v[212:215], v[10:13]
	v_mfma_f32_16x16x32_bf16 v[26:29], v[142:145], v[204:207], v[26:29]
	v_mfma_f32_16x16x32_bf16 v[26:29], v[138:141], v[200:203], v[26:29]
	v_mfma_f32_16x16x32_bf16 v[42:45], v[138:141], v[192:195], v[42:45]
	v_mfma_f32_16x16x32_bf16 v[42:45], v[142:145], v[196:199], v[42:45]
	v_mfma_f32_16x16x32_bf16 v[58:61], v[142:145], v[188:191], v[58:61]
	v_mfma_f32_16x16x32_bf16 v[58:61], v[138:141], v[184:187], v[58:61]
	v_mfma_f32_16x16x32_bf16 v[54:57], v[146:149], v[184:187], v[54:57]
	v_mfma_f32_16x16x32_bf16 v[54:57], v[150:153], v[188:191], v[54:57]
	v_mfma_f32_16x16x32_bf16 v[38:41], v[150:153], v[196:199], v[38:41]
	v_mfma_f32_16x16x32_bf16 v[38:41], v[146:149], v[192:195], v[38:41]
	v_mfma_f32_16x16x32_bf16 v[22:25], v[146:149], v[200:203], v[22:25]
	v_mfma_f32_16x16x32_bf16 v[22:25], v[150:153], v[204:207], v[22:25]
	v_mfma_f32_16x16x32_bf16 v[6:9], v[150:153], v[212:215], v[6:9]
	v_mfma_f32_16x16x32_bf16 v[6:9], v[146:149], v[208:211], v[6:9]
	v_mfma_f32_16x16x32_bf16 v[2:5], v[154:157], v[208:211], v[2:5]
	v_mfma_f32_16x16x32_bf16 v[2:5], v[158:161], v[212:215], v[2:5]
	v_mfma_f32_16x16x32_bf16 v[18:21], v[158:161], v[204:207], v[18:21]
	v_mfma_f32_16x16x32_bf16 v[18:21], v[154:157], v[200:203], v[18:21]
	s_barrier
	s_setprio 2
	v_mfma_f32_16x16x32_bf16 v[34:37], v[154:157], v[192:195], v[34:37]
	v_mfma_f32_16x16x32_bf16 v[34:37], v[158:161], v[196:199], v[34:37]
	v_mfma_f32_16x16x32_bf16 v[50:53], v[158:161], v[188:191], v[50:53]
	v_mfma_f32_16x16x32_bf16 v[50:53], v[154:157], v[184:187], v[50:53]
	s_setprio 0
	s_add_u32 s52, s52, 0x1000
	s_addc_u32 s53, s53, 0
	s_add_u32 s11, s11, 0x1000
	s_addc_u32 s39, s39, 0
	s_cmp_ge_i32 s43, s75
	s_mov_b32 s41, s43
	s_cbranch_scc0 .LBB0_1997
	s_and_b64 vcc, exec, s[34:35]
	s_cbranch_vccnz .LBB0_2002
	s_lshl_b32 s11, s2, 8
	s_cmp_gt_i32 s2, 63
	s_mov_b64 s[52:53], -1
	s_cbranch_scc1 .LBB0_2003

; #define PG8_STAGE(bufoff, gbase, voff) do { if constexpr (!pg8_noload<Epi>::value) { _Pragma("unroll") for (int _i = 0; _i < 2; ++_i) \
;         __builtin_amdgcn_global_load_lds((const unsigned*)((const char*)(gbase) + (size_t)_i * pstep + (voff)[0]), (PG8_LAS unsigned*)(lds + (bufoff) + ldsw + _i * 8192), 16, 0, 0); } } while (0)
; #define PG8_LDA(dst, b, h) do { _Pragma("unroll") for (int m = 0; m < 4; ++m) _Pragma("unroll") for (int k = 0; k < 2; ++k) dst[m][k] = *(const PG8_LAS bf16x8*)(lds + PG8_SA(b, h) + aoff + m * 2048 + k * 1024); } while (0)
; #define PG8_LDB(dst, b, h) do { _Pragma("unroll") for (int n = 0; n < 2; ++n) _Pragma("unroll") for (int k = 0; k < 2; ++k) dst[n][k] = *(const PG8_LAS bf16x8*)(lds + PG8_SB(b, h) + boff + n * 2048 + k * 1024); } while (0)
; #define PG8_MMA(ai, bj, At, Bt) do { __builtin_amdgcn_s_setprio(1); _Pragma("unroll") for (int m = 0; m < 4; ++m) _Pragma("unroll") for (int n = 0; n < 2; ++n) _Pragma("unroll") for (int k = 0; k < 2; ++k) \
;         acc[ai][bj][m][n] = __builtin_amdgcn_mfma_f32_16x16x32_bf16(Bt[n][k], At[m][k], acc[ai][bj][m][n], 0, 0, 0); __builtin_amdgcn_s_setprio(0); } while (0)
; #define PG8_WAIT_V(n) asm volatile("s_waitcnt vmcnt(" #n ")" ::: "memory")
; #define PG8_WAIT_L(n) asm volatile("s_waitcnt lgkmcnt(" #n ")" ::: "memory")
; template <class Epi, class Sched, bool ALIGN_EPI = false, bool SP2 = false, bool ABLK = false>
; __device__ __forceinline__ void gemm_phase(PG8_LAS unsigned char* lds, const Gemm g, const Sched& S, const Epi& E) {
;     ...
;             const char* a1 = cA + (size_t)(t + 1) * kstep;
;             const char* a2 = last ? nA : cA + (size_t)(t + 2) * kstep; const char* b2 = last ? nB : cB + (size_t)(t + 2) * kstepB;
;             const char* a3 = a2 + kstep; const char* b3 = b2 + kstepB;
;             if (last && has_next) S.a_ready(nxt);
;             if constexpr (SP2) {
;             PG8_LDB(B0, 0, 0); PG8_LDB(B1, 0, 1); PG8_SCHED; PG8_LDA(At, 0, 0); PG8_STAGE(PG8_SA(1, 1), a1 + hstep, voffA);
;             PG8_WAIT_V(8); PG8_WAIT_L(0); PG8_BAR; PG8_MMA(0, 0, At, B0); PG8_MMA(0, 1, At, B1); PG8_BAR; PG8_SCHED;
;             PG8_LDA(At, 0, 1); PG8_STAGE(PG8_SB(0, 0), b2, voffB); PG8_STAGE(PG8_SB(0, 1), b2 + hstep, voffB); PG8_STAGE(PG8_SA(0, 0), a2, voffA);
;             PG8_WAIT_V(8); PG8_WAIT_L(0); PG8_BAR; PG8_MMA(1, 0, At, B0); PG8_MMA(1, 1, At, B1); PG8_BAR; PG8_SCHED;
.LBB0_2118:
	s_or_b64 exec, exec, s[94:95]
	s_barrier
	.p2align	6
.LBB0_2119:
	s_or_b32 s30, s59, 1
	s_lshl_b64 s[14:15], s[30:31], 11
	s_add_u32 s14, s82, s14
	v_add_u32_e32 v133, s71, v148
	s_addc_u32 s15, s83, s15
	s_add_i32 s30, s59, 2
	ds_read_b128 v[144:147], v133
	ds_read_b128 v[184:187], v133 offset:1024
	ds_read_b128 v[188:191], v133 offset:2048
	ds_read_b128 v[192:195], v133 offset:3072
	v_add_u32_e32 v133, s73, v148
	s_lshl_b64 s[34:35], s[30:31], 11
	ds_read_b128 v[196:199], v133
	ds_read_b128 v[200:203], v133 offset:1024
	ds_read_b128 v[204:207], v133 offset:2048
	ds_read_b128 v[208:211], v133 offset:3072
	s_add_u32 s96, s82, s34
	s_addc_u32 s97, s83, s35
	s_and_b64 s[94:95], s[92:93], exec
	s_cselect_b32 s95, s97, s77
	s_cselect_b32 s94, s96, s28
	s_add_u32 s96, s88, s34
	s_addc_u32 s97, s89, s35
	s_and_b64 s[34:35], s[92:93], exec
	s_cselect_b32 s35, s97, s29
	s_cselect_b32 s34, s96, s75
	v_lshl_add_u64 v[180:181], s[14:15], 0, v[130:131]
	v_lshl_add_u64 v[244:245], v[180:181], 0, s[24:25]
	s_add_i32 m0, s17, 0xc000
	ds_read_b128 v[212:215], v168
	ds_read_b128 v[216:219], v168 offset:1024
	ds_read_b128 v[220:223], v168 offset:2048
	ds_read_b128 v[224:227], v168 offset:3072
	ds_read_b128 v[228:231], v168 offset:4096
	ds_read_b128 v[232:235], v168 offset:5120
	ds_read_b128 v[236:239], v168 offset:6144
	ds_read_b128 v[240:243], v168 offset:7168
	global_load_lds_dwordx4 v[244:245], off
	v_lshl_add_u64 v[180:181], v[180:181], 0, s[26:27]
	s_add_i32 m0, s17, 0xe000
	s_nop 0
	global_load_lds_dwordx4 v[180:181], off
	s_waitcnt vmcnt(8)
	s_waitcnt lgkmcnt(0)
	s_barrier
	s_setprio 1
	s_waitcnt lgkmcnt(0)
	v_mfma_f32_16x16x32_bf16 v[126:129], v[144:147], v[212:215], v[126:129]
	v_mfma_f32_16x16x32_bf16 v[126:129], v[184:187], v[216:219], v[126:129]
	v_mfma_f32_16x16x32_bf16 v[110:113], v[184:187], v[224:227], v[110:113]
	v_mfma_f32_16x16x32_bf16 v[110:113], v[144:147], v[220:223], v[110:113]
	v_mfma_f32_16x16x32_bf16 v[94:97], v[144:147], v[228:231], v[94:97]
	v_mfma_f32_16x16x32_bf16 v[94:97], v[184:187], v[232:235], v[94:97]
	v_mfma_f32_16x16x32_bf16 v[78:81], v[184:187], v[240:243], v[78:81]
	v_mfma_f32_16x16x32_bf16 v[78:81], v[144:147], v[236:239], v[78:81]
	v_mfma_f32_16x16x32_bf16 v[74:77], v[188:191], v[236:239], v[74:77]
	v_mfma_f32_16x16x32_bf16 v[74:77], v[192:195], v[240:243], v[74:77]
	v_mfma_f32_16x16x32_bf16 v[90:93], v[192:195], v[232:235], v[90:93]
	v_mfma_f32_16x16x32_bf16 v[90:93], v[188:191], v[228:231], v[90:93]
	v_mfma_f32_16x16x32_bf16 v[106:109], v[188:191], v[220:223], v[106:109]
	v_mfma_f32_16x16x32_bf16 v[106:109], v[192:195], v[224:227], v[106:109]
	v_mfma_f32_16x16x32_bf16 v[122:125], v[192:195], v[216:219], v[122:125]
	v_mfma_f32_16x16x32_bf16 v[122:125], v[188:191], v[212:215], v[122:125]
	v_mfma_f32_16x16x32_bf16 v[118:121], v[196:199], v[212:215], v[118:121]
	v_mfma_f32_16x16x32_bf16 v[118:121], v[200:203], v[216:219], v[118:121]
	v_mfma_f32_16x16x32_bf16 v[102:105], v[200:203], v[224:227], v[102:105]
	v_mfma_f32_16x16x32_bf16 v[102:105], v[196:199], v[220:223], v[102:105]
	v_mfma_f32_16x16x32_bf16 v[86:89], v[196:199], v[228:231], v[86:89]
	v_mfma_f32_16x16x32_bf16 v[86:89], v[200:203], v[232:235], v[86:89]
	v_mfma_f32_16x16x32_bf16 v[70:73], v[200:203], v[240:243], v[70:73]
	v_mfma_f32_16x16x32_bf16 v[70:73], v[196:199], v[236:239], v[70:73]
	v_mfma_f32_16x16x32_bf16 v[66:69], v[204:207], v[236:239], v[66:69]
	v_mfma_f32_16x16x32_bf16 v[66:69], v[208:211], v[240:243], v[66:69]
	v_mfma_f32_16x16x32_bf16 v[82:85], v[208:211], v[232:235], v[82:85]
	v_mfma_f32_16x16x32_bf16 v[82:85], v[204:207], v[228:231], v[82:85]
	s_barrier
	s_setprio 2
	v_mfma_f32_16x16x32_bf16 v[98:101], v[204:207], v[220:223], v[98:101]
	v_mfma_f32_16x16x32_bf16 v[98:101], v[208:211], v[224:227], v[98:101]
	v_mfma_f32_16x16x32_bf16 v[114:117], v[208:211], v[216:219], v[114:117]
	v_mfma_f32_16x16x32_bf16 v[114:117], v[204:207], v[212:215], v[114:117]
	s_setprio 0
	s_nop 0
	s_add_i32 s14, s71, s3
	v_lshl_add_u64 v[180:181], s[34:35], 0, v[130:131]
	s_mov_b32 m0, s14
	ds_read_b128 v[212:215], v168 offset:16384
	ds_read_b128 v[216:219], v168 offset:17408
	ds_read_b128 v[220:223], v168 offset:18432
	ds_read_b128 v[224:227], v168 offset:19456
	ds_read_b128 v[228:231], v168 offset:20480
	ds_read_b128 v[232:235], v168 offset:21504
	ds_read_b128 v[236:239], v168 offset:22528
	ds_read_b128 v[240:243], v168 offset:23552
	global_load_lds_dwordx4 v[180:181], off
	v_lshl_add_u64 v[244:245], v[180:181], 0, s[22:23]
	s_add_i32 m0, s14, 0x2000
	s_add_i32 s14, s73, s3
	global_load_lds_dwordx4 v[244:245], off
	v_lshl_add_u64 v[244:245], v[180:181], 0, s[24:25]
	s_mov_b32 m0, s14
	s_nop 0
	global_load_lds_dwordx4 v[244:245], off
	v_lshl_add_u64 v[244:245], v[180:181], 0, s[26:27]
	s_add_i32 m0, s14, 0x2000
	s_nop 0
	global_load_lds_dwordx4 v[244:245], off
	v_lshl_add_u64 v[244:245], s[94:95], 0, v[130:131]
	s_mov_b32 m0, s17
	v_lshl_add_u64 v[246:247], v[244:245], 0, s[22:23]
	global_load_lds_dwordx4 v[244:245], off
	s_mov_b32 m0, s56
	s_nop 0
	global_load_lds_dwordx4 v[246:247], off
	s_waitcnt vmcnt(8)
	s_waitcnt lgkmcnt(0)
	s_barrier
; #define PG8_STAGE(bufoff, gbase, voff) do { if constexpr (!pg8_noload<Epi>::value) { _Pragma("unroll") for (int _i = 0; _i < 2; ++_i) \
;         __builtin_amdgcn_global_load_lds((const unsigned*)((const char*)(gbase) + (size_t)_i * pstep + (voff)[0]), (PG8_LAS unsigned*)(lds + (bufoff) + ldsw + _i * 8192), 16, 0, 0); } } while (0)
; #define PG8_LDA(dst, b, h) do { _Pragma("unroll") for (int m = 0; m < 4; ++m) _Pragma("unroll") for (int k = 0; k < 2; ++k) dst[m][k] = *(const PG8_LAS bf16x8*)(lds + PG8_SA(b, h) + aoff + m * 2048 + k * 1024); } while (0)
; #define PG8_LDB(dst, b, h) do { _Pragma("unroll") for (int n = 0; n < 2; ++n) _Pragma("unroll") for (int k = 0; k < 2; ++k) dst[n][k] = *(const PG8_LAS bf16x8*)(lds + PG8_SB(b, h) + boff + n * 2048 + k * 1024); } while (0)
; #define PG8_MMA(ai, bj, At, Bt) do { __builtin_amdgcn_s_setprio(1); _Pragma("unroll") for (int m = 0; m < 4; ++m) _Pragma("unroll") for (int n = 0; n < 2; ++n) _Pragma("unroll") for (int k = 0; k < 2; ++k) \
;         acc[ai][bj][m][n] = __builtin_amdgcn_mfma_f32_16x16x32_bf16(Bt[n][k], At[m][k], acc[ai][bj][m][n], 0, 0, 0); __builtin_amdgcn_s_setprio(0); } while (0)
; #define PG8_WAIT_V(n) asm volatile("s_waitcnt vmcnt(" #n ")" ::: "memory")
; #define PG8_WAIT_L(n) asm volatile("s_waitcnt lgkmcnt(" #n ")" ::: "memory")
; #define PG8_BAR __builtin_amdgcn_s_barrier()
; #define PG8_SCHED __builtin_amdgcn_sched_barrier(0)
; template <class Epi, class Sched, bool ALIGN_EPI = false, bool SP2 = false, bool ABLK = false>
; __device__ __forceinline__ void gemm_phase(PG8_LAS unsigned char* lds, const Gemm g, const Sched& S, const Epi& E) {
;     ...
;             PG8_LDB(B0, 0, 0); PG8_LDB(B1, 0, 1); PG8_SCHED; PG8_LDA(At, 0, 0); PG8_STAGE(PG8_SA(1, 1), a1 + hstep, voffA);
;             PG8_WAIT_V(8); PG8_WAIT_L(0); PG8_BAR; PG8_MMA(0, 0, At, B0); PG8_MMA(0, 1, At, B1); PG8_BAR; PG8_SCHED;
;             PG8_LDA(At, 0, 1); PG8_STAGE(PG8_SB(0, 0), b2, voffB); PG8_STAGE(PG8_SB(0, 1), b2 + hstep, voffB); PG8_STAGE(PG8_SA(0, 0), a2, voffA);
;             PG8_WAIT_V(8); PG8_WAIT_L(0); PG8_BAR; PG8_MMA(1, 0, At, B0); PG8_MMA(1, 1, At, B1); PG8_BAR; PG8_SCHED;
;             PG8_LDB(B0, 1, 0); PG8_LDB(B1, 1, 1); PG8_SCHED; PG8_LDA(At, 1, 0); PG8_STAGE(PG8_SA(0, 1), a2 + hstep, voffA);
;             PG8_WAIT_V(8); PG8_WAIT_L(0); PG8_BAR; PG8_MMA(0, 0, At, B0); PG8_MMA(0, 1, At, B1); PG8_BAR; PG8_SCHED;
	s_setprio 1
	s_waitcnt lgkmcnt(0)
	v_mfma_f32_16x16x32_bf16 v[62:65], v[144:147], v[212:215], v[62:65]
	v_mfma_f32_16x16x32_bf16 v[62:65], v[184:187], v[216:219], v[62:65]
	v_mfma_f32_16x16x32_bf16 v[46:49], v[184:187], v[224:227], v[46:49]
	v_mfma_f32_16x16x32_bf16 v[46:49], v[144:147], v[220:223], v[46:49]
	v_mfma_f32_16x16x32_bf16 v[30:33], v[144:147], v[228:231], v[30:33]
	v_mfma_f32_16x16x32_bf16 v[30:33], v[184:187], v[232:235], v[30:33]
	v_mfma_f32_16x16x32_bf16 v[14:17], v[184:187], v[240:243], v[14:17]
	v_mfma_f32_16x16x32_bf16 v[14:17], v[144:147], v[236:239], v[14:17]
	v_mfma_f32_16x16x32_bf16 v[10:13], v[188:191], v[236:239], v[10:13]
	v_mfma_f32_16x16x32_bf16 v[10:13], v[192:195], v[240:243], v[10:13]
	v_mfma_f32_16x16x32_bf16 v[26:29], v[192:195], v[232:235], v[26:29]
	v_mfma_f32_16x16x32_bf16 v[26:29], v[188:191], v[228:231], v[26:29]
	v_mfma_f32_16x16x32_bf16 v[42:45], v[188:191], v[220:223], v[42:45]
	v_mfma_f32_16x16x32_bf16 v[42:45], v[192:195], v[224:227], v[42:45]
	v_mfma_f32_16x16x32_bf16 v[58:61], v[192:195], v[216:219], v[58:61]
	v_mfma_f32_16x16x32_bf16 v[58:61], v[188:191], v[212:215], v[58:61]
	v_mfma_f32_16x16x32_bf16 v[54:57], v[196:199], v[212:215], v[54:57]
	v_mfma_f32_16x16x32_bf16 v[54:57], v[200:203], v[216:219], v[54:57]
	v_mfma_f32_16x16x32_bf16 v[38:41], v[200:203], v[224:227], v[38:41]
	v_mfma_f32_16x16x32_bf16 v[38:41], v[196:199], v[220:223], v[38:41]
	v_mfma_f32_16x16x32_bf16 v[22:25], v[196:199], v[228:231], v[22:25]
	v_mfma_f32_16x16x32_bf16 v[22:25], v[200:203], v[232:235], v[22:25]
	v_mfma_f32_16x16x32_bf16 v[6:9], v[200:203], v[240:243], v[6:9]
	v_mfma_f32_16x16x32_bf16 v[6:9], v[196:199], v[236:239], v[6:9]
	v_mfma_f32_16x16x32_bf16 v[2:5], v[204:207], v[236:239], v[2:5]
	v_mfma_f32_16x16x32_bf16 v[2:5], v[208:211], v[240:243], v[2:5]
	v_mfma_f32_16x16x32_bf16 v[18:21], v[208:211], v[232:235], v[18:21]
	v_mfma_f32_16x16x32_bf16 v[18:21], v[204:207], v[228:231], v[18:21]
	s_barrier
	s_setprio 2
	v_mfma_f32_16x16x32_bf16 v[34:37], v[204:207], v[220:223], v[34:37]
	v_mfma_f32_16x16x32_bf16 v[34:37], v[208:211], v[224:227], v[34:37]
	v_mfma_f32_16x16x32_bf16 v[50:53], v[208:211], v[216:219], v[50:53]
	v_mfma_f32_16x16x32_bf16 v[50:53], v[204:207], v[212:215], v[50:53]
	s_setprio 0
	s_nop 0
	s_add_i32 s14, 0, 0x18000
	v_add_u32_e32 v133, s14, v148
	s_add_i32 s15, 0, 0x1c000
	ds_read_b128 v[144:147], v133
	ds_read_b128 v[184:187], v133 offset:1024
	ds_read_b128 v[188:191], v133 offset:2048
	ds_read_b128 v[192:195], v133 offset:3072
	v_add_u32_e32 v133, s15, v148
	ds_read_b128 v[196:199], v133
	ds_read_b128 v[200:203], v133 offset:1024
	ds_read_b128 v[204:207], v133 offset:2048
	ds_read_b128 v[208:211], v133 offset:3072
	s_mov_b32 m0, s57
	v_lshl_add_u64 v[246:247], v[244:245], 0, s[24:25]
	ds_read_b128 v[212:215], v168 offset:32768
	ds_read_b128 v[216:219], v168 offset:33792
	ds_read_b128 v[220:223], v168 offset:34816
	ds_read_b128 v[224:227], v168 offset:35840
	ds_read_b128 v[228:231], v168 offset:36864
	ds_read_b128 v[232:235], v168 offset:37888
	ds_read_b128 v[236:239], v168 offset:38912
	ds_read_b128 v[240:243], v168 offset:39936
	global_load_lds_dwordx4 v[246:247], off
	v_lshl_add_u64 v[246:247], v[244:245], 0, s[26:27]
	s_mov_b32 m0, s58
	s_nop 0
	global_load_lds_dwordx4 v[246:247], off
	s_waitcnt vmcnt(8)
	s_waitcnt lgkmcnt(0)
	s_barrier
	s_setprio 1
	s_waitcnt lgkmcnt(0)
	v_mfma_f32_16x16x32_bf16 v[126:129], v[144:147], v[212:215], v[126:129]
	v_mfma_f32_16x16x32_bf16 v[126:129], v[184:187], v[216:219], v[126:129]
	v_mfma_f32_16x16x32_bf16 v[110:113], v[184:187], v[224:227], v[110:113]
	v_mfma_f32_16x16x32_bf16 v[110:113], v[144:147], v[220:223], v[110:113]
	v_mfma_f32_16x16x32_bf16 v[94:97], v[144:147], v[228:231], v[94:97]
	v_mfma_f32_16x16x32_bf16 v[94:97], v[184:187], v[232:235], v[94:97]
	v_mfma_f32_16x16x32_bf16 v[78:81], v[184:187], v[240:243], v[78:81]
	v_mfma_f32_16x16x32_bf16 v[78:81], v[144:147], v[236:239], v[78:81]
	v_mfma_f32_16x16x32_bf16 v[74:77], v[188:191], v[236:239], v[74:77]
	v_mfma_f32_16x16x32_bf16 v[74:77], v[192:195], v[240:243], v[74:77]
	v_mfma_f32_16x16x32_bf16 v[90:93], v[192:195], v[232:235], v[90:93]
	v_mfma_f32_16x16x32_bf16 v[90:93], v[188:191], v[228:231], v[90:93]
	v_mfma_f32_16x16x32_bf16 v[106:109], v[188:191], v[220:223], v[106:109]
	v_mfma_f32_16x16x32_bf16 v[106:109], v[192:195], v[224:227], v[106:109]
	v_mfma_f32_16x16x32_bf16 v[122:125], v[192:195], v[216:219], v[122:125]
	v_mfma_f32_16x16x32_bf16 v[122:125], v[188:191], v[212:215], v[122:125]
	v_mfma_f32_16x16x32_bf16 v[118:121], v[196:199], v[212:215], v[118:121]
	v_mfma_f32_16x16x32_bf16 v[118:121], v[200:203], v[216:219], v[118:121]
	v_mfma_f32_16x16x32_bf16 v[102:105], v[200:203], v[224:227], v[102:105]
	v_mfma_f32_16x16x32_bf16 v[102:105], v[196:199], v[220:223], v[102:105]
	v_mfma_f32_16x16x32_bf16 v[86:89], v[196:199], v[228:231], v[86:89]
	v_mfma_f32_16x16x32_bf16 v[86:89], v[200:203], v[232:235], v[86:89]
	v_mfma_f32_16x16x32_bf16 v[70:73], v[200:203], v[240:243], v[70:73]
	v_mfma_f32_16x16x32_bf16 v[70:73], v[196:199], v[236:239], v[70:73]
	v_mfma_f32_16x16x32_bf16 v[66:69], v[204:207], v[236:239], v[66:69]
	v_mfma_f32_16x16x32_bf16 v[66:69], v[208:211], v[240:243], v[66:69]
	v_mfma_f32_16x16x32_bf16 v[82:85], v[208:211], v[232:235], v[82:85]
	v_mfma_f32_16x16x32_bf16 v[82:85], v[204:207], v[228:231], v[82:85]
	s_barrier
; #define PG8_STAGE(bufoff, gbase, voff) do { if constexpr (!pg8_noload<Epi>::value) { _Pragma("unroll") for (int _i = 0; _i < 2; ++_i) \
;         __builtin_amdgcn_global_load_lds((const unsigned*)((const char*)(gbase) + (size_t)_i * pstep + (voff)[0]), (PG8_LAS unsigned*)(lds + (bufoff) + ldsw + _i * 8192), 16, 0, 0); } } while (0)
; #define PG8_LDA(dst, b, h) do { _Pragma("unroll") for (int m = 0; m < 4; ++m) _Pragma("unroll") for (int k = 0; k < 2; ++k) dst[m][k] = *(const PG8_LAS bf16x8*)(lds + PG8_SA(b, h) + aoff + m * 2048 + k * 1024); } while (0)
; #define PG8_MMA(ai, bj, At, Bt) do { __builtin_amdgcn_s_setprio(1); _Pragma("unroll") for (int m = 0; m < 4; ++m) _Pragma("unroll") for (int n = 0; n < 2; ++n) _Pragma("unroll") for (int k = 0; k < 2; ++k) \
;         acc[ai][bj][m][n] = __builtin_amdgcn_mfma_f32_16x16x32_bf16(Bt[n][k], At[m][k], acc[ai][bj][m][n], 0, 0, 0); __builtin_amdgcn_s_setprio(0); } while (0)
; #define PG8_WAIT_V(n) asm volatile("s_waitcnt vmcnt(" #n ")" ::: "memory")
; #define PG8_WAIT_L(n) asm volatile("s_waitcnt lgkmcnt(" #n ")" ::: "memory")
; #define PG8_BAR __builtin_amdgcn_s_barrier()
; #define PG8_SCHED __builtin_amdgcn_sched_barrier(0)
; template <class Epi, class Sched, bool ALIGN_EPI = false, bool SP2 = false, bool ABLK = false>
; __device__ __forceinline__ void gemm_phase(PG8_LAS unsigned char* lds, const Gemm g, const Sched& S, const Epi& E) {
;     ...
;             PG8_WAIT_V(8); PG8_WAIT_L(0); PG8_BAR; PG8_MMA(0, 0, At, B0); PG8_MMA(0, 1, At, B1); PG8_BAR; PG8_SCHED;
;             PG8_LDA(At, 1, 1); PG8_STAGE(PG8_SB(1, 0), b3, voffB); PG8_STAGE(PG8_SB(1, 1), b3 + hstep, voffB); PG8_STAGE(PG8_SA(1, 0), a3, voffA);
;             PG8_WAIT_V(8); PG8_WAIT_L(0); PG8_BAR; PG8_MMA(1, 0, At, B0); PG8_MMA(1, 1, At, B1); PG8_BAR; PG8_SCHED;
	s_setprio 2
	v_mfma_f32_16x16x32_bf16 v[98:101], v[204:207], v[220:223], v[98:101]
	v_mfma_f32_16x16x32_bf16 v[98:101], v[208:211], v[224:227], v[98:101]
	v_mfma_f32_16x16x32_bf16 v[114:117], v[208:211], v[216:219], v[114:117]
	v_mfma_f32_16x16x32_bf16 v[114:117], v[204:207], v[212:215], v[114:117]
	s_setprio 0
	s_nop 0
	s_add_i32 s14, s14, s3
	v_lshl_add_u64 v[246:247], v[180:181], 0, s[38:39]
	s_mov_b32 m0, s14
	ds_read_b128 v[212:215], v168 offset:49152
	ds_read_b128 v[216:219], v168 offset:50176
	ds_read_b128 v[220:223], v168 offset:51200
	ds_read_b128 v[224:227], v168 offset:52224
	ds_read_b128 v[228:231], v168 offset:53248
	ds_read_b128 v[232:235], v168 offset:54272
	ds_read_b128 v[236:239], v168 offset:55296
	ds_read_b128 v[240:243], v168 offset:56320
	global_load_lds_dwordx4 v[246:247], off
	v_lshl_add_u64 v[246:247], v[180:181], 0, s[40:41]
	s_add_i32 m0, s14, 0x2000
	s_add_i32 s14, s15, s3
	global_load_lds_dwordx4 v[246:247], off
	v_lshl_add_u64 v[246:247], v[180:181], 0, s[42:43]
	s_mov_b32 m0, s14
	v_lshl_add_u64 v[180:181], v[180:181], 0, s[44:45]
	global_load_lds_dwordx4 v[246:247], off
	s_add_i32 m0, s14, 0x2000
	s_nop 0
	global_load_lds_dwordx4 v[180:181], off
	v_lshl_add_u64 v[180:181], v[244:245], 0, s[38:39]
	s_mov_b32 m0, s61
	s_nop 0
	global_load_lds_dwordx4 v[180:181], off
	v_lshl_add_u64 v[180:181], v[244:245], 0, s[40:41]
	s_mov_b32 m0, s63
	s_nop 0
	global_load_lds_dwordx4 v[180:181], off
	s_waitcnt vmcnt(8)
	s_waitcnt lgkmcnt(0)
	s_barrier
	s_setprio 1
	s_waitcnt lgkmcnt(0)
	v_mfma_f32_16x16x32_bf16 v[62:65], v[144:147], v[212:215], v[62:65]
	v_mfma_f32_16x16x32_bf16 v[62:65], v[184:187], v[216:219], v[62:65]
	v_mfma_f32_16x16x32_bf16 v[46:49], v[184:187], v[224:227], v[46:49]
	v_mfma_f32_16x16x32_bf16 v[46:49], v[144:147], v[220:223], v[46:49]
	v_mfma_f32_16x16x32_bf16 v[30:33], v[144:147], v[228:231], v[30:33]
	v_mfma_f32_16x16x32_bf16 v[30:33], v[184:187], v[232:235], v[30:33]
	v_mfma_f32_16x16x32_bf16 v[14:17], v[184:187], v[240:243], v[14:17]
	v_mfma_f32_16x16x32_bf16 v[14:17], v[144:147], v[236:239], v[14:17]
	v_mfma_f32_16x16x32_bf16 v[10:13], v[188:191], v[236:239], v[10:13]
	v_mfma_f32_16x16x32_bf16 v[10:13], v[192:195], v[240:243], v[10:13]
	v_mfma_f32_16x16x32_bf16 v[26:29], v[192:195], v[232:235], v[26:29]
	v_mfma_f32_16x16x32_bf16 v[26:29], v[188:191], v[228:231], v[26:29]
	v_mfma_f32_16x16x32_bf16 v[42:45], v[188:191], v[220:223], v[42:45]
	v_mfma_f32_16x16x32_bf16 v[42:45], v[192:195], v[224:227], v[42:45]
	v_mfma_f32_16x16x32_bf16 v[58:61], v[192:195], v[216:219], v[58:61]
	v_mfma_f32_16x16x32_bf16 v[58:61], v[188:191], v[212:215], v[58:61]
	v_mfma_f32_16x16x32_bf16 v[54:57], v[196:199], v[212:215], v[54:57]
	v_mfma_f32_16x16x32_bf16 v[54:57], v[200:203], v[216:219], v[54:57]
	v_mfma_f32_16x16x32_bf16 v[38:41], v[200:203], v[224:227], v[38:41]
	v_mfma_f32_16x16x32_bf16 v[38:41], v[196:199], v[220:223], v[38:41]
	v_mfma_f32_16x16x32_bf16 v[22:25], v[196:199], v[228:231], v[22:25]
	v_mfma_f32_16x16x32_bf16 v[22:25], v[200:203], v[232:235], v[22:25]
	v_mfma_f32_16x16x32_bf16 v[6:9], v[200:203], v[240:243], v[6:9]
	v_mfma_f32_16x16x32_bf16 v[6:9], v[196:199], v[236:239], v[6:9]
	v_mfma_f32_16x16x32_bf16 v[2:5], v[204:207], v[236:239], v[2:5]
	v_mfma_f32_16x16x32_bf16 v[2:5], v[208:211], v[240:243], v[2:5]
	v_mfma_f32_16x16x32_bf16 v[18:21], v[208:211], v[232:235], v[18:21]
	v_mfma_f32_16x16x32_bf16 v[18:21], v[204:207], v[228:231], v[18:21]
	s_barrier
	s_setprio 2
	v_mfma_f32_16x16x32_bf16 v[34:37], v[204:207], v[220:223], v[34:37]
	v_mfma_f32_16x16x32_bf16 v[34:37], v[208:211], v[224:227], v[34:37]
	v_mfma_f32_16x16x32_bf16 v[50:53], v[208:211], v[216:219], v[50:53]
	v_mfma_f32_16x16x32_bf16 v[50:53], v[204:207], v[212:215], v[50:53]
	s_setprio 0
	s_cmp_gt_u32 s59, 29
	s_mov_b32 s59, s30
	s_cbranch_scc1 .LBB0_2131

; #define PG8_STAGE(bufoff, gbase, voff) do { if constexpr (!pg8_noload<Epi>::value) { _Pragma("unroll") for (int _i = 0; _i < 2; ++_i) \
;         __builtin_amdgcn_global_load_lds((const unsigned*)((const char*)(gbase) + (size_t)_i * pstep + (voff)[0]), (PG8_LAS unsigned*)(lds + (bufoff) + ldsw + _i * 8192), 16, 0, 0); } } while (0)
; #define PG8_LDA(dst, b, h) do { _Pragma("unroll") for (int m = 0; m < 4; ++m) _Pragma("unroll") for (int k = 0; k < 2; ++k) dst[m][k] = *(const PG8_LAS bf16x8*)(lds + PG8_SA(b, h) + aoff + m * 2048 + k * 1024); } while (0)
; #define PG8_LDB(dst, b, h) do { _Pragma("unroll") for (int n = 0; n < 2; ++n) _Pragma("unroll") for (int k = 0; k < 2; ++k) dst[n][k] = *(const PG8_LAS bf16x8*)(lds + PG8_SB(b, h) + boff + n * 2048 + k * 1024); } while (0)
; #define PG8_MMA(ai, bj, At, Bt) do { __builtin_amdgcn_s_setprio(1); _Pragma("unroll") for (int m = 0; m < 4; ++m) _Pragma("unroll") for (int n = 0; n < 2; ++n) _Pragma("unroll") for (int k = 0; k < 2; ++k) \
;         acc[ai][bj][m][n] = __builtin_amdgcn_mfma_f32_16x16x32_bf16(Bt[n][k], At[m][k], acc[ai][bj][m][n], 0, 0, 0); __builtin_amdgcn_s_setprio(0); } while (0)
; #define PG8_WAIT_V(n) asm volatile("s_waitcnt vmcnt(" #n ")" ::: "memory")
; #define PG8_WAIT_L(n) asm volatile("s_waitcnt lgkmcnt(" #n ")" ::: "memory")
; template <class Epi, class Sched, bool ALIGN_EPI = false, bool SP2 = false, bool ABLK = false>
; __device__ __forceinline__ void gemm_phase(PG8_LAS unsigned char* lds, const Gemm g, const Sched& S, const Epi& E) {
;     ...
;             PG8_LDB(B0, 0, 0); PG8_LDB(B1, 0, 1); PG8_SCHED; PG8_LDA(At, 0, 0); PG8_STAGE(PG8_SA(1, 1), a1 + hstep, voffA);
;             PG8_WAIT_V(8); PG8_WAIT_L(0); PG8_BAR; PG8_MMA(0, 0, At, B0); PG8_MMA(0, 1, At, B1); PG8_BAR; PG8_SCHED;
;             PG8_LDA(At, 0, 1); PG8_STAGE(PG8_SB(0, 0), b2, voffB); PG8_STAGE(PG8_SB(0, 1), b2 + hstep, voffB); PG8_STAGE(PG8_SA(0, 0), a2, voffA);
;             PG8_WAIT_V(8); PG8_WAIT_L(0); PG8_BAR; PG8_MMA(1, 0, At, B0); PG8_MMA(1, 1, At, B1); PG8_BAR; PG8_SCHED;
;     ...
; #pragma unroll
;         for (int a = 0; a < 2; ++a)
; #pragma unroll
;             for (int b = 0; b < 2; ++b)
; #pragma unroll
;                 for (int m = 0; m < 4; ++m)
; #pragma unroll
;                     for (int n = 0; n < 2; ++n) acc[a][b][m][n] = (f32x4){0.f, 0.f, 0.f, 0.f};
;         cur = nxt; cA = nA; cB = nB; ++ui; nt = cur.nt;
.LBB0_2398:
	s_add_i32 s3, s89, -2
	s_add_u32 s62, s62, 0x100800
	s_addc_u32 s63, s63, 0
	s_add_u32 s11, s64, 0x1000
	v_mov_b32_e32 v2, 0
	s_addc_u32 s49, s65, 0
	s_mov_b32 s53, 0
	s_waitcnt lgkmcnt(0)
	v_mov_b32_e32 v3, v2
	v_mov_b32_e32 v4, v2
	v_mov_b32_e32 v5, v2
	v_mov_b32_e32 v6, v2
	v_mov_b32_e32 v7, v2
	v_mov_b32_e32 v8, v2
	v_mov_b32_e32 v9, v2
	v_mov_b32_e32 v18, v2
	v_mov_b32_e32 v19, v2
	v_mov_b32_e32 v20, v2
	v_mov_b32_e32 v21, v2
	v_mov_b32_e32 v22, v2
	v_mov_b32_e32 v23, v2
	v_mov_b32_e32 v24, v2
	v_mov_b32_e32 v25, v2
	v_mov_b32_e32 v34, v2
	v_mov_b32_e32 v35, v2
	v_mov_b32_e32 v36, v2
	v_mov_b32_e32 v37, v2
	v_mov_b32_e32 v38, v2
	v_mov_b32_e32 v39, v2
	v_mov_b32_e32 v40, v2
	v_mov_b32_e32 v41, v2
	v_mov_b32_e32 v50, v2
	v_mov_b32_e32 v51, v2
	v_mov_b32_e32 v52, v2
	v_mov_b32_e32 v53, v2
	v_mov_b32_e32 v54, v2
	v_mov_b32_e32 v55, v2
	v_mov_b32_e32 v56, v2
	v_mov_b32_e32 v57, v2
	v_mov_b32_e32 v10, v2
	v_mov_b32_e32 v11, v2
	v_mov_b32_e32 v12, v2
	v_mov_b32_e32 v13, v2
	v_mov_b32_e32 v14, v2
	v_mov_b32_e32 v15, v2
	v_mov_b32_e32 v16, v2
	v_mov_b32_e32 v17, v2
	v_mov_b32_e32 v26, v2
	v_mov_b32_e32 v27, v2
	v_mov_b32_e32 v28, v2
	v_mov_b32_e32 v29, v2
	v_mov_b32_e32 v30, v2
	v_mov_b32_e32 v31, v2
	v_mov_b32_e32 v32, v2
	v_mov_b32_e32 v33, v2
	v_mov_b32_e32 v42, v2
	v_mov_b32_e32 v43, v2
	v_mov_b32_e32 v44, v2
	v_mov_b32_e32 v45, v2
	v_mov_b32_e32 v46, v2
	v_mov_b32_e32 v47, v2
	v_mov_b32_e32 v48, v2
	v_mov_b32_e32 v49, v2
	v_mov_b32_e32 v58, v2
	v_mov_b32_e32 v59, v2
	v_mov_b32_e32 v60, v2
	v_mov_b32_e32 v61, v2
	v_mov_b32_e32 v62, v2
	v_mov_b32_e32 v63, v2
	v_mov_b32_e32 v64, v2
	v_mov_b32_e32 v65, v2
	v_mov_b32_e32 v66, v2
	v_mov_b32_e32 v67, v2
	v_mov_b32_e32 v68, v2
	v_mov_b32_e32 v69, v2
	v_mov_b32_e32 v70, v2
	v_mov_b32_e32 v71, v2
	v_mov_b32_e32 v72, v2
	v_mov_b32_e32 v73, v2
	v_mov_b32_e32 v82, v2
	v_mov_b32_e32 v83, v2
	v_mov_b32_e32 v84, v2
	v_mov_b32_e32 v85, v2
	v_mov_b32_e32 v86, v2
	v_mov_b32_e32 v87, v2
	v_mov_b32_e32 v88, v2
	v_mov_b32_e32 v89, v2
	v_mov_b32_e32 v98, v2
	v_mov_b32_e32 v99, v2
	v_mov_b32_e32 v100, v2
	v_mov_b32_e32 v101, v2
	v_mov_b32_e32 v102, v2
	v_mov_b32_e32 v103, v2
	v_mov_b32_e32 v104, v2
	v_mov_b32_e32 v105, v2
	v_mov_b32_e32 v114, v2
	v_mov_b32_e32 v115, v2
	v_mov_b32_e32 v116, v2
	v_mov_b32_e32 v117, v2
	v_mov_b32_e32 v118, v2
	v_mov_b32_e32 v119, v2
	v_mov_b32_e32 v120, v2
	v_mov_b32_e32 v121, v2
	v_mov_b32_e32 v74, v2
	v_mov_b32_e32 v75, v2
	v_mov_b32_e32 v76, v2
	v_mov_b32_e32 v77, v2
	v_mov_b32_e32 v78, v2
	v_mov_b32_e32 v79, v2
	v_mov_b32_e32 v80, v2
	v_mov_b32_e32 v81, v2
	v_mov_b32_e32 v90, v2
	v_mov_b32_e32 v91, v2
	v_mov_b32_e32 v92, v2
	v_mov_b32_e32 v93, v2
	v_mov_b32_e32 v94, v2
	v_mov_b32_e32 v95, v2
	v_mov_b32_e32 v96, v2
	v_mov_b32_e32 v97, v2
	v_mov_b32_e32 v106, v2
	v_mov_b32_e32 v107, v2
	v_mov_b32_e32 v108, v2
	v_mov_b32_e32 v109, v2
	v_mov_b32_e32 v110, v2
	v_mov_b32_e32 v111, v2
	v_mov_b32_e32 v112, v2
	v_mov_b32_e32 v113, v2
	v_mov_b32_e32 v122, v2
	v_mov_b32_e32 v123, v2
	v_mov_b32_e32 v124, v2
	v_mov_b32_e32 v125, v2
	v_mov_b32_e32 v126, v2
	v_mov_b32_e32 v127, v2
	v_mov_b32_e32 v128, v2
	v_mov_b32_e32 v129, v2
	.p2align	6
.LBB0_2399:
	s_nop 0
	ds_read_b128 v[130:133], v175
	ds_read_b128 v[134:137], v175 offset:1024
	ds_read_b128 v[138:141], v175 offset:2048
	ds_read_b128 v[142:145], v175 offset:3072
	ds_read_b128 v[146:149], v176
	ds_read_b128 v[150:153], v176 offset:1024
	ds_read_b128 v[154:157], v176 offset:2048
	ds_read_b128 v[158:161], v176 offset:3072
	s_add_i32 s55, s53, 2
	s_add_u32 s64, s62, 0xfff00800
	s_addc_u32 s65, s63, -1
	s_cmp_eq_u32 s3, s53
	s_cselect_b32 s65, s57, s65
	s_cselect_b32 s64, s56, s64
	s_cselect_b32 s91, s59, s49
	s_cselect_b32 s90, s58, s11
	v_lshl_add_u64 v[170:171], s[62:63], 0, v[166:167]
	s_add_i32 m0, s61, 0xc000
	ds_read_b128 v[184:187], v177
	ds_read_b128 v[188:191], v177 offset:1024
	ds_read_b128 v[192:195], v177 offset:2048
	ds_read_b128 v[196:199], v177 offset:3072
	ds_read_b128 v[200:203], v177 offset:4096
	ds_read_b128 v[204:207], v177 offset:5120
	ds_read_b128 v[208:211], v177 offset:6144
	ds_read_b128 v[212:215], v177 offset:7168
	global_load_lds_dwordx4 v[170:171], off
	v_lshl_add_u64 v[170:171], v[170:171], 0, s[12:13]
	s_add_i32 m0, s61, 0xe000
	s_nop 0
	global_load_lds_dwordx4 v[170:171], off
	s_waitcnt vmcnt(8)
	s_waitcnt lgkmcnt(0)
	s_barrier
	s_setprio 1
	s_waitcnt lgkmcnt(0)
	v_mfma_f32_16x16x32_bf16 v[126:129], v[130:133], v[184:187], v[126:129]
	v_mfma_f32_16x16x32_bf16 v[126:129], v[134:137], v[188:191], v[126:129]
	v_mfma_f32_16x16x32_bf16 v[110:113], v[134:137], v[196:199], v[110:113]
	v_mfma_f32_16x16x32_bf16 v[110:113], v[130:133], v[192:195], v[110:113]
	v_mfma_f32_16x16x32_bf16 v[94:97], v[130:133], v[200:203], v[94:97]
	v_mfma_f32_16x16x32_bf16 v[94:97], v[134:137], v[204:207], v[94:97]
	v_mfma_f32_16x16x32_bf16 v[78:81], v[134:137], v[212:215], v[78:81]
	v_mfma_f32_16x16x32_bf16 v[78:81], v[130:133], v[208:211], v[78:81]
	v_mfma_f32_16x16x32_bf16 v[74:77], v[138:141], v[208:211], v[74:77]
	v_mfma_f32_16x16x32_bf16 v[74:77], v[142:145], v[212:215], v[74:77]
	v_mfma_f32_16x16x32_bf16 v[90:93], v[142:145], v[204:207], v[90:93]
	v_mfma_f32_16x16x32_bf16 v[90:93], v[138:141], v[200:203], v[90:93]
	v_mfma_f32_16x16x32_bf16 v[106:109], v[138:141], v[192:195], v[106:109]
	v_mfma_f32_16x16x32_bf16 v[106:109], v[142:145], v[196:199], v[106:109]
	v_mfma_f32_16x16x32_bf16 v[122:125], v[142:145], v[188:191], v[122:125]
	v_mfma_f32_16x16x32_bf16 v[122:125], v[138:141], v[184:187], v[122:125]
	v_mfma_f32_16x16x32_bf16 v[118:121], v[146:149], v[184:187], v[118:121]
	v_mfma_f32_16x16x32_bf16 v[118:121], v[150:153], v[188:191], v[118:121]
	v_mfma_f32_16x16x32_bf16 v[102:105], v[150:153], v[196:199], v[102:105]
	v_mfma_f32_16x16x32_bf16 v[102:105], v[146:149], v[192:195], v[102:105]
	v_mfma_f32_16x16x32_bf16 v[86:89], v[146:149], v[200:203], v[86:89]
	v_mfma_f32_16x16x32_bf16 v[86:89], v[150:153], v[204:207], v[86:89]
	v_mfma_f32_16x16x32_bf16 v[70:73], v[150:153], v[212:215], v[70:73]
	v_mfma_f32_16x16x32_bf16 v[70:73], v[146:149], v[208:211], v[70:73]
	v_mfma_f32_16x16x32_bf16 v[66:69], v[154:157], v[208:211], v[66:69]
	v_mfma_f32_16x16x32_bf16 v[66:69], v[158:161], v[212:215], v[66:69]
	v_mfma_f32_16x16x32_bf16 v[82:85], v[158:161], v[204:207], v[82:85]
	v_mfma_f32_16x16x32_bf16 v[82:85], v[154:157], v[200:203], v[82:85]
	s_barrier
; #define PG8_STAGE(bufoff, gbase, voff) do { if constexpr (!pg8_noload<Epi>::value) { _Pragma("unroll") for (int _i = 0; _i < 2; ++_i) \
;         __builtin_amdgcn_global_load_lds((const unsigned*)((const char*)(gbase) + (size_t)_i * pstep + (voff)[0]), (PG8_LAS unsigned*)(lds + (bufoff) + ldsw + _i * 8192), 16, 0, 0); } } while (0)
; #define PG8_LDA(dst, b, h) do { _Pragma("unroll") for (int m = 0; m < 4; ++m) _Pragma("unroll") for (int k = 0; k < 2; ++k) dst[m][k] = *(const PG8_LAS bf16x8*)(lds + PG8_SA(b, h) + aoff + m * 2048 + k * 1024); } while (0)
; #define PG8_LDB(dst, b, h) do { _Pragma("unroll") for (int n = 0; n < 2; ++n) _Pragma("unroll") for (int k = 0; k < 2; ++k) dst[n][k] = *(const PG8_LAS bf16x8*)(lds + PG8_SB(b, h) + boff + n * 2048 + k * 1024); } while (0)
; #define PG8_MMA(ai, bj, At, Bt) do { __builtin_amdgcn_s_setprio(1); _Pragma("unroll") for (int m = 0; m < 4; ++m) _Pragma("unroll") for (int n = 0; n < 2; ++n) _Pragma("unroll") for (int k = 0; k < 2; ++k) \
;         acc[ai][bj][m][n] = __builtin_amdgcn_mfma_f32_16x16x32_bf16(Bt[n][k], At[m][k], acc[ai][bj][m][n], 0, 0, 0); __builtin_amdgcn_s_setprio(0); } while (0)
; #define PG8_WAIT_V(n) asm volatile("s_waitcnt vmcnt(" #n ")" ::: "memory")
; #define PG8_WAIT_L(n) asm volatile("s_waitcnt lgkmcnt(" #n ")" ::: "memory")
; #define PG8_BAR __builtin_amdgcn_s_barrier()
; #define PG8_SCHED __builtin_amdgcn_sched_barrier(0)
; template <class Epi, class Sched, bool ALIGN_EPI = false, bool SP2 = false, bool ABLK = false>
; __device__ __forceinline__ void gemm_phase(PG8_LAS unsigned char* lds, const Gemm g, const Sched& S, const Epi& E) {
;     ...
;             PG8_LDB(B0, 0, 0); PG8_LDB(B1, 0, 1); PG8_SCHED; PG8_LDA(At, 0, 0); PG8_STAGE(PG8_SA(1, 1), a1 + hstep, voffA);
;             PG8_WAIT_V(8); PG8_WAIT_L(0); PG8_BAR; PG8_MMA(0, 0, At, B0); PG8_MMA(0, 1, At, B1); PG8_BAR; PG8_SCHED;
;             PG8_LDA(At, 0, 1); PG8_STAGE(PG8_SB(0, 0), b2, voffB); PG8_STAGE(PG8_SB(0, 1), b2 + hstep, voffB); PG8_STAGE(PG8_SA(0, 0), a2, voffA);
;             PG8_WAIT_V(8); PG8_WAIT_L(0); PG8_BAR; PG8_MMA(1, 0, At, B0); PG8_MMA(1, 1, At, B1); PG8_BAR; PG8_SCHED;
;             PG8_LDB(B0, 1, 0); PG8_LDB(B1, 1, 1); PG8_SCHED; PG8_LDA(At, 1, 0); PG8_STAGE(PG8_SA(0, 1), a2 + hstep, voffA);
;             PG8_WAIT_V(8); PG8_WAIT_L(0); PG8_BAR; PG8_MMA(0, 0, At, B0); PG8_MMA(0, 1, At, B1); PG8_BAR; PG8_SCHED;
	s_setprio 2
	v_mfma_f32_16x16x32_bf16 v[98:101], v[154:157], v[192:195], v[98:101]
	v_mfma_f32_16x16x32_bf16 v[98:101], v[158:161], v[196:199], v[98:101]
	v_mfma_f32_16x16x32_bf16 v[114:117], v[158:161], v[188:191], v[114:117]
	v_mfma_f32_16x16x32_bf16 v[114:117], v[154:157], v[184:187], v[114:117]
	s_setprio 0
	s_nop 0
	s_add_i32 s53, s80, s69
	v_lshl_add_u64 v[170:171], s[90:91], 0, v[162:163]
	s_mov_b32 m0, s53
	ds_read_b128 v[184:187], v177 offset:16384
	ds_read_b128 v[188:191], v177 offset:17408
	ds_read_b128 v[192:195], v177 offset:18432
	ds_read_b128 v[196:199], v177 offset:19456
	ds_read_b128 v[200:203], v177 offset:20480
	ds_read_b128 v[204:207], v177 offset:21504
	ds_read_b128 v[208:211], v177 offset:22528
	ds_read_b128 v[212:215], v177 offset:23552
	global_load_lds_dwordx4 v[170:171], off
	v_lshl_add_u64 v[216:217], v[170:171], 0, s[12:13]
	s_add_i32 m0, s53, 0x2000
	s_add_i32 s53, s81, s69
	global_load_lds_dwordx4 v[216:217], off
	v_lshl_add_u64 v[216:217], v[170:171], 0, s[14:15]
	s_mov_b32 m0, s53
	s_nop 0
	global_load_lds_dwordx4 v[216:217], off
	v_lshl_add_u64 v[216:217], v[170:171], 0, s[16:17]
	s_add_i32 m0, s53, 0x2000
	s_nop 0
	global_load_lds_dwordx4 v[216:217], off
	v_lshl_add_u64 v[216:217], s[64:65], 0, v[162:163]
	s_mov_b32 m0, s61
	v_lshl_add_u64 v[218:219], v[216:217], 0, s[12:13]
	global_load_lds_dwordx4 v[216:217], off
	s_mov_b32 m0, s70
	s_nop 0
	global_load_lds_dwordx4 v[218:219], off
	s_waitcnt vmcnt(8)
	s_waitcnt lgkmcnt(0)
	s_barrier
	s_setprio 1
	s_waitcnt lgkmcnt(0)
	v_mfma_f32_16x16x32_bf16 v[62:65], v[130:133], v[184:187], v[62:65]
	v_mfma_f32_16x16x32_bf16 v[62:65], v[134:137], v[188:191], v[62:65]
	v_mfma_f32_16x16x32_bf16 v[46:49], v[134:137], v[196:199], v[46:49]
	v_mfma_f32_16x16x32_bf16 v[46:49], v[130:133], v[192:195], v[46:49]
	v_mfma_f32_16x16x32_bf16 v[30:33], v[130:133], v[200:203], v[30:33]
	v_mfma_f32_16x16x32_bf16 v[30:33], v[134:137], v[204:207], v[30:33]
	v_mfma_f32_16x16x32_bf16 v[14:17], v[134:137], v[212:215], v[14:17]
	v_mfma_f32_16x16x32_bf16 v[14:17], v[130:133], v[208:211], v[14:17]
	v_mfma_f32_16x16x32_bf16 v[10:13], v[138:141], v[208:211], v[10:13]
	v_mfma_f32_16x16x32_bf16 v[10:13], v[142:145], v[212:215], v[10:13]
	v_mfma_f32_16x16x32_bf16 v[26:29], v[142:145], v[204:207], v[26:29]
	v_mfma_f32_16x16x32_bf16 v[26:29], v[138:141], v[200:203], v[26:29]
	v_mfma_f32_16x16x32_bf16 v[42:45], v[138:141], v[192:195], v[42:45]
	v_mfma_f32_16x16x32_bf16 v[42:45], v[142:145], v[196:199], v[42:45]
	v_mfma_f32_16x16x32_bf16 v[58:61], v[142:145], v[188:191], v[58:61]
	v_mfma_f32_16x16x32_bf16 v[58:61], v[138:141], v[184:187], v[58:61]
	v_mfma_f32_16x16x32_bf16 v[54:57], v[146:149], v[184:187], v[54:57]
	v_mfma_f32_16x16x32_bf16 v[54:57], v[150:153], v[188:191], v[54:57]
	v_mfma_f32_16x16x32_bf16 v[38:41], v[150:153], v[196:199], v[38:41]
	v_mfma_f32_16x16x32_bf16 v[38:41], v[146:149], v[192:195], v[38:41]
	v_mfma_f32_16x16x32_bf16 v[22:25], v[146:149], v[200:203], v[22:25]
	v_mfma_f32_16x16x32_bf16 v[22:25], v[150:153], v[204:207], v[22:25]
	v_mfma_f32_16x16x32_bf16 v[6:9], v[150:153], v[212:215], v[6:9]
	v_mfma_f32_16x16x32_bf16 v[6:9], v[146:149], v[208:211], v[6:9]
	v_mfma_f32_16x16x32_bf16 v[2:5], v[154:157], v[208:211], v[2:5]
	v_mfma_f32_16x16x32_bf16 v[2:5], v[158:161], v[212:215], v[2:5]
	v_mfma_f32_16x16x32_bf16 v[18:21], v[158:161], v[204:207], v[18:21]
	v_mfma_f32_16x16x32_bf16 v[18:21], v[154:157], v[200:203], v[18:21]
	s_barrier
	s_setprio 2
	v_mfma_f32_16x16x32_bf16 v[34:37], v[154:157], v[192:195], v[34:37]
	v_mfma_f32_16x16x32_bf16 v[34:37], v[158:161], v[196:199], v[34:37]
	v_mfma_f32_16x16x32_bf16 v[50:53], v[158:161], v[188:191], v[50:53]
	v_mfma_f32_16x16x32_bf16 v[50:53], v[154:157], v[184:187], v[50:53]
	s_setprio 0
	s_nop 0
	s_add_i32 s53, 0, 0x18000
	s_add_i32 s64, 0, 0x1c000
	v_add_u32_e32 v142, s53, v1
	v_add_u32_e32 v158, s64, v1
	ds_read_b128 v[130:133], v142
	ds_read_b128 v[134:137], v142 offset:1024
	ds_read_b128 v[138:141], v142 offset:2048
	ds_read_b128 v[142:145], v142 offset:3072
	ds_read_b128 v[146:149], v158
	ds_read_b128 v[150:153], v158 offset:1024
	ds_read_b128 v[154:157], v158 offset:2048
	ds_read_b128 v[158:161], v158 offset:3072
	s_mov_b32 m0, s71
	v_lshl_add_u64 v[218:219], v[216:217], 0, s[14:15]
	ds_read_b128 v[184:187], v177 offset:32768
	ds_read_b128 v[188:191], v177 offset:33792
	ds_read_b128 v[192:195], v177 offset:34816
	ds_read_b128 v[196:199], v177 offset:35840
	ds_read_b128 v[200:203], v177 offset:36864
	ds_read_b128 v[204:207], v177 offset:37888
	ds_read_b128 v[208:211], v177 offset:38912
	ds_read_b128 v[212:215], v177 offset:39936
	global_load_lds_dwordx4 v[218:219], off
	v_lshl_add_u64 v[218:219], v[216:217], 0, s[16:17]
	s_mov_b32 m0, s72
	s_nop 0
	global_load_lds_dwordx4 v[218:219], off
	s_waitcnt vmcnt(8)
	s_waitcnt lgkmcnt(0)
	s_barrier
; #define PG8_STAGE(bufoff, gbase, voff) do { if constexpr (!pg8_noload<Epi>::value) { _Pragma("unroll") for (int _i = 0; _i < 2; ++_i) \
;         __builtin_amdgcn_global_load_lds((const unsigned*)((const char*)(gbase) + (size_t)_i * pstep + (voff)[0]), (PG8_LAS unsigned*)(lds + (bufoff) + ldsw + _i * 8192), 16, 0, 0); } } while (0)
; #define PG8_LDA(dst, b, h) do { _Pragma("unroll") for (int m = 0; m < 4; ++m) _Pragma("unroll") for (int k = 0; k < 2; ++k) dst[m][k] = *(const PG8_LAS bf16x8*)(lds + PG8_SA(b, h) + aoff + m * 2048 + k * 1024); } while (0)
; #define PG8_MMA(ai, bj, At, Bt) do { __builtin_amdgcn_s_setprio(1); _Pragma("unroll") for (int m = 0; m < 4; ++m) _Pragma("unroll") for (int n = 0; n < 2; ++n) _Pragma("unroll") for (int k = 0; k < 2; ++k) \
;         acc[ai][bj][m][n] = __builtin_amdgcn_mfma_f32_16x16x32_bf16(Bt[n][k], At[m][k], acc[ai][bj][m][n], 0, 0, 0); __builtin_amdgcn_s_setprio(0); } while (0)
; #define PG8_WAIT_V(n) asm volatile("s_waitcnt vmcnt(" #n ")" ::: "memory")
; #define PG8_WAIT_L(n) asm volatile("s_waitcnt lgkmcnt(" #n ")" ::: "memory")
; #define PG8_BAR __builtin_amdgcn_s_barrier()
; #define PG8_SCHED __builtin_amdgcn_sched_barrier(0)
; template <class Epi, class Sched, bool ALIGN_EPI = false, bool SP2 = false, bool ABLK = false>
; __device__ __forceinline__ void gemm_phase(PG8_LAS unsigned char* lds, const Gemm g, const Sched& S, const Epi& E) {
;     ...
;             PG8_WAIT_V(8); PG8_WAIT_L(0); PG8_BAR; PG8_MMA(0, 0, At, B0); PG8_MMA(0, 1, At, B1); PG8_BAR; PG8_SCHED;
;             PG8_LDA(At, 1, 1); PG8_STAGE(PG8_SB(1, 0), b3, voffB); PG8_STAGE(PG8_SB(1, 1), b3 + hstep, voffB); PG8_STAGE(PG8_SA(1, 0), a3, voffA);
;             PG8_WAIT_V(8); PG8_WAIT_L(0); PG8_BAR; PG8_MMA(1, 0, At, B0); PG8_MMA(1, 1, At, B1); PG8_BAR; PG8_SCHED;
	s_setprio 1
	s_waitcnt lgkmcnt(0)
	v_mfma_f32_16x16x32_bf16 v[126:129], v[130:133], v[184:187], v[126:129]
	v_mfma_f32_16x16x32_bf16 v[126:129], v[134:137], v[188:191], v[126:129]
	v_mfma_f32_16x16x32_bf16 v[110:113], v[134:137], v[196:199], v[110:113]
	v_mfma_f32_16x16x32_bf16 v[110:113], v[130:133], v[192:195], v[110:113]
	v_mfma_f32_16x16x32_bf16 v[94:97], v[130:133], v[200:203], v[94:97]
	v_mfma_f32_16x16x32_bf16 v[94:97], v[134:137], v[204:207], v[94:97]
	v_mfma_f32_16x16x32_bf16 v[78:81], v[134:137], v[212:215], v[78:81]
	v_mfma_f32_16x16x32_bf16 v[78:81], v[130:133], v[208:211], v[78:81]
	v_mfma_f32_16x16x32_bf16 v[74:77], v[138:141], v[208:211], v[74:77]
	v_mfma_f32_16x16x32_bf16 v[74:77], v[142:145], v[212:215], v[74:77]
	v_mfma_f32_16x16x32_bf16 v[90:93], v[142:145], v[204:207], v[90:93]
	v_mfma_f32_16x16x32_bf16 v[90:93], v[138:141], v[200:203], v[90:93]
	v_mfma_f32_16x16x32_bf16 v[106:109], v[138:141], v[192:195], v[106:109]
	v_mfma_f32_16x16x32_bf16 v[106:109], v[142:145], v[196:199], v[106:109]
	v_mfma_f32_16x16x32_bf16 v[122:125], v[142:145], v[188:191], v[122:125]
	v_mfma_f32_16x16x32_bf16 v[122:125], v[138:141], v[184:187], v[122:125]
	v_mfma_f32_16x16x32_bf16 v[118:121], v[146:149], v[184:187], v[118:121]
	v_mfma_f32_16x16x32_bf16 v[118:121], v[150:153], v[188:191], v[118:121]
	v_mfma_f32_16x16x32_bf16 v[102:105], v[150:153], v[196:199], v[102:105]
	v_mfma_f32_16x16x32_bf16 v[102:105], v[146:149], v[192:195], v[102:105]
	v_mfma_f32_16x16x32_bf16 v[86:89], v[146:149], v[200:203], v[86:89]
	v_mfma_f32_16x16x32_bf16 v[86:89], v[150:153], v[204:207], v[86:89]
	v_mfma_f32_16x16x32_bf16 v[70:73], v[150:153], v[212:215], v[70:73]
	v_mfma_f32_16x16x32_bf16 v[70:73], v[146:149], v[208:211], v[70:73]
	v_mfma_f32_16x16x32_bf16 v[66:69], v[154:157], v[208:211], v[66:69]
	v_mfma_f32_16x16x32_bf16 v[66:69], v[158:161], v[212:215], v[66:69]
	v_mfma_f32_16x16x32_bf16 v[82:85], v[158:161], v[204:207], v[82:85]
	v_mfma_f32_16x16x32_bf16 v[82:85], v[154:157], v[200:203], v[82:85]
	s_barrier
	s_setprio 2
	v_mfma_f32_16x16x32_bf16 v[98:101], v[154:157], v[192:195], v[98:101]
	v_mfma_f32_16x16x32_bf16 v[98:101], v[158:161], v[196:199], v[98:101]
	v_mfma_f32_16x16x32_bf16 v[114:117], v[158:161], v[188:191], v[114:117]
	v_mfma_f32_16x16x32_bf16 v[114:117], v[154:157], v[184:187], v[114:117]
	s_setprio 0
	s_nop 0
	s_add_i32 s53, s53, s69
	v_lshl_add_u64 v[218:219], v[170:171], 0, s[24:25]
	s_mov_b32 m0, s53
	ds_read_b128 v[184:187], v177 offset:49152
	ds_read_b128 v[188:191], v177 offset:50176
	ds_read_b128 v[192:195], v177 offset:51200
	ds_read_b128 v[196:199], v177 offset:52224
	ds_read_b128 v[200:203], v177 offset:53248
	ds_read_b128 v[204:207], v177 offset:54272
	ds_read_b128 v[208:211], v177 offset:55296
	ds_read_b128 v[212:215], v177 offset:56320
	global_load_lds_dwordx4 v[218:219], off
	v_lshl_add_u64 v[218:219], v[170:171], 0, s[26:27]
	s_add_i32 m0, s53, 0x2000
	s_add_i32 s53, s64, s69
	global_load_lds_dwordx4 v[218:219], off
	v_lshl_add_u64 v[218:219], v[170:171], 0, s[28:29]
	s_mov_b32 m0, s53
	v_lshl_add_u64 v[170:171], v[170:171], 0, s[30:31]
	global_load_lds_dwordx4 v[218:219], off
	s_add_i32 m0, s53, 0x2000
	s_nop 0
	global_load_lds_dwordx4 v[170:171], off
	v_lshl_add_u64 v[170:171], v[216:217], 0, s[24:25]
	s_mov_b32 m0, s75
	s_nop 0
	global_load_lds_dwordx4 v[170:171], off
	v_lshl_add_u64 v[170:171], v[216:217], 0, s[26:27]
	s_mov_b32 m0, s76
	s_nop 0
	global_load_lds_dwordx4 v[170:171], off
	s_waitcnt vmcnt(8)
	s_waitcnt lgkmcnt(0)
	s_barrier
	s_setprio 1
	s_waitcnt lgkmcnt(0)
	v_mfma_f32_16x16x32_bf16 v[62:65], v[130:133], v[184:187], v[62:65]
	v_mfma_f32_16x16x32_bf16 v[62:65], v[134:137], v[188:191], v[62:65]
	v_mfma_f32_16x16x32_bf16 v[46:49], v[134:137], v[196:199], v[46:49]
	v_mfma_f32_16x16x32_bf16 v[46:49], v[130:133], v[192:195], v[46:49]
	v_mfma_f32_16x16x32_bf16 v[30:33], v[130:133], v[200:203], v[30:33]
	v_mfma_f32_16x16x32_bf16 v[30:33], v[134:137], v[204:207], v[30:33]
	v_mfma_f32_16x16x32_bf16 v[14:17], v[134:137], v[212:215], v[14:17]
	v_mfma_f32_16x16x32_bf16 v[14:17], v[130:133], v[208:211], v[14:17]
	v_mfma_f32_16x16x32_bf16 v[10:13], v[138:141], v[208:211], v[10:13]
	v_mfma_f32_16x16x32_bf16 v[10:13], v[142:145], v[212:215], v[10:13]
	v_mfma_f32_16x16x32_bf16 v[26:29], v[142:145], v[204:207], v[26:29]
	v_mfma_f32_16x16x32_bf16 v[26:29], v[138:141], v[200:203], v[26:29]
	v_mfma_f32_16x16x32_bf16 v[42:45], v[138:141], v[192:195], v[42:45]
	v_mfma_f32_16x16x32_bf16 v[42:45], v[142:145], v[196:199], v[42:45]
	v_mfma_f32_16x16x32_bf16 v[58:61], v[142:145], v[188:191], v[58:61]
	v_mfma_f32_16x16x32_bf16 v[58:61], v[138:141], v[184:187], v[58:61]
	v_mfma_f32_16x16x32_bf16 v[54:57], v[146:149], v[184:187], v[54:57]
	v_mfma_f32_16x16x32_bf16 v[54:57], v[150:153], v[188:191], v[54:57]
	v_mfma_f32_16x16x32_bf16 v[38:41], v[150:153], v[196:199], v[38:41]
	v_mfma_f32_16x16x32_bf16 v[38:41], v[146:149], v[192:195], v[38:41]
	v_mfma_f32_16x16x32_bf16 v[22:25], v[146:149], v[200:203], v[22:25]
	v_mfma_f32_16x16x32_bf16 v[22:25], v[150:153], v[204:207], v[22:25]
	v_mfma_f32_16x16x32_bf16 v[6:9], v[150:153], v[212:215], v[6:9]
	v_mfma_f32_16x16x32_bf16 v[6:9], v[146:149], v[208:211], v[6:9]
	v_mfma_f32_16x16x32_bf16 v[2:5], v[154:157], v[208:211], v[2:5]
	v_mfma_f32_16x16x32_bf16 v[2:5], v[158:161], v[212:215], v[2:5]
	v_mfma_f32_16x16x32_bf16 v[18:21], v[158:161], v[204:207], v[18:21]
	v_mfma_f32_16x16x32_bf16 v[18:21], v[154:157], v[200:203], v[18:21]
	s_barrier
	s_setprio 2
	v_mfma_f32_16x16x32_bf16 v[34:37], v[154:157], v[192:195], v[34:37]
	v_mfma_f32_16x16x32_bf16 v[34:37], v[158:161], v[196:199], v[34:37]
	v_mfma_f32_16x16x32_bf16 v[50:53], v[158:161], v[188:191], v[50:53]
	v_mfma_f32_16x16x32_bf16 v[50:53], v[154:157], v[184:187], v[50:53]
	s_setprio 0
	s_add_u32 s62, s62, 0x1000
	s_addc_u32 s63, s63, 0
	s_add_u32 s11, s11, 0x1000
	s_addc_u32 s49, s49, 0
	s_cmp_ge_i32 s55, s89
	s_mov_b32 s53, s55
	s_cbranch_scc0 .LBB0_2399
	s_and_b64 vcc, exec, s[34:35]
	s_cbranch_vccnz .LBB0_2404
	s_lshl_b32 s11, s2, 8
	s_cmp_gt_i32 s2, 63
	s_mov_b64 s[62:63], -1
	s_cbranch_scc1 .LBB0_2405
